# 7 merged K-loops + setprio/loop-counter SALU moved off the MMA critical path (setprio 1 before barrier, setprio 0 after)
# speedup vs baseline: 1.0155x; 1.0061x over previous
; #define PG8_STAGE(bufoff, gbase, voff) do { _Pragma("unroll") for (int _i = 0; _i < 2; ++_i) \
;         __builtin_amdgcn_global_load_lds((const unsigned*)((const char*)(gbase) + (voff)[_i]), (LAS unsigned*)(lds + (bufoff) + ldsw + _i * 8192), 16, 0, 0); } while (0)
; #define PG8_LDA(dst, b, h) do { _Pragma("unroll") for (int m = 0; m < 4; ++m) _Pragma("unroll") for (int k = 0; k < 2; ++k) dst[m][k] = *(const LAS bf16x8*)(lds + PG8_SA(b, h) + aoff + m * 2048 + k * 1024); } while (0)
; #define PG8_LDB(dst, b, h) do { _Pragma("unroll") for (int n = 0; n < 2; ++n) _Pragma("unroll") for (int k = 0; k < 2; ++k) dst[n][k] = *(const LAS bf16x8*)(lds + PG8_SB(b, h) + boff + n * 2048 + k * 1024); } while (0)
; #define PG8_MMA(ai, bj, At, Bt) do { __builtin_amdgcn_s_setprio(1); _Pragma("unroll") for (int m = 0; m < 4; ++m) _Pragma("unroll") for (int n = 0; n < 2; ++n) _Pragma("unroll") for (int k = 0; k < 2; ++k) \
;         acc[ai][bj][m][n] = __builtin_amdgcn_mfma_f32_16x16x32_bf16(Bt[n][k], At[m][k], acc[ai][bj][m][n], 0, 0, 0); __builtin_amdgcn_s_setprio(0); } while (0)
; template <class Epi, class Sched>
; __device__ __forceinline__ void gemm_phase(LAS unsigned char* lds, const Gemm g, const Sched& S, const Epi& E) {
;     ...
;         for (int t = 0; t < nt; t += 2) {
;             const bool last = (t == nt - 2);
;             const char* a1 = cA + (size_t)(t + 1) * kstep;
;             const char* a2 = last ? nA : cA + (size_t)(t + 2) * kstep; const char* b2 = last ? nB : cB + (size_t)(t + 2) * kstep;
;             const char* a3 = a2 + kstep; const char* b3 = b2 + kstep;
;             if (last && has_next) S.a_ready(nxt);
;             PG8_LDB(B0, 0, 0); PG8_SCHED; PG8_LDA(At, 0, 0); PG8_STAGE(PG8_SA(1, 1), a1 + hstepA, voffA);
;             PG8_WAIT_L(8); PG8_BAR; PG8_WAIT_L(0); PG8_MMA(0, 0, At, B0); PG8_BAR; PG8_SCHED;
;             PG8_LDB(B1, 0, 1); PG8_STAGE(PG8_SB(0, 0), b2, voffB);
;             PG8_BAR; PG8_WAIT_L(0); PG8_MMA(0, 1, At, B1); PG8_BAR;
;             PG8_LDA(At, 0, 1); PG8_STAGE(PG8_SA(0, 0), a2, voffA);
;             PG8_BAR; PG8_WAIT_L(0); PG8_MMA(1, 0, At, B0); PG8_BAR; PG8_SCHED;
;             PG8_STAGE(PG8_SB(0, 1), b2 + hstepB, voffB);
;             PG8_WAIT_V(6); PG8_BAR; PG8_MMA(1, 1, At, B1); PG8_BAR;
;             PG8_LDB(B0, 1, 0); PG8_SCHED; PG8_LDA(At, 1, 0); PG8_STAGE(PG8_SA(0, 1), a2 + hstepA, voffA);
.LBB0_352:
	s_setprio 0
	s_add_u32 s20, s6, 0xfff80080
	s_addc_u32 s21, s7, -1
	s_add_i32 s56, 0, 0x10000
	v_add_u32_e32 v2, s56, v1
	ds_read_b128 v[144:147], v2
	ds_read_b128 v[150:153], v2 offset:1024
	ds_read_b128 v[154:157], v2 offset:2048
	ds_read_b128 v[158:161], v2 offset:3072
	s_cmp_eq_u32 s55, 28
	s_cselect_b32 s25, s15, s21
	s_cselect_b32 s24, s51, s20
	s_cselect_b32 s21, s1, s54
	s_cselect_b32 s20, s52, s53
	ds_read_b128 v[162:165], v149
	ds_read_b128 v[166:169], v149 offset:1024
	ds_read_b128 v[170:173], v149 offset:2048
	ds_read_b128 v[174:177], v149 offset:3072
	ds_read_b128 v[178:181], v149 offset:4096
	ds_read_b128 v[182:185], v149 offset:5120
	ds_read_b128 v[186:189], v149 offset:6144
	ds_read_b128 v[190:193], v149 offset:7168
	s_add_i32 s58, 0, 0x14000
	v_add_u32_e32 v2, s58, v1
	ds_read_b128 v[194:197], v2
	ds_read_b128 v[198:201], v2 offset:1024
	ds_read_b128 v[202:205], v2 offset:2048
	ds_read_b128 v[206:209], v2 offset:3072
	s_add_i32 m0, s31, 0xc000
	s_nop 0
	global_load_lds_dwordx4 v140, s[6:7]
	s_add_i32 m0, s31, 0xe000
	s_nop 0
	global_load_lds_dwordx4 v142, s[6:7]
	s_waitcnt lgkmcnt(0)
	s_setprio 1
	s_barrier
	v_mfma_f32_16x16x32_bf16 v[128:131], v[144:147], v[162:165], v[128:131]
	v_mfma_f32_16x16x32_bf16 v[124:127], v[154:157], v[162:165], v[124:127]
	v_mfma_f32_16x16x32_bf16 v[112:115], v[144:147], v[170:173], v[112:115]
	v_mfma_f32_16x16x32_bf16 v[108:111], v[154:157], v[170:173], v[108:111]
	v_mfma_f32_16x16x32_bf16 v[96:99], v[144:147], v[178:181], v[96:99]
	v_mfma_f32_16x16x32_bf16 v[92:95], v[154:157], v[178:181], v[92:95]
	v_mfma_f32_16x16x32_bf16 v[80:83], v[144:147], v[186:189], v[80:83]
	v_mfma_f32_16x16x32_bf16 v[76:79], v[154:157], v[186:189], v[76:79]
	v_mfma_f32_16x16x32_bf16 v[128:131], v[150:153], v[166:169], v[128:131]
	v_mfma_f32_16x16x32_bf16 v[124:127], v[158:161], v[166:169], v[124:127]
	v_mfma_f32_16x16x32_bf16 v[112:115], v[150:153], v[174:177], v[112:115]
	v_mfma_f32_16x16x32_bf16 v[108:111], v[158:161], v[174:177], v[108:111]
	v_mfma_f32_16x16x32_bf16 v[96:99], v[150:153], v[182:185], v[96:99]
	v_mfma_f32_16x16x32_bf16 v[92:95], v[158:161], v[182:185], v[92:95]
	v_mfma_f32_16x16x32_bf16 v[80:83], v[150:153], v[190:193], v[80:83]
	v_mfma_f32_16x16x32_bf16 v[76:79], v[158:161], v[190:193], v[76:79]
	v_mfma_f32_16x16x32_bf16 v[120:123], v[194:197], v[162:165], v[120:123]
	v_mfma_f32_16x16x32_bf16 v[116:119], v[202:205], v[162:165], v[116:119]
	v_mfma_f32_16x16x32_bf16 v[104:107], v[194:197], v[170:173], v[104:107]
	v_mfma_f32_16x16x32_bf16 v[100:103], v[202:205], v[170:173], v[100:103]
	v_mfma_f32_16x16x32_bf16 v[88:91], v[194:197], v[178:181], v[88:91]
	v_mfma_f32_16x16x32_bf16 v[84:87], v[202:205], v[178:181], v[84:87]
	v_mfma_f32_16x16x32_bf16 v[72:75], v[194:197], v[186:189], v[72:75]
	v_mfma_f32_16x16x32_bf16 v[68:71], v[202:205], v[186:189], v[68:71]
	v_mfma_f32_16x16x32_bf16 v[120:123], v[198:201], v[166:169], v[120:123]
	v_mfma_f32_16x16x32_bf16 v[116:119], v[206:209], v[166:169], v[116:119]
	v_mfma_f32_16x16x32_bf16 v[104:107], v[198:201], v[174:177], v[104:107]
	v_mfma_f32_16x16x32_bf16 v[100:103], v[206:209], v[174:177], v[100:103]
	v_mfma_f32_16x16x32_bf16 v[88:91], v[198:201], v[182:185], v[88:91]
	v_mfma_f32_16x16x32_bf16 v[84:87], v[206:209], v[182:185], v[84:87]
	v_mfma_f32_16x16x32_bf16 v[72:75], v[198:201], v[190:193], v[72:75]
	v_mfma_f32_16x16x32_bf16 v[68:71], v[206:209], v[190:193], v[68:71]
	s_barrier
	s_setprio 0
	ds_read_b128 v[162:165], v149 offset:16384
	ds_read_b128 v[166:169], v149 offset:17408
	ds_read_b128 v[170:173], v149 offset:18432
	ds_read_b128 v[174:177], v149 offset:19456
	ds_read_b128 v[178:181], v149 offset:20480
	ds_read_b128 v[182:185], v149 offset:21504
	ds_read_b128 v[186:189], v149 offset:22528
	ds_read_b128 v[190:193], v149 offset:23552
	s_add_i32 s56, s56, s30
	v_lshl_add_u64 v[210:211], s[20:21], 0, v[136:137]
	s_mov_b32 m0, s56
	s_nop 0
	global_load_lds_dwordx4 v[210:211], off
	v_lshl_add_u64 v[212:213], s[20:21], 0, v[132:133]
	s_add_i32 m0, s56, 0x2000
	s_nop 0
	global_load_lds_dwordx4 v[212:213], off
	s_mov_b32 m0, s31
	v_lshl_add_u64 v[216:217], s[24:25], 0, v[138:139]
	global_load_lds_dwordx4 v[216:217], off
	v_lshl_add_u64 v[218:219], s[24:25], 0, v[134:135]
	s_mov_b32 m0, s35
	s_nop 0
	global_load_lds_dwordx4 v[218:219], off
	s_add_u32 s56, s20, 0x80000
	s_addc_u32 s57, s21, 0
	s_add_i32 s58, s58, s30
	s_mov_b32 m0, s58
	s_nop 0
	global_load_lds_dwordx4 v136, s[56:57]
	s_add_i32 m0, s58, 0x2000
	s_nop 0
	global_load_lds_dwordx4 v132, s[56:57]
	s_waitcnt lgkmcnt(0)
	s_waitcnt vmcnt(6)
	s_setprio 1
	s_barrier
; #define PG8_STAGE(bufoff, gbase, voff) do { _Pragma("unroll") for (int _i = 0; _i < 2; ++_i) \
;         __builtin_amdgcn_global_load_lds((const unsigned*)((const char*)(gbase) + (voff)[_i]), (LAS unsigned*)(lds + (bufoff) + ldsw + _i * 8192), 16, 0, 0); } while (0)
; #define PG8_LDA(dst, b, h) do { _Pragma("unroll") for (int m = 0; m < 4; ++m) _Pragma("unroll") for (int k = 0; k < 2; ++k) dst[m][k] = *(const LAS bf16x8*)(lds + PG8_SA(b, h) + aoff + m * 2048 + k * 1024); } while (0)
; #define PG8_LDB(dst, b, h) do { _Pragma("unroll") for (int n = 0; n < 2; ++n) _Pragma("unroll") for (int k = 0; k < 2; ++k) dst[n][k] = *(const LAS bf16x8*)(lds + PG8_SB(b, h) + boff + n * 2048 + k * 1024); } while (0)
; #define PG8_MMA(ai, bj, At, Bt) do { __builtin_amdgcn_s_setprio(1); _Pragma("unroll") for (int m = 0; m < 4; ++m) _Pragma("unroll") for (int n = 0; n < 2; ++n) _Pragma("unroll") for (int k = 0; k < 2; ++k) \
;         acc[ai][bj][m][n] = __builtin_amdgcn_mfma_f32_16x16x32_bf16(Bt[n][k], At[m][k], acc[ai][bj][m][n], 0, 0, 0); __builtin_amdgcn_s_setprio(0); } while (0)
; #define PG8_WAIT_V(n) asm volatile("s_waitcnt vmcnt(" #n ")" ::: "memory")
; #define PG8_WAIT_L(n) asm volatile("s_waitcnt lgkmcnt(" #n ")" ::: "memory")
; #define PG8_BAR __builtin_amdgcn_s_barrier()
; #define PG8_SCHED __builtin_amdgcn_sched_barrier(0)
; template <class Epi, class Sched>
; __device__ __forceinline__ void gemm_phase(LAS unsigned char* lds, const Gemm g, const Sched& S, const Epi& E) {
;     ...
;             PG8_WAIT_V(6); PG8_BAR; PG8_MMA(1, 1, At, B1); PG8_BAR;
;             PG8_LDB(B0, 1, 0); PG8_SCHED; PG8_LDA(At, 1, 0); PG8_STAGE(PG8_SA(0, 1), a2 + hstepA, voffA);
;             PG8_WAIT_L(8); PG8_BAR; PG8_WAIT_L(0); PG8_MMA(0, 0, At, B0); PG8_BAR; PG8_SCHED;
;             PG8_LDB(B1, 1, 1); PG8_STAGE(PG8_SB(1, 0), b3, voffB);
;             PG8_BAR; PG8_WAIT_L(0); PG8_MMA(0, 1, At, B1); PG8_BAR;
;             PG8_LDA(At, 1, 1); PG8_STAGE(PG8_SA(1, 0), a3, voffA);
	v_mfma_f32_16x16x32_bf16 v[64:67], v[144:147], v[162:165], v[64:67]
	v_mfma_f32_16x16x32_bf16 v[60:63], v[154:157], v[162:165], v[60:63]
	v_mfma_f32_16x16x32_bf16 v[48:51], v[144:147], v[170:173], v[48:51]
	v_mfma_f32_16x16x32_bf16 v[44:47], v[154:157], v[170:173], v[44:47]
	v_mfma_f32_16x16x32_bf16 v[32:35], v[144:147], v[178:181], v[32:35]
	v_mfma_f32_16x16x32_bf16 v[28:31], v[154:157], v[178:181], v[28:31]
	v_mfma_f32_16x16x32_bf16 v[16:19], v[144:147], v[186:189], v[16:19]
	v_mfma_f32_16x16x32_bf16 v[12:15], v[154:157], v[186:189], v[12:15]
	v_mfma_f32_16x16x32_bf16 v[64:67], v[150:153], v[166:169], v[64:67]
	v_mfma_f32_16x16x32_bf16 v[60:63], v[158:161], v[166:169], v[60:63]
	v_mfma_f32_16x16x32_bf16 v[48:51], v[150:153], v[174:177], v[48:51]
	v_mfma_f32_16x16x32_bf16 v[44:47], v[158:161], v[174:177], v[44:47]
	v_mfma_f32_16x16x32_bf16 v[32:35], v[150:153], v[182:185], v[32:35]
	v_mfma_f32_16x16x32_bf16 v[28:31], v[158:161], v[182:185], v[28:31]
	v_mfma_f32_16x16x32_bf16 v[16:19], v[150:153], v[190:193], v[16:19]
	v_mfma_f32_16x16x32_bf16 v[12:15], v[158:161], v[190:193], v[12:15]
	v_mfma_f32_16x16x32_bf16 v[56:59], v[194:197], v[162:165], v[56:59]
	v_mfma_f32_16x16x32_bf16 v[52:55], v[202:205], v[162:165], v[52:55]
	v_mfma_f32_16x16x32_bf16 v[40:43], v[194:197], v[170:173], v[40:43]
	v_mfma_f32_16x16x32_bf16 v[36:39], v[202:205], v[170:173], v[36:39]
	v_mfma_f32_16x16x32_bf16 v[24:27], v[194:197], v[178:181], v[24:27]
	v_mfma_f32_16x16x32_bf16 v[20:23], v[202:205], v[178:181], v[20:23]
	v_mfma_f32_16x16x32_bf16 v[8:11], v[194:197], v[186:189], v[8:11]
	v_mfma_f32_16x16x32_bf16 v[4:7], v[202:205], v[186:189], v[4:7]
	v_mfma_f32_16x16x32_bf16 v[56:59], v[198:201], v[166:169], v[56:59]
	v_mfma_f32_16x16x32_bf16 v[52:55], v[206:209], v[166:169], v[52:55]
	v_mfma_f32_16x16x32_bf16 v[40:43], v[198:201], v[174:177], v[40:43]
	v_mfma_f32_16x16x32_bf16 v[36:39], v[206:209], v[174:177], v[36:39]
	v_mfma_f32_16x16x32_bf16 v[24:27], v[198:201], v[182:185], v[24:27]
	v_mfma_f32_16x16x32_bf16 v[20:23], v[206:209], v[182:185], v[20:23]
	v_mfma_f32_16x16x32_bf16 v[8:11], v[198:201], v[190:193], v[8:11]
	v_mfma_f32_16x16x32_bf16 v[4:7], v[206:209], v[190:193], v[4:7]
	s_barrier
	s_setprio 0
	s_add_i32 s56, 0, 0x18000
	v_add_u32_e32 v2, s56, v1
	ds_read_b128 v[144:147], v2
	ds_read_b128 v[150:153], v2 offset:1024
	ds_read_b128 v[154:157], v2 offset:2048
	ds_read_b128 v[158:161], v2 offset:3072
	s_add_u32 s24, s24, 0x80000
	s_addc_u32 s25, s25, 0
	ds_read_b128 v[162:165], v149 offset:32768
	ds_read_b128 v[166:169], v149 offset:33792
	ds_read_b128 v[170:173], v149 offset:34816
	ds_read_b128 v[174:177], v149 offset:35840
	ds_read_b128 v[178:181], v149 offset:36864
	ds_read_b128 v[182:185], v149 offset:37888
	ds_read_b128 v[186:189], v149 offset:38912
	ds_read_b128 v[190:193], v149 offset:39936
	s_mov_b32 m0, s36
	s_nop 0
	global_load_lds_dwordx4 v138, s[24:25]
	s_mov_b32 m0, s37
	s_nop 0
	global_load_lds_dwordx4 v134, s[24:25]
	s_add_i32 s24, 0, 0x1c000
	v_add_u32_e32 v2, s24, v1
	ds_read_b128 v[194:197], v2
	ds_read_b128 v[198:201], v2 offset:1024
	ds_read_b128 v[202:205], v2 offset:2048
	ds_read_b128 v[206:209], v2 offset:3072
	s_waitcnt lgkmcnt(0)
	s_setprio 1
	s_barrier
	v_mfma_f32_16x16x32_bf16 v[128:131], v[144:147], v[162:165], v[128:131]
	v_mfma_f32_16x16x32_bf16 v[124:127], v[154:157], v[162:165], v[124:127]
	v_mfma_f32_16x16x32_bf16 v[112:115], v[144:147], v[170:173], v[112:115]
	v_mfma_f32_16x16x32_bf16 v[108:111], v[154:157], v[170:173], v[108:111]
	v_mfma_f32_16x16x32_bf16 v[96:99], v[144:147], v[178:181], v[96:99]
	v_mfma_f32_16x16x32_bf16 v[92:95], v[154:157], v[178:181], v[92:95]
	v_mfma_f32_16x16x32_bf16 v[80:83], v[144:147], v[186:189], v[80:83]
	v_mfma_f32_16x16x32_bf16 v[76:79], v[154:157], v[186:189], v[76:79]
	v_mfma_f32_16x16x32_bf16 v[128:131], v[150:153], v[166:169], v[128:131]
	v_mfma_f32_16x16x32_bf16 v[124:127], v[158:161], v[166:169], v[124:127]
	v_mfma_f32_16x16x32_bf16 v[112:115], v[150:153], v[174:177], v[112:115]
	v_mfma_f32_16x16x32_bf16 v[108:111], v[158:161], v[174:177], v[108:111]
	v_mfma_f32_16x16x32_bf16 v[96:99], v[150:153], v[182:185], v[96:99]
	v_mfma_f32_16x16x32_bf16 v[92:95], v[158:161], v[182:185], v[92:95]
	v_mfma_f32_16x16x32_bf16 v[80:83], v[150:153], v[190:193], v[80:83]
	v_mfma_f32_16x16x32_bf16 v[76:79], v[158:161], v[190:193], v[76:79]
	v_mfma_f32_16x16x32_bf16 v[120:123], v[194:197], v[162:165], v[120:123]
	v_mfma_f32_16x16x32_bf16 v[116:119], v[202:205], v[162:165], v[116:119]
	v_mfma_f32_16x16x32_bf16 v[104:107], v[194:197], v[170:173], v[104:107]
	v_mfma_f32_16x16x32_bf16 v[100:103], v[202:205], v[170:173], v[100:103]
	v_mfma_f32_16x16x32_bf16 v[88:91], v[194:197], v[178:181], v[88:91]
	v_mfma_f32_16x16x32_bf16 v[84:87], v[202:205], v[178:181], v[84:87]
	v_mfma_f32_16x16x32_bf16 v[72:75], v[194:197], v[186:189], v[72:75]
	v_mfma_f32_16x16x32_bf16 v[68:71], v[202:205], v[186:189], v[68:71]
	v_mfma_f32_16x16x32_bf16 v[120:123], v[198:201], v[166:169], v[120:123]
	v_mfma_f32_16x16x32_bf16 v[116:119], v[206:209], v[166:169], v[116:119]
	v_mfma_f32_16x16x32_bf16 v[104:107], v[198:201], v[174:177], v[104:107]
	v_mfma_f32_16x16x32_bf16 v[100:103], v[206:209], v[174:177], v[100:103]
	v_mfma_f32_16x16x32_bf16 v[88:91], v[198:201], v[182:185], v[88:91]
	v_mfma_f32_16x16x32_bf16 v[84:87], v[206:209], v[182:185], v[84:87]
	v_mfma_f32_16x16x32_bf16 v[72:75], v[198:201], v[190:193], v[72:75]
	v_mfma_f32_16x16x32_bf16 v[68:71], v[206:209], v[190:193], v[68:71]
	s_barrier
; __device__ __forceinline__ int opaque_tid() { int t = threadIdx.x; asm volatile("" : "+v"(t)); return t; }
; #define PG8_STAGE(bufoff, gbase, voff) do { _Pragma("unroll") for (int _i = 0; _i < 2; ++_i) \
;         __builtin_amdgcn_global_load_lds((const unsigned*)((const char*)(gbase) + (voff)[_i]), (LAS unsigned*)(lds + (bufoff) + ldsw + _i * 8192), 16, 0, 0); } while (0)
; #define PG8_LDA(dst, b, h) do { _Pragma("unroll") for (int m = 0; m < 4; ++m) _Pragma("unroll") for (int k = 0; k < 2; ++k) dst[m][k] = *(const LAS bf16x8*)(lds + PG8_SA(b, h) + aoff + m * 2048 + k * 1024); } while (0)
; #define PG8_MMA(ai, bj, At, Bt) do { __builtin_amdgcn_s_setprio(1); _Pragma("unroll") for (int m = 0; m < 4; ++m) _Pragma("unroll") for (int n = 0; n < 2; ++n) _Pragma("unroll") for (int k = 0; k < 2; ++k) \
;         acc[ai][bj][m][n] = __builtin_amdgcn_mfma_f32_16x16x32_bf16(Bt[n][k], At[m][k], acc[ai][bj][m][n], 0, 0, 0); __builtin_amdgcn_s_setprio(0); } while (0)
; #define PG8_WAIT_V(n) asm volatile("s_waitcnt vmcnt(" #n ")" ::: "memory")
; #define PG8_WAIT_L(n) asm volatile("s_waitcnt lgkmcnt(" #n ")" ::: "memory")
; #define PG8_BAR __builtin_amdgcn_s_barrier()
; template <class Epi, class Sched>
; __device__ __forceinline__ void gemm_phase(LAS unsigned char* lds, const Gemm g, const Sched& S, const Epi& E) {
;     ...
;             PG8_LDA(At, 1, 1); PG8_STAGE(PG8_SA(1, 0), a3, voffA);
;             PG8_BAR; PG8_WAIT_L(0); PG8_MMA(1, 0, At, B0); PG8_BAR; PG8_SCHED;
;             PG8_STAGE(PG8_SB(1, 1), b3 + hstepB, voffB);
;             PG8_WAIT_V(6); PG8_BAR; PG8_MMA(1, 1, At, B1); PG8_BAR;
;         }
;         E(acc, cur, wr, wc, ui, fq);
;         S.done(cur);
;         if (!has_next) break;
;     __device__ __forceinline__ void operator()(const f32x4 (&acc)[2][2][4][2], const Unit& u, int wr, int wc, int ui, int) const {
;         const int ol_ = opaque_tid() & 63, fr = ol_ & 15, fq = ol_ >> 4;
;         const int row0 = u.pm * BM + wr * 64 + fr, col0 = u.pn * BM + wc * 32 + 8 * fq;
;         const bool cmp = (u.pn == 8 || u.pn == 9);
;         bf16_t* cb = (u.pn == 8) ? kcmp : vcmp;
;         float r_[2][4];
;         rs_read(r_, ui, wr, fr);
; #pragma unroll
;         for (int ai = 0; ai < 2; ++ai)
; #pragma unroll
;             for (int m = 0; m < 4; ++m) { const int row = row0 + ai * HALF + m * 16; const float r = r_[ai][m];
	s_setprio 0
	ds_read_b128 v[162:165], v149 offset:49152
	ds_read_b128 v[166:169], v149 offset:50176
	ds_read_b128 v[170:173], v149 offset:51200
	ds_read_b128 v[174:177], v149 offset:52224
	ds_read_b128 v[178:181], v149 offset:53248
	ds_read_b128 v[182:185], v149 offset:54272
	ds_read_b128 v[186:189], v149 offset:55296
	ds_read_b128 v[190:193], v149 offset:56320
	s_add_i32 s25, s56, s30
	v_lshl_add_u64 v[210:211], v[210:211], 0, s[8:9]
	s_mov_b32 m0, s25
	s_nop 0
	global_load_lds_dwordx4 v[210:211], off
	v_lshl_add_u64 v[210:211], v[212:213], 0, s[8:9]
	s_add_i32 m0, s25, 0x2000
	s_nop 0
	global_load_lds_dwordx4 v[210:211], off
	s_mov_b32 m0, s40
	v_lshl_add_u64 v[210:211], v[216:217], 0, s[8:9]
	global_load_lds_dwordx4 v[210:211], off
	v_lshl_add_u64 v[210:211], v[218:219], 0, s[8:9]
	s_mov_b32 m0, s41
	s_nop 0
	global_load_lds_dwordx4 v[210:211], off
	s_add_u32 s20, s20, 0x80080
	s_addc_u32 s21, s21, 0
	s_add_i32 s24, s24, s30
	s_mov_b32 m0, s24
	s_nop 0
	global_load_lds_dwordx4 v136, s[20:21]
	s_add_i32 m0, s24, 0x2000
	s_nop 0
	global_load_lds_dwordx4 v132, s[20:21]
	s_add_i32 s55, s55, 2
	s_add_u32 s6, s6, 0x100
	s_addc_u32 s7, s7, 0
	s_add_u32 s53, s53, 0x100
	s_addc_u32 s54, s54, 0
	s_cmp_gt_u32 s55, 29
	s_waitcnt lgkmcnt(0)
	s_waitcnt vmcnt(6)
	s_setprio 1
	s_barrier
	v_mfma_f32_16x16x32_bf16 v[64:67], v[144:147], v[162:165], v[64:67]
	v_mfma_f32_16x16x32_bf16 v[60:63], v[154:157], v[162:165], v[60:63]
	v_mfma_f32_16x16x32_bf16 v[48:51], v[144:147], v[170:173], v[48:51]
	v_mfma_f32_16x16x32_bf16 v[44:47], v[154:157], v[170:173], v[44:47]
	v_mfma_f32_16x16x32_bf16 v[32:35], v[144:147], v[178:181], v[32:35]
	v_mfma_f32_16x16x32_bf16 v[28:31], v[154:157], v[178:181], v[28:31]
	v_mfma_f32_16x16x32_bf16 v[16:19], v[144:147], v[186:189], v[16:19]
	v_mfma_f32_16x16x32_bf16 v[12:15], v[154:157], v[186:189], v[12:15]
	v_mfma_f32_16x16x32_bf16 v[64:67], v[150:153], v[166:169], v[64:67]
	v_mfma_f32_16x16x32_bf16 v[60:63], v[158:161], v[166:169], v[60:63]
	v_mfma_f32_16x16x32_bf16 v[48:51], v[150:153], v[174:177], v[48:51]
	v_mfma_f32_16x16x32_bf16 v[44:47], v[158:161], v[174:177], v[44:47]
	v_mfma_f32_16x16x32_bf16 v[32:35], v[150:153], v[182:185], v[32:35]
	v_mfma_f32_16x16x32_bf16 v[28:31], v[158:161], v[182:185], v[28:31]
	v_mfma_f32_16x16x32_bf16 v[16:19], v[150:153], v[190:193], v[16:19]
	v_mfma_f32_16x16x32_bf16 v[12:15], v[158:161], v[190:193], v[12:15]
	v_mfma_f32_16x16x32_bf16 v[56:59], v[194:197], v[162:165], v[56:59]
	v_mfma_f32_16x16x32_bf16 v[52:55], v[202:205], v[162:165], v[52:55]
	v_mfma_f32_16x16x32_bf16 v[40:43], v[194:197], v[170:173], v[40:43]
	v_mfma_f32_16x16x32_bf16 v[36:39], v[202:205], v[170:173], v[36:39]
	v_mfma_f32_16x16x32_bf16 v[24:27], v[194:197], v[178:181], v[24:27]
	v_mfma_f32_16x16x32_bf16 v[20:23], v[202:205], v[178:181], v[20:23]
	v_mfma_f32_16x16x32_bf16 v[8:11], v[194:197], v[186:189], v[8:11]
	v_mfma_f32_16x16x32_bf16 v[4:7], v[202:205], v[186:189], v[4:7]
	v_mfma_f32_16x16x32_bf16 v[56:59], v[198:201], v[166:169], v[56:59]
	v_mfma_f32_16x16x32_bf16 v[52:55], v[206:209], v[166:169], v[52:55]
	v_mfma_f32_16x16x32_bf16 v[40:43], v[198:201], v[174:177], v[40:43]
	v_mfma_f32_16x16x32_bf16 v[36:39], v[206:209], v[174:177], v[36:39]
	v_mfma_f32_16x16x32_bf16 v[24:27], v[198:201], v[182:185], v[24:27]
	v_mfma_f32_16x16x32_bf16 v[20:23], v[206:209], v[182:185], v[20:23]
	v_mfma_f32_16x16x32_bf16 v[8:11], v[198:201], v[190:193], v[8:11]
	v_mfma_f32_16x16x32_bf16 v[4:7], v[206:209], v[190:193], v[4:7]
	s_barrier
	s_cbranch_scc0 .LBB0_352
	s_setprio 0
	s_lshl_b32 s1, s50, 8
	s_lshl_b32 s6, s44, 8
	s_add_i32 s1, s1, s38
	s_or_b32 s6, s6, s39
	s_cmp_eq_u32 s44, 8
	s_mov_b32 s7, 0x3bcb0000
	s_cselect_b32 s15, s7, 0x3ccb4000
	s_lshl_b32 s7, s45, 10
	v_mov_b32_e32 v2, v0
	s_and_b32 s7, s7, 0x400
	s_add_i32 s7, s46, s7
	v_and_b32_e32 v144, 15, v2
	v_or_b32_e32 v148, s1, v144
	v_lshl_add_u32 v144, v144, 2, s7
	v_lshrrev_b32_e32 v2, 1, v2
	ds_read2_b32 v[164:165], v144 offset1:16
	ds_read2_b32 v[160:161], v144 offset0:32 offset1:48
	ds_read2_b32 v[156:157], v144 offset0:128 offset1:144
	ds_read2_b32 v[152:153], v144 offset0:160 offset1:176
	v_and_b32_e32 v2, 24, v2
	v_or_b32_e32 v146, s6, v2
	s_and_b32 s6, s44, -2
	s_cmp_lg_u32 s6, 8
	s_cselect_b64 s[6:7], -1, 0
	s_add_u32 s24, s47, s15
	s_waitcnt lgkmcnt(0)
	v_mov_b32_e32 v162, v165
	v_mov_b32_e32 v158, v161
	v_mov_b32_e32 v154, v157
	v_mov_b32_e32 v144, v153
	v_ashrrev_i32_e32 v147, 31, v146
	s_addc_u32 s25, s48, 0
	s_mov_b64 s[20:21], -1
	s_and_b64 vcc, exec, s[6:7]
	s_cbranch_vccz .LBB0_355
	v_mov_b64_e32 v[150:151], s[92:93]
	s_movk_i32 s15, 0x3600
	v_mad_i64_i32 v[150:151], s[20:21], v148, s15, v[150:151]
	v_lshl_add_u64 v[170:171], v[146:147], 1, v[150:151]
	s_mov_b64 s[20:21], 0

; #define PG8_STAGE(bufoff, gbase, voff) do { _Pragma("unroll") for (int _i = 0; _i < 2; ++_i) \
;         __builtin_amdgcn_global_load_lds((const unsigned*)((const char*)(gbase) + (voff)[_i]), (LAS unsigned*)(lds + (bufoff) + ldsw + _i * 8192), 16, 0, 0); } while (0)
; #define PG8_LDA(dst, b, h) do { _Pragma("unroll") for (int m = 0; m < 4; ++m) _Pragma("unroll") for (int k = 0; k < 2; ++k) dst[m][k] = *(const LAS bf16x8*)(lds + PG8_SA(b, h) + aoff + m * 2048 + k * 1024); } while (0)
; #define PG8_LDB(dst, b, h) do { _Pragma("unroll") for (int n = 0; n < 2; ++n) _Pragma("unroll") for (int k = 0; k < 2; ++k) dst[n][k] = *(const LAS bf16x8*)(lds + PG8_SB(b, h) + boff + n * 2048 + k * 1024); } while (0)
; #define PG8_MMA(ai, bj, At, Bt) do { __builtin_amdgcn_s_setprio(1); _Pragma("unroll") for (int m = 0; m < 4; ++m) _Pragma("unroll") for (int n = 0; n < 2; ++n) _Pragma("unroll") for (int k = 0; k < 2; ++k) \
;         acc[ai][bj][m][n] = __builtin_amdgcn_mfma_f32_16x16x32_bf16(Bt[n][k], At[m][k], acc[ai][bj][m][n], 0, 0, 0); __builtin_amdgcn_s_setprio(0); } while (0)
; template <class Epi, class Sched>
; __device__ __forceinline__ void gemm_phase(LAS unsigned char* lds, const Gemm g, const Sched& S, const Epi& E) {
;     ...
;         for (int t = 0; t < nt; t += 2) {
;             const bool last = (t == nt - 2);
;             const char* a1 = cA + (size_t)(t + 1) * kstep;
;             const char* a2 = last ? nA : cA + (size_t)(t + 2) * kstep; const char* b2 = last ? nB : cB + (size_t)(t + 2) * kstep;
;             const char* a3 = a2 + kstep; const char* b3 = b2 + kstep;
;             if (last && has_next) S.a_ready(nxt);
;             PG8_LDB(B0, 0, 0); PG8_SCHED; PG8_LDA(At, 0, 0); PG8_STAGE(PG8_SA(1, 1), a1 + hstepA, voffA);
;             PG8_WAIT_L(8); PG8_BAR; PG8_WAIT_L(0); PG8_MMA(0, 0, At, B0); PG8_BAR; PG8_SCHED;
;             PG8_LDB(B1, 0, 1); PG8_STAGE(PG8_SB(0, 0), b2, voffB);
;             PG8_BAR; PG8_WAIT_L(0); PG8_MMA(0, 1, At, B1); PG8_BAR;
;             PG8_LDA(At, 0, 1); PG8_STAGE(PG8_SA(0, 0), a2, voffA);
;             PG8_BAR; PG8_WAIT_L(0); PG8_MMA(1, 0, At, B0); PG8_BAR; PG8_SCHED;
;             PG8_STAGE(PG8_SB(0, 1), b2 + hstepB, voffB);
;             PG8_WAIT_V(6); PG8_BAR; PG8_MMA(1, 1, At, B1); PG8_BAR;
;             PG8_LDB(B0, 1, 0); PG8_SCHED; PG8_LDA(At, 1, 0); PG8_STAGE(PG8_SA(0, 1), a2 + hstepA, voffA);
.LBB0_491:
	s_setprio 0
	s_add_u32 s6, s4, 0xfff80080
	s_addc_u32 s7, s5, -1
	s_add_i32 s68, 0, 0x10000
	v_add_u32_e32 v154, s68, v1
	ds_read_b128 v[142:145], v154
	ds_read_b128 v[146:149], v154 offset:1024
	ds_read_b128 v[150:153], v154 offset:2048
	ds_read_b128 v[158:161], v154 offset:3072
	s_cmp_eq_u32 s67, 60
	s_cselect_b32 s15, s18, s7
	s_cselect_b32 s14, s19, s6
	s_cselect_b32 s7, s51, s66
	s_cselect_b32 s6, s53, s65
	ds_read_b128 v[162:165], v156
	ds_read_b128 v[166:169], v156 offset:1024
	ds_read_b128 v[170:173], v156 offset:2048
	ds_read_b128 v[174:177], v156 offset:3072
	ds_read_b128 v[178:181], v156 offset:4096
	ds_read_b128 v[182:185], v156 offset:5120
	ds_read_b128 v[186:189], v156 offset:6144
	ds_read_b128 v[190:193], v156 offset:7168
	s_add_i32 s70, 0, 0x14000
	v_add_u32_e32 v154, s70, v1
	ds_read_b128 v[194:197], v154
	ds_read_b128 v[198:201], v154 offset:1024
	ds_read_b128 v[202:205], v154 offset:2048
	ds_read_b128 v[206:209], v154 offset:3072
	s_add_i32 m0, s30, 0xc000
	s_nop 0
	global_load_lds_dwordx4 v138, s[4:5]
	s_add_i32 m0, s30, 0xe000
	s_nop 0
	global_load_lds_dwordx4 v140, s[4:5]
	s_waitcnt lgkmcnt(0)
	s_setprio 1
	s_barrier
	v_mfma_f32_16x16x32_bf16 v[128:131], v[142:145], v[162:165], v[128:131]
	v_mfma_f32_16x16x32_bf16 v[124:127], v[150:153], v[162:165], v[124:127]
	v_mfma_f32_16x16x32_bf16 v[120:123], v[142:145], v[170:173], v[120:123]
	v_mfma_f32_16x16x32_bf16 v[116:119], v[150:153], v[170:173], v[116:119]
	v_mfma_f32_16x16x32_bf16 v[112:115], v[142:145], v[178:181], v[112:115]
	v_mfma_f32_16x16x32_bf16 v[108:111], v[150:153], v[178:181], v[108:111]
	v_mfma_f32_16x16x32_bf16 v[104:107], v[142:145], v[186:189], v[104:107]
	v_mfma_f32_16x16x32_bf16 v[100:103], v[150:153], v[186:189], v[100:103]
	v_mfma_f32_16x16x32_bf16 v[128:131], v[146:149], v[166:169], v[128:131]
	v_mfma_f32_16x16x32_bf16 v[124:127], v[158:161], v[166:169], v[124:127]
	v_mfma_f32_16x16x32_bf16 v[120:123], v[146:149], v[174:177], v[120:123]
	v_mfma_f32_16x16x32_bf16 v[116:119], v[158:161], v[174:177], v[116:119]
	v_mfma_f32_16x16x32_bf16 v[112:115], v[146:149], v[182:185], v[112:115]
	v_mfma_f32_16x16x32_bf16 v[108:111], v[158:161], v[182:185], v[108:111]
	v_mfma_f32_16x16x32_bf16 v[104:107], v[146:149], v[190:193], v[104:107]
	v_mfma_f32_16x16x32_bf16 v[100:103], v[158:161], v[190:193], v[100:103]
	v_mfma_f32_16x16x32_bf16 v[64:67], v[194:197], v[162:165], v[64:67]
	v_mfma_f32_16x16x32_bf16 v[60:63], v[202:205], v[162:165], v[60:63]
	v_mfma_f32_16x16x32_bf16 v[56:59], v[194:197], v[170:173], v[56:59]
	v_mfma_f32_16x16x32_bf16 v[52:55], v[202:205], v[170:173], v[52:55]
	v_mfma_f32_16x16x32_bf16 v[48:51], v[194:197], v[178:181], v[48:51]
	v_mfma_f32_16x16x32_bf16 v[44:47], v[202:205], v[178:181], v[44:47]
	v_mfma_f32_16x16x32_bf16 v[40:43], v[194:197], v[186:189], v[40:43]
	v_mfma_f32_16x16x32_bf16 v[36:39], v[202:205], v[186:189], v[36:39]
	v_mfma_f32_16x16x32_bf16 v[64:67], v[198:201], v[166:169], v[64:67]
	v_mfma_f32_16x16x32_bf16 v[60:63], v[206:209], v[166:169], v[60:63]
	v_mfma_f32_16x16x32_bf16 v[56:59], v[198:201], v[174:177], v[56:59]
	v_mfma_f32_16x16x32_bf16 v[52:55], v[206:209], v[174:177], v[52:55]
	v_mfma_f32_16x16x32_bf16 v[48:51], v[198:201], v[182:185], v[48:51]
	v_mfma_f32_16x16x32_bf16 v[44:47], v[206:209], v[182:185], v[44:47]
	v_mfma_f32_16x16x32_bf16 v[40:43], v[198:201], v[190:193], v[40:43]
	v_mfma_f32_16x16x32_bf16 v[36:39], v[206:209], v[190:193], v[36:39]
	s_barrier
	s_setprio 0
	ds_read_b128 v[162:165], v156 offset:16384
	ds_read_b128 v[166:169], v156 offset:17408
	ds_read_b128 v[170:173], v156 offset:18432
	ds_read_b128 v[174:177], v156 offset:19456
	ds_read_b128 v[178:181], v156 offset:20480
	ds_read_b128 v[182:185], v156 offset:21504
	ds_read_b128 v[186:189], v156 offset:22528
	ds_read_b128 v[190:193], v156 offset:23552
	s_add_i32 s68, s68, s29
	v_lshl_add_u64 v[154:155], s[6:7], 0, v[2:3]
	s_mov_b32 m0, s68
	v_lshl_add_u64 v[210:211], s[6:7], 0, v[136:137]
	global_load_lds_dwordx4 v[154:155], off
	s_add_i32 m0, s68, 0x2000
	s_nop 0
	global_load_lds_dwordx4 v[210:211], off
	s_mov_b32 m0, s30
	v_lshl_add_u64 v[212:213], s[14:15], 0, v[132:133]
	global_load_lds_dwordx4 v[212:213], off
	v_lshl_add_u64 v[216:217], s[14:15], 0, v[134:135]
	s_mov_b32 m0, s31
	s_nop 0
	global_load_lds_dwordx4 v[216:217], off
	s_add_u32 s68, s6, 0x100000
	s_addc_u32 s69, s7, 0
	s_add_i32 s70, s70, s29
	s_mov_b32 m0, s70
	s_nop 0
	global_load_lds_dwordx4 v2, s[68:69]
	s_add_i32 m0, s70, 0x2000
	s_nop 0
	global_load_lds_dwordx4 v136, s[68:69]
	s_waitcnt lgkmcnt(0)
	s_waitcnt vmcnt(6)
	s_setprio 1
	s_barrier
; #define PG8_STAGE(bufoff, gbase, voff) do { _Pragma("unroll") for (int _i = 0; _i < 2; ++_i) \
;         __builtin_amdgcn_global_load_lds((const unsigned*)((const char*)(gbase) + (voff)[_i]), (LAS unsigned*)(lds + (bufoff) + ldsw + _i * 8192), 16, 0, 0); } while (0)
; #define PG8_LDA(dst, b, h) do { _Pragma("unroll") for (int m = 0; m < 4; ++m) _Pragma("unroll") for (int k = 0; k < 2; ++k) dst[m][k] = *(const LAS bf16x8*)(lds + PG8_SA(b, h) + aoff + m * 2048 + k * 1024); } while (0)
; #define PG8_LDB(dst, b, h) do { _Pragma("unroll") for (int n = 0; n < 2; ++n) _Pragma("unroll") for (int k = 0; k < 2; ++k) dst[n][k] = *(const LAS bf16x8*)(lds + PG8_SB(b, h) + boff + n * 2048 + k * 1024); } while (0)
; #define PG8_MMA(ai, bj, At, Bt) do { __builtin_amdgcn_s_setprio(1); _Pragma("unroll") for (int m = 0; m < 4; ++m) _Pragma("unroll") for (int n = 0; n < 2; ++n) _Pragma("unroll") for (int k = 0; k < 2; ++k) \
;         acc[ai][bj][m][n] = __builtin_amdgcn_mfma_f32_16x16x32_bf16(Bt[n][k], At[m][k], acc[ai][bj][m][n], 0, 0, 0); __builtin_amdgcn_s_setprio(0); } while (0)
; #define PG8_WAIT_V(n) asm volatile("s_waitcnt vmcnt(" #n ")" ::: "memory")
; #define PG8_WAIT_L(n) asm volatile("s_waitcnt lgkmcnt(" #n ")" ::: "memory")
; #define PG8_BAR __builtin_amdgcn_s_barrier()
; #define PG8_SCHED __builtin_amdgcn_sched_barrier(0)
; template <class Epi, class Sched>
; __device__ __forceinline__ void gemm_phase(LAS unsigned char* lds, const Gemm g, const Sched& S, const Epi& E) {
;     ...
;             PG8_WAIT_V(6); PG8_BAR; PG8_MMA(1, 1, At, B1); PG8_BAR;
;             PG8_LDB(B0, 1, 0); PG8_SCHED; PG8_LDA(At, 1, 0); PG8_STAGE(PG8_SA(0, 1), a2 + hstepA, voffA);
;             PG8_WAIT_L(8); PG8_BAR; PG8_WAIT_L(0); PG8_MMA(0, 0, At, B0); PG8_BAR; PG8_SCHED;
;             PG8_LDB(B1, 1, 1); PG8_STAGE(PG8_SB(1, 0), b3, voffB);
;             PG8_BAR; PG8_WAIT_L(0); PG8_MMA(0, 1, At, B1); PG8_BAR;
;             PG8_LDA(At, 1, 1); PG8_STAGE(PG8_SA(1, 0), a3, voffA);
	v_mfma_f32_16x16x32_bf16 v[96:99], v[142:145], v[162:165], v[96:99]
	v_mfma_f32_16x16x32_bf16 v[92:95], v[150:153], v[162:165], v[92:95]
	v_mfma_f32_16x16x32_bf16 v[88:91], v[142:145], v[170:173], v[88:91]
	v_mfma_f32_16x16x32_bf16 v[84:87], v[150:153], v[170:173], v[84:87]
	v_mfma_f32_16x16x32_bf16 v[80:83], v[142:145], v[178:181], v[80:83]
	v_mfma_f32_16x16x32_bf16 v[76:79], v[150:153], v[178:181], v[76:79]
	v_mfma_f32_16x16x32_bf16 v[72:75], v[142:145], v[186:189], v[72:75]
	v_mfma_f32_16x16x32_bf16 v[68:71], v[150:153], v[186:189], v[68:71]
	v_mfma_f32_16x16x32_bf16 v[96:99], v[146:149], v[166:169], v[96:99]
	v_mfma_f32_16x16x32_bf16 v[92:95], v[158:161], v[166:169], v[92:95]
	v_mfma_f32_16x16x32_bf16 v[88:91], v[146:149], v[174:177], v[88:91]
	v_mfma_f32_16x16x32_bf16 v[84:87], v[158:161], v[174:177], v[84:87]
	v_mfma_f32_16x16x32_bf16 v[80:83], v[146:149], v[182:185], v[80:83]
	v_mfma_f32_16x16x32_bf16 v[76:79], v[158:161], v[182:185], v[76:79]
	v_mfma_f32_16x16x32_bf16 v[72:75], v[146:149], v[190:193], v[72:75]
	v_mfma_f32_16x16x32_bf16 v[68:71], v[158:161], v[190:193], v[68:71]
	v_mfma_f32_16x16x32_bf16 v[32:35], v[194:197], v[162:165], v[32:35]
	v_mfma_f32_16x16x32_bf16 v[28:31], v[202:205], v[162:165], v[28:31]
	v_mfma_f32_16x16x32_bf16 v[24:27], v[194:197], v[170:173], v[24:27]
	v_mfma_f32_16x16x32_bf16 v[20:23], v[202:205], v[170:173], v[20:23]
	v_mfma_f32_16x16x32_bf16 v[16:19], v[194:197], v[178:181], v[16:19]
	v_mfma_f32_16x16x32_bf16 v[12:15], v[202:205], v[178:181], v[12:15]
	v_mfma_f32_16x16x32_bf16 v[8:11], v[194:197], v[186:189], v[8:11]
	v_mfma_f32_16x16x32_bf16 v[4:7], v[202:205], v[186:189], v[4:7]
	v_mfma_f32_16x16x32_bf16 v[32:35], v[198:201], v[166:169], v[32:35]
	v_mfma_f32_16x16x32_bf16 v[28:31], v[206:209], v[166:169], v[28:31]
	v_mfma_f32_16x16x32_bf16 v[24:27], v[198:201], v[174:177], v[24:27]
	v_mfma_f32_16x16x32_bf16 v[20:23], v[206:209], v[174:177], v[20:23]
	v_mfma_f32_16x16x32_bf16 v[16:19], v[198:201], v[182:185], v[16:19]
	v_mfma_f32_16x16x32_bf16 v[12:15], v[206:209], v[182:185], v[12:15]
	v_mfma_f32_16x16x32_bf16 v[8:11], v[198:201], v[190:193], v[8:11]
	v_mfma_f32_16x16x32_bf16 v[4:7], v[206:209], v[190:193], v[4:7]
	s_barrier
	s_setprio 0
	s_add_i32 s68, 0, 0x18000
	v_add_u32_e32 v157, s68, v1
	ds_read_b128 v[142:145], v157
	ds_read_b128 v[146:149], v157 offset:1024
	ds_read_b128 v[150:153], v157 offset:2048
	ds_read_b128 v[158:161], v157 offset:3072
	s_add_u32 s14, s14, 0x80000
	s_addc_u32 s15, s15, 0
	ds_read_b128 v[162:165], v156 offset:32768
	ds_read_b128 v[166:169], v156 offset:33792
	ds_read_b128 v[170:173], v156 offset:34816
	ds_read_b128 v[174:177], v156 offset:35840
	ds_read_b128 v[178:181], v156 offset:36864
	ds_read_b128 v[182:185], v156 offset:37888
	ds_read_b128 v[186:189], v156 offset:38912
	ds_read_b128 v[190:193], v156 offset:39936
	s_mov_b32 m0, s38
	s_nop 0
	global_load_lds_dwordx4 v132, s[14:15]
	s_mov_b32 m0, s39
	s_nop 0
	global_load_lds_dwordx4 v134, s[14:15]
	s_add_i32 s14, 0, 0x1c000
	v_add_u32_e32 v157, s14, v1
	ds_read_b128 v[194:197], v157
	ds_read_b128 v[198:201], v157 offset:1024
	ds_read_b128 v[202:205], v157 offset:2048
	ds_read_b128 v[206:209], v157 offset:3072
	s_waitcnt lgkmcnt(0)
	s_setprio 1
	s_barrier
	v_mfma_f32_16x16x32_bf16 v[128:131], v[142:145], v[162:165], v[128:131]
	v_mfma_f32_16x16x32_bf16 v[124:127], v[150:153], v[162:165], v[124:127]
	v_mfma_f32_16x16x32_bf16 v[120:123], v[142:145], v[170:173], v[120:123]
	v_mfma_f32_16x16x32_bf16 v[116:119], v[150:153], v[170:173], v[116:119]
	v_mfma_f32_16x16x32_bf16 v[112:115], v[142:145], v[178:181], v[112:115]
	v_mfma_f32_16x16x32_bf16 v[108:111], v[150:153], v[178:181], v[108:111]
	v_mfma_f32_16x16x32_bf16 v[104:107], v[142:145], v[186:189], v[104:107]
	v_mfma_f32_16x16x32_bf16 v[100:103], v[150:153], v[186:189], v[100:103]
	v_mfma_f32_16x16x32_bf16 v[128:131], v[146:149], v[166:169], v[128:131]
	v_mfma_f32_16x16x32_bf16 v[124:127], v[158:161], v[166:169], v[124:127]
	v_mfma_f32_16x16x32_bf16 v[120:123], v[146:149], v[174:177], v[120:123]
	v_mfma_f32_16x16x32_bf16 v[116:119], v[158:161], v[174:177], v[116:119]
	v_mfma_f32_16x16x32_bf16 v[112:115], v[146:149], v[182:185], v[112:115]
	v_mfma_f32_16x16x32_bf16 v[108:111], v[158:161], v[182:185], v[108:111]
	v_mfma_f32_16x16x32_bf16 v[104:107], v[146:149], v[190:193], v[104:107]
	v_mfma_f32_16x16x32_bf16 v[100:103], v[158:161], v[190:193], v[100:103]
	v_mfma_f32_16x16x32_bf16 v[64:67], v[194:197], v[162:165], v[64:67]
	v_mfma_f32_16x16x32_bf16 v[60:63], v[202:205], v[162:165], v[60:63]
	v_mfma_f32_16x16x32_bf16 v[56:59], v[194:197], v[170:173], v[56:59]
	v_mfma_f32_16x16x32_bf16 v[52:55], v[202:205], v[170:173], v[52:55]
	v_mfma_f32_16x16x32_bf16 v[48:51], v[194:197], v[178:181], v[48:51]
	v_mfma_f32_16x16x32_bf16 v[44:47], v[202:205], v[178:181], v[44:47]
	v_mfma_f32_16x16x32_bf16 v[40:43], v[194:197], v[186:189], v[40:43]
	v_mfma_f32_16x16x32_bf16 v[36:39], v[202:205], v[186:189], v[36:39]
	v_mfma_f32_16x16x32_bf16 v[64:67], v[198:201], v[166:169], v[64:67]
	v_mfma_f32_16x16x32_bf16 v[60:63], v[206:209], v[166:169], v[60:63]
	v_mfma_f32_16x16x32_bf16 v[56:59], v[198:201], v[174:177], v[56:59]
	v_mfma_f32_16x16x32_bf16 v[52:55], v[206:209], v[174:177], v[52:55]
	v_mfma_f32_16x16x32_bf16 v[48:51], v[198:201], v[182:185], v[48:51]
	v_mfma_f32_16x16x32_bf16 v[44:47], v[206:209], v[182:185], v[44:47]
	v_mfma_f32_16x16x32_bf16 v[40:43], v[198:201], v[190:193], v[40:43]
	v_mfma_f32_16x16x32_bf16 v[36:39], v[206:209], v[190:193], v[36:39]
	s_barrier
; __device__ __forceinline__ int opaque_tid() { int t = threadIdx.x; asm volatile("" : "+v"(t)); return t; }
; #define PG8_STAGE(bufoff, gbase, voff) do { _Pragma("unroll") for (int _i = 0; _i < 2; ++_i) \
;         __builtin_amdgcn_global_load_lds((const unsigned*)((const char*)(gbase) + (voff)[_i]), (LAS unsigned*)(lds + (bufoff) + ldsw + _i * 8192), 16, 0, 0); } while (0)
; #define PG8_LDA(dst, b, h) do { _Pragma("unroll") for (int m = 0; m < 4; ++m) _Pragma("unroll") for (int k = 0; k < 2; ++k) dst[m][k] = *(const LAS bf16x8*)(lds + PG8_SA(b, h) + aoff + m * 2048 + k * 1024); } while (0)
; #define PG8_MMA(ai, bj, At, Bt) do { __builtin_amdgcn_s_setprio(1); _Pragma("unroll") for (int m = 0; m < 4; ++m) _Pragma("unroll") for (int n = 0; n < 2; ++n) _Pragma("unroll") for (int k = 0; k < 2; ++k) \
;         acc[ai][bj][m][n] = __builtin_amdgcn_mfma_f32_16x16x32_bf16(Bt[n][k], At[m][k], acc[ai][bj][m][n], 0, 0, 0); __builtin_amdgcn_s_setprio(0); } while (0)
; #define PG8_WAIT_V(n) asm volatile("s_waitcnt vmcnt(" #n ")" ::: "memory")
; #define PG8_WAIT_L(n) asm volatile("s_waitcnt lgkmcnt(" #n ")" ::: "memory")
; #define PG8_BAR __builtin_amdgcn_s_barrier()
; #define PG8_SCHED __builtin_amdgcn_sched_barrier(0)
; template <class Epi, class Sched>
; __device__ __forceinline__ void gemm_phase(LAS unsigned char* lds, const Gemm g, const Sched& S, const Epi& E) {
;     ...
;             PG8_LDA(At, 1, 1); PG8_STAGE(PG8_SA(1, 0), a3, voffA);
;             PG8_BAR; PG8_WAIT_L(0); PG8_MMA(1, 0, At, B0); PG8_BAR; PG8_SCHED;
;             PG8_STAGE(PG8_SB(1, 1), b3 + hstepB, voffB);
;             PG8_WAIT_V(6); PG8_BAR; PG8_MMA(1, 1, At, B1); PG8_BAR;
;         }
;         E(acc, cur, wr, wc, ui, fq);
;         S.done(cur);
;         if (!has_next) break;
;     __device__ __forceinline__ void operator()(const f32x4 (&acc)[2][2][4][2], const Unit& u, int wr, int wc, int, int) const {
;         const int ol_ = opaque_tid() & 63, fr = ol_ & 15, fq = ol_ >> 4;
;         const int row0 = u.pm * BM + wr * 64 + fr, col0 = u.pn * BM + wc * 32 + 8 * fq;
; #pragma unroll
;         for (int bj = 0; bj < 2; ++bj) { f32x4 b0 = (f32x4){0.f, 0.f, 0.f, 0.f}, b1 = b0;
; #pragma unroll 8
;             for (int pp = 0; pp < 32; ++pp) { b0 += *(const f32x4*)(bias + pp * 256 + col0 + bj * HALF); b1 += *(const f32x4*)(bias + pp * 256 + col0 + bj * HALF + 4); }
	s_setprio 0
	ds_read_b128 v[162:165], v156 offset:49152
	ds_read_b128 v[166:169], v156 offset:50176
	ds_read_b128 v[170:173], v156 offset:51200
	ds_read_b128 v[174:177], v156 offset:52224
	ds_read_b128 v[178:181], v156 offset:53248
	ds_read_b128 v[182:185], v156 offset:54272
	ds_read_b128 v[186:189], v156 offset:55296
	ds_read_b128 v[190:193], v156 offset:56320
	s_add_i32 s15, s68, s29
	v_lshl_add_u64 v[154:155], v[154:155], 0, s[8:9]
	s_mov_b32 m0, s15
	s_nop 0
	global_load_lds_dwordx4 v[154:155], off
	v_lshl_add_u64 v[154:155], v[210:211], 0, s[8:9]
	s_add_i32 m0, s15, 0x2000
	s_nop 0
	global_load_lds_dwordx4 v[154:155], off
	s_mov_b32 m0, s62
	v_lshl_add_u64 v[154:155], v[212:213], 0, s[8:9]
	global_load_lds_dwordx4 v[154:155], off
	v_lshl_add_u64 v[154:155], v[216:217], 0, s[8:9]
	s_mov_b32 m0, s63
	s_nop 0
	global_load_lds_dwordx4 v[154:155], off
	s_add_u32 s6, s6, 0x100080
	s_addc_u32 s7, s7, 0
	s_add_i32 s14, s14, s29
	s_mov_b32 m0, s14
	s_nop 0
	global_load_lds_dwordx4 v2, s[6:7]
	s_add_i32 m0, s14, 0x2000
	s_nop 0
	global_load_lds_dwordx4 v136, s[6:7]
	s_add_i32 s67, s67, 2
	s_add_u32 s4, s4, 0x100
	s_addc_u32 s5, s5, 0
	s_add_u32 s65, s65, 0x100
	s_addc_u32 s66, s66, 0
	s_cmp_gt_u32 s67, 61
	s_waitcnt lgkmcnt(0)
	s_waitcnt vmcnt(6)
	s_setprio 1
	s_barrier
	v_mfma_f32_16x16x32_bf16 v[96:99], v[142:145], v[162:165], v[96:99]
	v_mfma_f32_16x16x32_bf16 v[92:95], v[150:153], v[162:165], v[92:95]
	v_mfma_f32_16x16x32_bf16 v[88:91], v[142:145], v[170:173], v[88:91]
	v_mfma_f32_16x16x32_bf16 v[84:87], v[150:153], v[170:173], v[84:87]
	v_mfma_f32_16x16x32_bf16 v[80:83], v[142:145], v[178:181], v[80:83]
	v_mfma_f32_16x16x32_bf16 v[76:79], v[150:153], v[178:181], v[76:79]
	v_mfma_f32_16x16x32_bf16 v[72:75], v[142:145], v[186:189], v[72:75]
	v_mfma_f32_16x16x32_bf16 v[68:71], v[150:153], v[186:189], v[68:71]
	v_mfma_f32_16x16x32_bf16 v[96:99], v[146:149], v[166:169], v[96:99]
	v_mfma_f32_16x16x32_bf16 v[92:95], v[158:161], v[166:169], v[92:95]
	v_mfma_f32_16x16x32_bf16 v[88:91], v[146:149], v[174:177], v[88:91]
	v_mfma_f32_16x16x32_bf16 v[84:87], v[158:161], v[174:177], v[84:87]
	v_mfma_f32_16x16x32_bf16 v[80:83], v[146:149], v[182:185], v[80:83]
	v_mfma_f32_16x16x32_bf16 v[76:79], v[158:161], v[182:185], v[76:79]
	v_mfma_f32_16x16x32_bf16 v[72:75], v[146:149], v[190:193], v[72:75]
	v_mfma_f32_16x16x32_bf16 v[68:71], v[158:161], v[190:193], v[68:71]
	v_mfma_f32_16x16x32_bf16 v[32:35], v[194:197], v[162:165], v[32:35]
	v_mfma_f32_16x16x32_bf16 v[28:31], v[202:205], v[162:165], v[28:31]
	v_mfma_f32_16x16x32_bf16 v[24:27], v[194:197], v[170:173], v[24:27]
	v_mfma_f32_16x16x32_bf16 v[20:23], v[202:205], v[170:173], v[20:23]
	v_mfma_f32_16x16x32_bf16 v[16:19], v[194:197], v[178:181], v[16:19]
	v_mfma_f32_16x16x32_bf16 v[12:15], v[202:205], v[178:181], v[12:15]
	v_mfma_f32_16x16x32_bf16 v[8:11], v[194:197], v[186:189], v[8:11]
	v_mfma_f32_16x16x32_bf16 v[4:7], v[202:205], v[186:189], v[4:7]
	v_mfma_f32_16x16x32_bf16 v[32:35], v[198:201], v[166:169], v[32:35]
	v_mfma_f32_16x16x32_bf16 v[28:31], v[206:209], v[166:169], v[28:31]
	v_mfma_f32_16x16x32_bf16 v[24:27], v[198:201], v[174:177], v[24:27]
	v_mfma_f32_16x16x32_bf16 v[20:23], v[206:209], v[174:177], v[20:23]
	v_mfma_f32_16x16x32_bf16 v[16:19], v[198:201], v[182:185], v[16:19]
	v_mfma_f32_16x16x32_bf16 v[12:15], v[206:209], v[182:185], v[12:15]
	v_mfma_f32_16x16x32_bf16 v[8:11], v[198:201], v[190:193], v[8:11]
	v_mfma_f32_16x16x32_bf16 v[4:7], v[206:209], v[190:193], v[4:7]
	s_barrier
	s_cbranch_scc0 .LBB0_491
	s_setprio 0
	v_mov_b32_e32 v157, v0
	s_lshl_b32 s1, s1, 8
	v_lshrrev_b32_e32 v142, 1, v157
	v_and_or_b32 v142, v142, 24, s1
	v_or_b32_e32 v154, s61, v142
	v_ashrrev_i32_e32 v155, 31, v154
	v_mov_b32_e32 v144, 0
	v_lshl_add_u64 v[142:143], v[154:155], 2, s[46:47]
	s_mov_b64 s[4:5], 0
	v_mov_b32_e32 v145, v144
	v_mov_b32_e32 v146, v144
	v_mov_b32_e32 v147, v144
	v_mov_b32_e32 v148, v144
	v_mov_b32_e32 v149, v144
	v_mov_b32_e32 v150, v144
	v_mov_b32_e32 v151, v144

; #define PG8_STAGE(bufoff, gbase, voff) do { _Pragma("unroll") for (int _i = 0; _i < 2; ++_i) \
;         __builtin_amdgcn_global_load_lds((const unsigned*)((const char*)(gbase) + (voff)[_i]), (LAS unsigned*)(lds + (bufoff) + ldsw + _i * 8192), 16, 0, 0); } while (0)
; #define PG8_LDA(dst, b, h) do { _Pragma("unroll") for (int m = 0; m < 4; ++m) _Pragma("unroll") for (int k = 0; k < 2; ++k) dst[m][k] = *(const LAS bf16x8*)(lds + PG8_SA(b, h) + aoff + m * 2048 + k * 1024); } while (0)
; #define PG8_LDB(dst, b, h) do { _Pragma("unroll") for (int n = 0; n < 2; ++n) _Pragma("unroll") for (int k = 0; k < 2; ++k) dst[n][k] = *(const LAS bf16x8*)(lds + PG8_SB(b, h) + boff + n * 2048 + k * 1024); } while (0)
; #define PG8_MMA(ai, bj, At, Bt) do { __builtin_amdgcn_s_setprio(1); _Pragma("unroll") for (int m = 0; m < 4; ++m) _Pragma("unroll") for (int n = 0; n < 2; ++n) _Pragma("unroll") for (int k = 0; k < 2; ++k) \
;         acc[ai][bj][m][n] = __builtin_amdgcn_mfma_f32_16x16x32_bf16(Bt[n][k], At[m][k], acc[ai][bj][m][n], 0, 0, 0); __builtin_amdgcn_s_setprio(0); } while (0)
; template <class Epi, class Sched>
; __device__ __forceinline__ void gemm_phase(LAS unsigned char* lds, const Gemm g, const Sched& S, const Epi& E) {
;     ...
;         for (int t = 0; t < nt; t += 2) {
;             const bool last = (t == nt - 2);
;             const char* a1 = cA + (size_t)(t + 1) * kstep;
;             const char* a2 = last ? nA : cA + (size_t)(t + 2) * kstep; const char* b2 = last ? nB : cB + (size_t)(t + 2) * kstep;
;             const char* a3 = a2 + kstep; const char* b3 = b2 + kstep;
;             if (last && has_next) S.a_ready(nxt);
;             PG8_LDB(B0, 0, 0); PG8_SCHED; PG8_LDA(At, 0, 0); PG8_STAGE(PG8_SA(1, 1), a1 + hstepA, voffA);
;             PG8_WAIT_L(8); PG8_BAR; PG8_WAIT_L(0); PG8_MMA(0, 0, At, B0); PG8_BAR; PG8_SCHED;
;             PG8_LDB(B1, 0, 1); PG8_STAGE(PG8_SB(0, 0), b2, voffB);
;             PG8_BAR; PG8_WAIT_L(0); PG8_MMA(0, 1, At, B1); PG8_BAR;
;             PG8_LDA(At, 0, 1); PG8_STAGE(PG8_SA(0, 0), a2, voffA);
;             PG8_BAR; PG8_WAIT_L(0); PG8_MMA(1, 0, At, B0); PG8_BAR; PG8_SCHED;
;             PG8_STAGE(PG8_SB(0, 1), b2 + hstepB, voffB);
;             PG8_WAIT_V(6); PG8_BAR; PG8_MMA(1, 1, At, B1); PG8_BAR;
;             PG8_LDB(B0, 1, 0); PG8_SCHED; PG8_LDA(At, 1, 0); PG8_STAGE(PG8_SA(0, 1), a2 + hstepA, voffA);
.LBB0_966:
	s_setprio 0
	s_add_u32 s20, s6, 0xfff80080
	s_addc_u32 s21, s7, -1
	s_add_i32 s52, 0, 0x10000
	v_add_u32_e32 v144, s52, v1
	ds_read_b128 v[132:135], v144
	ds_read_b128 v[136:139], v144 offset:1024
	ds_read_b128 v[140:143], v144 offset:2048
	ds_read_b128 v[144:147], v144 offset:3072
	s_cmp_eq_u32 s51, 28
	s_cselect_b32 s25, s15, s21
	s_cselect_b32 s24, s47, s20
	s_cselect_b32 s21, s1, s50
	s_cselect_b32 s20, s48, s49
	ds_read_b128 v[148:151], v224
	ds_read_b128 v[152:155], v224 offset:1024
	ds_read_b128 v[156:159], v224 offset:2048
	ds_read_b128 v[160:163], v224 offset:3072
	ds_read_b128 v[164:167], v224 offset:4096
	ds_read_b128 v[168:171], v224 offset:5120
	ds_read_b128 v[172:175], v224 offset:6144
	ds_read_b128 v[176:179], v224 offset:7168
	s_add_i32 s54, 0, 0x14000
	v_add_u32_e32 v202, s54, v1
	ds_read_b128 v[180:183], v202
	ds_read_b128 v[184:187], v202 offset:1024
	ds_read_b128 v[188:191], v202 offset:2048
	ds_read_b128 v[202:205], v202 offset:3072
	s_add_i32 m0, s31, 0xc000
	s_nop 0
	global_load_lds_dwordx4 v198, s[6:7]
	s_add_i32 m0, s31, 0xe000
	s_nop 0
	global_load_lds_dwordx4 v200, s[6:7]
	s_waitcnt lgkmcnt(0)
	s_setprio 1
	s_barrier
	v_mfma_f32_16x16x32_bf16 v[128:131], v[132:135], v[148:151], v[128:131]
	v_mfma_f32_16x16x32_bf16 v[124:127], v[140:143], v[148:151], v[124:127]
	v_mfma_f32_16x16x32_bf16 v[112:115], v[132:135], v[156:159], v[112:115]
	v_mfma_f32_16x16x32_bf16 v[108:111], v[140:143], v[156:159], v[108:111]
	v_mfma_f32_16x16x32_bf16 v[100:103], v[132:135], v[164:167], v[100:103]
	v_mfma_f32_16x16x32_bf16 v[92:95], v[140:143], v[164:167], v[92:95]
	v_mfma_f32_16x16x32_bf16 v[84:87], v[132:135], v[172:175], v[84:87]
	v_mfma_f32_16x16x32_bf16 v[76:79], v[140:143], v[172:175], v[76:79]
	v_mfma_f32_16x16x32_bf16 v[128:131], v[136:139], v[152:155], v[128:131]
	v_mfma_f32_16x16x32_bf16 v[124:127], v[144:147], v[152:155], v[124:127]
	v_mfma_f32_16x16x32_bf16 v[112:115], v[136:139], v[160:163], v[112:115]
	v_mfma_f32_16x16x32_bf16 v[108:111], v[144:147], v[160:163], v[108:111]
	v_mfma_f32_16x16x32_bf16 v[100:103], v[136:139], v[168:171], v[100:103]
	v_mfma_f32_16x16x32_bf16 v[92:95], v[144:147], v[168:171], v[92:95]
	v_mfma_f32_16x16x32_bf16 v[84:87], v[136:139], v[176:179], v[84:87]
	v_mfma_f32_16x16x32_bf16 v[76:79], v[144:147], v[176:179], v[76:79]
	v_mfma_f32_16x16x32_bf16 v[120:123], v[180:183], v[148:151], v[120:123]
	v_mfma_f32_16x16x32_bf16 v[116:119], v[188:191], v[148:151], v[116:119]
	v_mfma_f32_16x16x32_bf16 v[104:107], v[180:183], v[156:159], v[104:107]
	v_mfma_f32_16x16x32_bf16 v[96:99], v[188:191], v[156:159], v[96:99]
	v_mfma_f32_16x16x32_bf16 v[88:91], v[180:183], v[164:167], v[88:91]
	v_mfma_f32_16x16x32_bf16 v[80:83], v[188:191], v[164:167], v[80:83]
	v_mfma_f32_16x16x32_bf16 v[72:75], v[180:183], v[172:175], v[72:75]
	v_mfma_f32_16x16x32_bf16 v[68:71], v[188:191], v[172:175], v[68:71]
	v_mfma_f32_16x16x32_bf16 v[120:123], v[184:187], v[152:155], v[120:123]
	v_mfma_f32_16x16x32_bf16 v[116:119], v[202:205], v[152:155], v[116:119]
	v_mfma_f32_16x16x32_bf16 v[104:107], v[184:187], v[160:163], v[104:107]
	v_mfma_f32_16x16x32_bf16 v[96:99], v[202:205], v[160:163], v[96:99]
	v_mfma_f32_16x16x32_bf16 v[88:91], v[184:187], v[168:171], v[88:91]
	v_mfma_f32_16x16x32_bf16 v[80:83], v[202:205], v[168:171], v[80:83]
	v_mfma_f32_16x16x32_bf16 v[72:75], v[184:187], v[176:179], v[72:75]
	v_mfma_f32_16x16x32_bf16 v[68:71], v[202:205], v[176:179], v[68:71]
	s_barrier
	s_setprio 0
	ds_read_b128 v[148:151], v224 offset:16384
	ds_read_b128 v[152:155], v224 offset:17408
	ds_read_b128 v[156:159], v224 offset:18432
	ds_read_b128 v[160:163], v224 offset:19456
	ds_read_b128 v[164:167], v224 offset:20480
	ds_read_b128 v[168:171], v224 offset:21504
	ds_read_b128 v[172:175], v224 offset:22528
	ds_read_b128 v[176:179], v224 offset:23552
	s_add_i32 s52, s52, s30
	v_lshl_add_u64 v[206:207], s[20:21], 0, v[2:3]
	s_mov_b32 m0, s52
	s_nop 0
	global_load_lds_dwordx4 v[206:207], off
	v_lshl_add_u64 v[208:209], s[20:21], 0, v[192:193]
	s_add_i32 m0, s52, 0x2000
	s_nop 0
	global_load_lds_dwordx4 v[208:209], off
	s_mov_b32 m0, s31
	v_lshl_add_u64 v[210:211], s[24:25], 0, v[196:197]
	global_load_lds_dwordx4 v[210:211], off
	v_lshl_add_u64 v[212:213], s[24:25], 0, v[194:195]
	s_mov_b32 m0, s35
	s_nop 0
	global_load_lds_dwordx4 v[212:213], off
	s_add_u32 s52, s20, 0x80000
	s_addc_u32 s53, s21, 0
	s_add_i32 s54, s54, s30
	s_mov_b32 m0, s54
	s_nop 0
	global_load_lds_dwordx4 v2, s[52:53]
	s_add_i32 m0, s54, 0x2000
	s_nop 0
	global_load_lds_dwordx4 v192, s[52:53]
	s_waitcnt lgkmcnt(0)
	s_waitcnt vmcnt(6)
	s_setprio 1
	s_barrier
; #define PG8_STAGE(bufoff, gbase, voff) do { _Pragma("unroll") for (int _i = 0; _i < 2; ++_i) \
;         __builtin_amdgcn_global_load_lds((const unsigned*)((const char*)(gbase) + (voff)[_i]), (LAS unsigned*)(lds + (bufoff) + ldsw + _i * 8192), 16, 0, 0); } while (0)
; #define PG8_LDA(dst, b, h) do { _Pragma("unroll") for (int m = 0; m < 4; ++m) _Pragma("unroll") for (int k = 0; k < 2; ++k) dst[m][k] = *(const LAS bf16x8*)(lds + PG8_SA(b, h) + aoff + m * 2048 + k * 1024); } while (0)
; #define PG8_LDB(dst, b, h) do { _Pragma("unroll") for (int n = 0; n < 2; ++n) _Pragma("unroll") for (int k = 0; k < 2; ++k) dst[n][k] = *(const LAS bf16x8*)(lds + PG8_SB(b, h) + boff + n * 2048 + k * 1024); } while (0)
; #define PG8_MMA(ai, bj, At, Bt) do { __builtin_amdgcn_s_setprio(1); _Pragma("unroll") for (int m = 0; m < 4; ++m) _Pragma("unroll") for (int n = 0; n < 2; ++n) _Pragma("unroll") for (int k = 0; k < 2; ++k) \
;         acc[ai][bj][m][n] = __builtin_amdgcn_mfma_f32_16x16x32_bf16(Bt[n][k], At[m][k], acc[ai][bj][m][n], 0, 0, 0); __builtin_amdgcn_s_setprio(0); } while (0)
; #define PG8_WAIT_V(n) asm volatile("s_waitcnt vmcnt(" #n ")" ::: "memory")
; #define PG8_WAIT_L(n) asm volatile("s_waitcnt lgkmcnt(" #n ")" ::: "memory")
; #define PG8_BAR __builtin_amdgcn_s_barrier()
; #define PG8_SCHED __builtin_amdgcn_sched_barrier(0)
; template <class Epi, class Sched>
; __device__ __forceinline__ void gemm_phase(LAS unsigned char* lds, const Gemm g, const Sched& S, const Epi& E) {
;     ...
;             PG8_WAIT_V(6); PG8_BAR; PG8_MMA(1, 1, At, B1); PG8_BAR;
;             PG8_LDB(B0, 1, 0); PG8_SCHED; PG8_LDA(At, 1, 0); PG8_STAGE(PG8_SA(0, 1), a2 + hstepA, voffA);
;             PG8_WAIT_L(8); PG8_BAR; PG8_WAIT_L(0); PG8_MMA(0, 0, At, B0); PG8_BAR; PG8_SCHED;
;             PG8_LDB(B1, 1, 1); PG8_STAGE(PG8_SB(1, 0), b3, voffB);
;             PG8_BAR; PG8_WAIT_L(0); PG8_MMA(0, 1, At, B1); PG8_BAR;
;             PG8_LDA(At, 1, 1); PG8_STAGE(PG8_SA(1, 0), a3, voffA);
	v_mfma_f32_16x16x32_bf16 v[64:67], v[132:135], v[148:151], v[64:67]
	v_mfma_f32_16x16x32_bf16 v[60:63], v[140:143], v[148:151], v[60:63]
	v_mfma_f32_16x16x32_bf16 v[52:55], v[132:135], v[156:159], v[52:55]
	v_mfma_f32_16x16x32_bf16 v[44:47], v[140:143], v[156:159], v[44:47]
	v_mfma_f32_16x16x32_bf16 v[36:39], v[132:135], v[164:167], v[36:39]
	v_mfma_f32_16x16x32_bf16 v[28:31], v[140:143], v[164:167], v[28:31]
	v_mfma_f32_16x16x32_bf16 v[20:23], v[132:135], v[172:175], v[20:23]
	v_mfma_f32_16x16x32_bf16 v[12:15], v[140:143], v[172:175], v[12:15]
	v_mfma_f32_16x16x32_bf16 v[64:67], v[136:139], v[152:155], v[64:67]
	v_mfma_f32_16x16x32_bf16 v[60:63], v[144:147], v[152:155], v[60:63]
	v_mfma_f32_16x16x32_bf16 v[52:55], v[136:139], v[160:163], v[52:55]
	v_mfma_f32_16x16x32_bf16 v[44:47], v[144:147], v[160:163], v[44:47]
	v_mfma_f32_16x16x32_bf16 v[36:39], v[136:139], v[168:171], v[36:39]
	v_mfma_f32_16x16x32_bf16 v[28:31], v[144:147], v[168:171], v[28:31]
	v_mfma_f32_16x16x32_bf16 v[20:23], v[136:139], v[176:179], v[20:23]
	v_mfma_f32_16x16x32_bf16 v[12:15], v[144:147], v[176:179], v[12:15]
	v_mfma_f32_16x16x32_bf16 v[56:59], v[180:183], v[148:151], v[56:59]
	v_mfma_f32_16x16x32_bf16 v[48:51], v[188:191], v[148:151], v[48:51]
	v_mfma_f32_16x16x32_bf16 v[40:43], v[180:183], v[156:159], v[40:43]
	v_mfma_f32_16x16x32_bf16 v[32:35], v[188:191], v[156:159], v[32:35]
	v_mfma_f32_16x16x32_bf16 v[24:27], v[180:183], v[164:167], v[24:27]
	v_mfma_f32_16x16x32_bf16 v[16:19], v[188:191], v[164:167], v[16:19]
	v_mfma_f32_16x16x32_bf16 v[8:11], v[180:183], v[172:175], v[8:11]
	v_mfma_f32_16x16x32_bf16 v[4:7], v[188:191], v[172:175], v[4:7]
	v_mfma_f32_16x16x32_bf16 v[56:59], v[184:187], v[152:155], v[56:59]
	v_mfma_f32_16x16x32_bf16 v[48:51], v[202:205], v[152:155], v[48:51]
	v_mfma_f32_16x16x32_bf16 v[40:43], v[184:187], v[160:163], v[40:43]
	v_mfma_f32_16x16x32_bf16 v[32:35], v[202:205], v[160:163], v[32:35]
	v_mfma_f32_16x16x32_bf16 v[24:27], v[184:187], v[168:171], v[24:27]
	v_mfma_f32_16x16x32_bf16 v[16:19], v[202:205], v[168:171], v[16:19]
	v_mfma_f32_16x16x32_bf16 v[8:11], v[184:187], v[176:179], v[8:11]
	v_mfma_f32_16x16x32_bf16 v[4:7], v[202:205], v[176:179], v[4:7]
	s_barrier
	s_setprio 0
	s_add_i32 s52, 0, 0x18000
	v_add_u32_e32 v144, s52, v1
	ds_read_b128 v[132:135], v144
	ds_read_b128 v[136:139], v144 offset:1024
	ds_read_b128 v[140:143], v144 offset:2048
	ds_read_b128 v[144:147], v144 offset:3072
	s_add_u32 s24, s24, 0x80000
	s_addc_u32 s25, s25, 0
	ds_read_b128 v[148:151], v224 offset:32768
	ds_read_b128 v[152:155], v224 offset:33792
	ds_read_b128 v[156:159], v224 offset:34816
	ds_read_b128 v[160:163], v224 offset:35840
	ds_read_b128 v[164:167], v224 offset:36864
	ds_read_b128 v[168:171], v224 offset:37888
	ds_read_b128 v[172:175], v224 offset:38912
	ds_read_b128 v[176:179], v224 offset:39936
	s_mov_b32 m0, s36
	s_nop 0
	global_load_lds_dwordx4 v196, s[24:25]
	s_mov_b32 m0, s37
	s_nop 0
	global_load_lds_dwordx4 v194, s[24:25]
	s_add_i32 s24, 0, 0x1c000
	v_add_u32_e32 v202, s24, v1
	ds_read_b128 v[180:183], v202
	ds_read_b128 v[184:187], v202 offset:1024
	ds_read_b128 v[188:191], v202 offset:2048
	ds_read_b128 v[202:205], v202 offset:3072
	s_waitcnt lgkmcnt(0)
	s_setprio 1
	s_barrier
	v_mfma_f32_16x16x32_bf16 v[128:131], v[132:135], v[148:151], v[128:131]
	v_mfma_f32_16x16x32_bf16 v[124:127], v[140:143], v[148:151], v[124:127]
	v_mfma_f32_16x16x32_bf16 v[112:115], v[132:135], v[156:159], v[112:115]
	v_mfma_f32_16x16x32_bf16 v[108:111], v[140:143], v[156:159], v[108:111]
	v_mfma_f32_16x16x32_bf16 v[100:103], v[132:135], v[164:167], v[100:103]
	v_mfma_f32_16x16x32_bf16 v[92:95], v[140:143], v[164:167], v[92:95]
	v_mfma_f32_16x16x32_bf16 v[84:87], v[132:135], v[172:175], v[84:87]
	v_mfma_f32_16x16x32_bf16 v[76:79], v[140:143], v[172:175], v[76:79]
	v_mfma_f32_16x16x32_bf16 v[128:131], v[136:139], v[152:155], v[128:131]
	v_mfma_f32_16x16x32_bf16 v[124:127], v[144:147], v[152:155], v[124:127]
	v_mfma_f32_16x16x32_bf16 v[112:115], v[136:139], v[160:163], v[112:115]
	v_mfma_f32_16x16x32_bf16 v[108:111], v[144:147], v[160:163], v[108:111]
	v_mfma_f32_16x16x32_bf16 v[100:103], v[136:139], v[168:171], v[100:103]
	v_mfma_f32_16x16x32_bf16 v[92:95], v[144:147], v[168:171], v[92:95]
	v_mfma_f32_16x16x32_bf16 v[84:87], v[136:139], v[176:179], v[84:87]
	v_mfma_f32_16x16x32_bf16 v[76:79], v[144:147], v[176:179], v[76:79]
	v_mfma_f32_16x16x32_bf16 v[120:123], v[180:183], v[148:151], v[120:123]
	v_mfma_f32_16x16x32_bf16 v[116:119], v[188:191], v[148:151], v[116:119]
	v_mfma_f32_16x16x32_bf16 v[104:107], v[180:183], v[156:159], v[104:107]
	v_mfma_f32_16x16x32_bf16 v[96:99], v[188:191], v[156:159], v[96:99]
	v_mfma_f32_16x16x32_bf16 v[88:91], v[180:183], v[164:167], v[88:91]
	v_mfma_f32_16x16x32_bf16 v[80:83], v[188:191], v[164:167], v[80:83]
	v_mfma_f32_16x16x32_bf16 v[72:75], v[180:183], v[172:175], v[72:75]
	v_mfma_f32_16x16x32_bf16 v[68:71], v[188:191], v[172:175], v[68:71]
	v_mfma_f32_16x16x32_bf16 v[120:123], v[184:187], v[152:155], v[120:123]
	v_mfma_f32_16x16x32_bf16 v[116:119], v[202:205], v[152:155], v[116:119]
	v_mfma_f32_16x16x32_bf16 v[104:107], v[184:187], v[160:163], v[104:107]
	v_mfma_f32_16x16x32_bf16 v[96:99], v[202:205], v[160:163], v[96:99]
	v_mfma_f32_16x16x32_bf16 v[88:91], v[184:187], v[168:171], v[88:91]
	v_mfma_f32_16x16x32_bf16 v[80:83], v[202:205], v[168:171], v[80:83]
	v_mfma_f32_16x16x32_bf16 v[72:75], v[184:187], v[176:179], v[72:75]
	v_mfma_f32_16x16x32_bf16 v[68:71], v[202:205], v[176:179], v[68:71]
	s_barrier
; __device__ __forceinline__ int opaque_tid() { int t = threadIdx.x; asm volatile("" : "+v"(t)); return t; }
; #define PG8_STAGE(bufoff, gbase, voff) do { _Pragma("unroll") for (int _i = 0; _i < 2; ++_i) \
;         __builtin_amdgcn_global_load_lds((const unsigned*)((const char*)(gbase) + (voff)[_i]), (LAS unsigned*)(lds + (bufoff) + ldsw + _i * 8192), 16, 0, 0); } while (0)
; #define PG8_LDA(dst, b, h) do { _Pragma("unroll") for (int m = 0; m < 4; ++m) _Pragma("unroll") for (int k = 0; k < 2; ++k) dst[m][k] = *(const LAS bf16x8*)(lds + PG8_SA(b, h) + aoff + m * 2048 + k * 1024); } while (0)
; #define PG8_MMA(ai, bj, At, Bt) do { __builtin_amdgcn_s_setprio(1); _Pragma("unroll") for (int m = 0; m < 4; ++m) _Pragma("unroll") for (int n = 0; n < 2; ++n) _Pragma("unroll") for (int k = 0; k < 2; ++k) \
;         acc[ai][bj][m][n] = __builtin_amdgcn_mfma_f32_16x16x32_bf16(Bt[n][k], At[m][k], acc[ai][bj][m][n], 0, 0, 0); __builtin_amdgcn_s_setprio(0); } while (0)
; #define PG8_WAIT_V(n) asm volatile("s_waitcnt vmcnt(" #n ")" ::: "memory")
; #define PG8_WAIT_L(n) asm volatile("s_waitcnt lgkmcnt(" #n ")" ::: "memory")
; #define PG8_BAR __builtin_amdgcn_s_barrier()
; #define PG8_SCHED __builtin_amdgcn_sched_barrier(0)
;     __device__ __forceinline__ void operator()(const f32x4 (&acc)[2][2][4][2], const Unit& u, int wr, int wc, int, int) const {
;         const int ol_ = opaque_tid() & 63, fr = ol_ & 15, fq = ol_ >> 4;
;         const int row0 = u.pm * BM + wr * 64 + fr, col0 = u.pn * BM + wc * 32 + 8 * fq;
;         u32x4 cin[2][4][2];
; #pragma unroll
;         for (int ai = 0; ai < 2; ++ai)
; #pragma unroll
;             for (int m = 0; m < 4; ++m)
; #pragma unroll
;                 for (int bj = 0; bj < 2; ++bj) cin[ai][m][bj] = *(const u32x4*)(C + (size_t)(row0 + ai * HALF + m * 16) * ldc + col0 + bj * HALF);
; template <class Epi, class Sched>
; __device__ __forceinline__ void gemm_phase(LAS unsigned char* lds, const Gemm g, const Sched& S, const Epi& E) {
;     ...
;             PG8_LDA(At, 1, 1); PG8_STAGE(PG8_SA(1, 0), a3, voffA);
;             PG8_BAR; PG8_WAIT_L(0); PG8_MMA(1, 0, At, B0); PG8_BAR; PG8_SCHED;
;             PG8_STAGE(PG8_SB(1, 1), b3 + hstepB, voffB);
;             PG8_WAIT_V(6); PG8_BAR; PG8_MMA(1, 1, At, B1); PG8_BAR;
;         }
;         E(acc, cur, wr, wc, ui, fq);
;         S.done(cur);
;         if (!has_next) break;
	s_setprio 0
	ds_read_b128 v[148:151], v224 offset:49152
	ds_read_b128 v[152:155], v224 offset:50176
	ds_read_b128 v[156:159], v224 offset:51200
	ds_read_b128 v[160:163], v224 offset:52224
	ds_read_b128 v[164:167], v224 offset:53248
	ds_read_b128 v[168:171], v224 offset:54272
	ds_read_b128 v[172:175], v224 offset:55296
	ds_read_b128 v[176:179], v224 offset:56320
	s_add_i32 s25, s52, s30
	v_lshl_add_u64 v[206:207], v[206:207], 0, s[8:9]
	s_mov_b32 m0, s25
	s_nop 0
	global_load_lds_dwordx4 v[206:207], off
	v_lshl_add_u64 v[206:207], v[208:209], 0, s[8:9]
	s_add_i32 m0, s25, 0x2000
	s_nop 0
	global_load_lds_dwordx4 v[206:207], off
	s_mov_b32 m0, s40
	v_lshl_add_u64 v[206:207], v[210:211], 0, s[8:9]
	global_load_lds_dwordx4 v[206:207], off
	v_lshl_add_u64 v[206:207], v[212:213], 0, s[8:9]
	s_mov_b32 m0, s41
	s_nop 0
	global_load_lds_dwordx4 v[206:207], off
	s_add_u32 s20, s20, 0x80080
	s_addc_u32 s21, s21, 0
	s_add_i32 s24, s24, s30
	s_mov_b32 m0, s24
	s_nop 0
	global_load_lds_dwordx4 v2, s[20:21]
	s_add_i32 m0, s24, 0x2000
	s_nop 0
	global_load_lds_dwordx4 v192, s[20:21]
	s_add_i32 s51, s51, 2
	s_add_u32 s6, s6, 0x100
	s_addc_u32 s7, s7, 0
	s_add_u32 s49, s49, 0x100
	s_addc_u32 s50, s50, 0
	s_cmp_gt_u32 s51, 29
	s_waitcnt lgkmcnt(0)
	s_waitcnt vmcnt(6)
	s_setprio 1
	s_barrier
	v_mfma_f32_16x16x32_bf16 v[64:67], v[132:135], v[148:151], v[64:67]
	v_mfma_f32_16x16x32_bf16 v[60:63], v[140:143], v[148:151], v[60:63]
	v_mfma_f32_16x16x32_bf16 v[52:55], v[132:135], v[156:159], v[52:55]
	v_mfma_f32_16x16x32_bf16 v[44:47], v[140:143], v[156:159], v[44:47]
	v_mfma_f32_16x16x32_bf16 v[36:39], v[132:135], v[164:167], v[36:39]
	v_mfma_f32_16x16x32_bf16 v[28:31], v[140:143], v[164:167], v[28:31]
	v_mfma_f32_16x16x32_bf16 v[20:23], v[132:135], v[172:175], v[20:23]
	v_mfma_f32_16x16x32_bf16 v[12:15], v[140:143], v[172:175], v[12:15]
	v_mfma_f32_16x16x32_bf16 v[64:67], v[136:139], v[152:155], v[64:67]
	v_mfma_f32_16x16x32_bf16 v[60:63], v[144:147], v[152:155], v[60:63]
	v_mfma_f32_16x16x32_bf16 v[52:55], v[136:139], v[160:163], v[52:55]
	v_mfma_f32_16x16x32_bf16 v[44:47], v[144:147], v[160:163], v[44:47]
	v_mfma_f32_16x16x32_bf16 v[36:39], v[136:139], v[168:171], v[36:39]
	v_mfma_f32_16x16x32_bf16 v[28:31], v[144:147], v[168:171], v[28:31]
	v_mfma_f32_16x16x32_bf16 v[20:23], v[136:139], v[176:179], v[20:23]
	v_mfma_f32_16x16x32_bf16 v[12:15], v[144:147], v[176:179], v[12:15]
	v_mfma_f32_16x16x32_bf16 v[56:59], v[180:183], v[148:151], v[56:59]
	v_mfma_f32_16x16x32_bf16 v[48:51], v[188:191], v[148:151], v[48:51]
	v_mfma_f32_16x16x32_bf16 v[40:43], v[180:183], v[156:159], v[40:43]
	v_mfma_f32_16x16x32_bf16 v[32:35], v[188:191], v[156:159], v[32:35]
	v_mfma_f32_16x16x32_bf16 v[24:27], v[180:183], v[164:167], v[24:27]
	v_mfma_f32_16x16x32_bf16 v[16:19], v[188:191], v[164:167], v[16:19]
	v_mfma_f32_16x16x32_bf16 v[8:11], v[180:183], v[172:175], v[8:11]
	v_mfma_f32_16x16x32_bf16 v[4:7], v[188:191], v[172:175], v[4:7]
	v_mfma_f32_16x16x32_bf16 v[56:59], v[184:187], v[152:155], v[56:59]
	v_mfma_f32_16x16x32_bf16 v[48:51], v[202:205], v[152:155], v[48:51]
	v_mfma_f32_16x16x32_bf16 v[40:43], v[184:187], v[160:163], v[40:43]
	v_mfma_f32_16x16x32_bf16 v[32:35], v[202:205], v[160:163], v[32:35]
	v_mfma_f32_16x16x32_bf16 v[24:27], v[184:187], v[168:171], v[24:27]
	v_mfma_f32_16x16x32_bf16 v[16:19], v[202:205], v[168:171], v[16:19]
	v_mfma_f32_16x16x32_bf16 v[8:11], v[184:187], v[176:179], v[8:11]
	v_mfma_f32_16x16x32_bf16 v[4:7], v[202:205], v[176:179], v[4:7]
	s_barrier
	s_cbranch_scc0 .LBB0_966
	s_setprio 0
	v_mov_b32_e32 v133, v0
	s_lshl_b32 s1, s46, 8
	s_add_i32 s1, s1, s38
	v_and_or_b32 v132, v133, 15, s1
	s_lshl_b32 s1, s45, 8
	v_lshrrev_b32_e32 v133, 1, v133
	v_and_or_b32 v133, v133, 24, s1
	v_or_b32_e32 v134, s39, v133
	v_ashrrev_i32_e32 v135, 31, v134
	v_lshlrev_b64 v[202:203], 1, v[134:135]
	v_ashrrev_i32_e32 v133, 31, v132
	v_lshl_add_u64 v[134:135], s[88:89], 0, v[202:203]
	v_lshlrev_b64 v[226:227], 12, v[132:133]
	v_lshl_add_u64 v[136:137], v[134:135], 0, v[226:227]
	global_load_dwordx4 v[216:219], v[136:137], off
	global_load_dwordx4 v[188:191], v[136:137], off offset:256
	v_or_b32_e32 v136, 16, v132
	v_ashrrev_i32_e32 v137, 31, v136
	v_lshlrev_b64 v[222:223], 12, v[136:137]
	v_lshl_add_u64 v[136:137], v[134:135], 0, v[222:223]
	global_load_dwordx4 v[184:187], v[136:137], off
	global_load_dwordx4 v[180:183], v[136:137], off offset:256
	v_or_b32_e32 v136, 32, v132
	v_ashrrev_i32_e32 v137, 31, v136
	v_lshlrev_b64 v[220:221], 12, v[136:137]
	v_lshl_add_u64 v[136:137], v[134:135], 0, v[220:221]
	global_load_dwordx4 v[176:179], v[136:137], off
	global_load_dwordx4 v[168:171], v[136:137], off offset:256
	v_or_b32_e32 v132, 48, v132
	v_ashrrev_i32_e32 v133, 31, v132
	v_lshlrev_b64 v[212:213], 12, v[132:133]
	v_lshl_add_u64 v[132:133], v[134:135], 0, v[212:213]
	global_load_dwordx4 v[172:175], v[132:133], off
	global_load_dwordx4 v[164:167], v[132:133], off offset:256
	s_mov_b64 s[6:7], 0x80000
	v_lshl_add_u64 v[210:211], v[226:227], 0, s[6:7]
	v_lshl_add_u64 v[132:133], v[134:135], 0, v[210:211]
	global_load_dwordx4 v[160:163], v[132:133], off
	global_load_dwordx4 v[156:159], v[132:133], off offset:256
	s_mov_b64 s[6:7], 0x90000
	v_lshl_add_u64 v[208:209], v[226:227], 0, s[6:7]
	v_lshl_add_u64 v[132:133], v[134:135], 0, v[208:209]
	global_load_dwordx4 v[152:155], v[132:133], off
	global_load_dwordx4 v[148:151], v[132:133], off offset:256
	s_mov_b64 s[6:7], 0xa0000
	v_lshl_add_u64 v[206:207], v[226:227], 0, s[6:7]
	v_lshl_add_u64 v[132:133], v[134:135], 0, v[206:207]
	global_load_dwordx4 v[144:147], v[132:133], off
	global_load_dwordx4 v[140:143], v[132:133], off offset:256
	s_mov_b64 s[6:7], 0xb0000
	v_lshl_add_u64 v[204:205], v[226:227], 0, s[6:7]
	v_lshl_add_u64 v[132:133], v[134:135], 0, v[204:205]
	global_load_dwordx4 v[136:139], v[132:133], off
	s_nop 0
	global_load_dwordx4 v[132:135], v[132:133], off offset:256
	s_and_b64 vcc, exec, s[42:43]
	s_mov_b32 s45, s0
	s_mov_b32 s46, s14
	s_mov_b64 s[20:21], s[18:19]
	s_mov_b64 s[6:7], s[4:5]
	s_waitcnt vmcnt(0)
; __device__ __forceinline__ unsigned cvt_pk_bf16(float lo, float hi) { const f32x2 v = {lo, hi}; const bf16v2_ r = __builtin_convertvector(v, bf16v2_); return __builtin_bit_cast(unsigned, r); }
; __device__ __forceinline__ float bflo(unsigned w) { return __uint_as_float(w << 16); }
; __device__ __forceinline__ float bfhi(unsigned w) { return __uint_as_float(w & 0xffff0000u); }
;     __device__ __forceinline__ void operator()(const f32x4 (&acc)[2][2][4][2], const Unit& u, int wr, int wc, int, int) const {
;     ...
; #pragma unroll
;         for (int ai = 0; ai < 2; ++ai)
; #pragma unroll
;             for (int m = 0; m < 4; ++m)
; #pragma unroll
;                 for (int bj = 0; bj < 2; ++bj) { const u32x4 c = cin[ai][m][bj]; const f32x4 v0 = acc[ai][bj][m][0], v1 = acc[ai][bj][m][1];
;                     u32x4 w; w.x = cvt_pk_bf16(bflo(c.x) + v0[0], bfhi(c.x) + v0[1]); w.y = cvt_pk_bf16(bflo(c.y) + v0[2], bfhi(c.y) + v0[3]);
;                     w.z = cvt_pk_bf16(bflo(c.z) + v1[0], bfhi(c.z) + v1[1]); w.w = cvt_pk_bf16(bflo(c.w) + v1[2], bfhi(c.w) + v1[3]);
;                     *(u32x4*)(C + (size_t)(row0 + ai * HALF + m * 16) * ldc + col0 + bj * HALF) = w; }
	v_lshlrev_b32_e32 v228, 16, v216
	v_and_b32_e32 v229, 0xffff0000, v216
	v_lshlrev_b32_e32 v216, 16, v217
	v_and_b32_e32 v217, 0xffff0000, v217
	v_pk_add_f32 v[128:129], v[128:129], v[228:229]
	v_pk_add_f32 v[130:131], v[130:131], v[216:217]
	v_cvt_pk_bf16_f32 v128, v128, v129
	v_cvt_pk_bf16_f32 v129, v130, v131
	v_lshlrev_b32_e32 v130, 16, v218
	v_and_b32_e32 v131, 0xffff0000, v218
	v_pk_add_f32 v[124:125], v[124:125], v[130:131]
	s_nop 0
	v_cvt_pk_bf16_f32 v130, v124, v125
	v_lshlrev_b32_e32 v124, 16, v219
	v_and_b32_e32 v125, 0xffff0000, v219
	v_pk_add_f32 v[124:125], v[126:127], v[124:125]
	v_lshlrev_b32_e32 v126, 16, v188
	v_and_b32_e32 v127, 0xffff0000, v188
	v_pk_add_f32 v[120:121], v[120:121], v[126:127]
	v_lshlrev_b32_e32 v126, 16, v189
	v_and_b32_e32 v127, 0xffff0000, v189
	v_pk_add_f32 v[122:123], v[122:123], v[126:127]
	v_cvt_pk_bf16_f32 v120, v120, v121
	v_cvt_pk_bf16_f32 v121, v122, v123
	v_lshlrev_b32_e32 v122, 16, v190
	v_and_b32_e32 v123, 0xffff0000, v190
	v_pk_add_f32 v[116:117], v[116:117], v[122:123]
	v_cvt_pk_bf16_f32 v131, v124, v125
	v_cvt_pk_bf16_f32 v122, v116, v117
	v_lshlrev_b32_e32 v116, 16, v191
	v_and_b32_e32 v117, 0xffff0000, v191
	v_pk_add_f32 v[116:117], v[118:119], v[116:117]
	v_lshl_add_u64 v[124:125], s[88:89], 0, v[226:227]
	v_cvt_pk_bf16_f32 v123, v116, v117
	v_lshlrev_b32_e32 v116, 16, v184
	v_and_b32_e32 v117, 0xffff0000, v184
	v_pk_add_f32 v[112:113], v[112:113], v[116:117]
	v_lshlrev_b32_e32 v116, 16, v185
	v_and_b32_e32 v117, 0xffff0000, v185
	v_pk_add_f32 v[114:115], v[114:115], v[116:117]
	v_cvt_pk_bf16_f32 v112, v112, v113
	v_cvt_pk_bf16_f32 v113, v114, v115
	v_lshlrev_b32_e32 v114, 16, v186
	v_and_b32_e32 v115, 0xffff0000, v186
	v_pk_add_f32 v[108:109], v[108:109], v[114:115]
	v_lshl_add_u64 v[124:125], v[124:125], 0, v[202:203]
	v_cvt_pk_bf16_f32 v114, v108, v109
	v_lshlrev_b32_e32 v108, 16, v187
	v_and_b32_e32 v109, 0xffff0000, v187
	v_pk_add_f32 v[108:109], v[110:111], v[108:109]
	v_lshlrev_b32_e32 v110, 16, v180
	v_and_b32_e32 v111, 0xffff0000, v180
	v_pk_add_f32 v[104:105], v[104:105], v[110:111]
	v_lshlrev_b32_e32 v110, 16, v181
	v_and_b32_e32 v111, 0xffff0000, v181
	v_pk_add_f32 v[106:107], v[106:107], v[110:111]
	v_cvt_pk_bf16_f32 v104, v104, v105
	v_cvt_pk_bf16_f32 v105, v106, v107
	v_lshlrev_b32_e32 v106, 16, v182
	v_and_b32_e32 v107, 0xffff0000, v182
	v_pk_add_f32 v[96:97], v[96:97], v[106:107]
	v_cvt_pk_bf16_f32 v115, v108, v109
	v_cvt_pk_bf16_f32 v106, v96, v97
	v_lshlrev_b32_e32 v96, 16, v183
	v_and_b32_e32 v97, 0xffff0000, v183
	v_pk_add_f32 v[96:97], v[98:99], v[96:97]
	v_lshlrev_b32_e32 v98, 16, v177
	v_cvt_pk_bf16_f32 v107, v96, v97
	v_lshlrev_b32_e32 v96, 16, v176
	v_and_b32_e32 v97, 0xffff0000, v176
	v_and_b32_e32 v99, 0xffff0000, v177
	v_pk_add_f32 v[96:97], v[100:101], v[96:97]
	v_pk_add_f32 v[98:99], v[102:103], v[98:99]
	v_cvt_pk_bf16_f32 v96, v96, v97
	v_cvt_pk_bf16_f32 v97, v98, v99
	v_lshlrev_b32_e32 v98, 16, v178
	v_and_b32_e32 v99, 0xffff0000, v178
	v_pk_add_f32 v[92:93], v[92:93], v[98:99]
	v_lshl_add_u64 v[108:109], s[88:89], 0, v[222:223]
	v_cvt_pk_bf16_f32 v98, v92, v93
	v_lshlrev_b32_e32 v92, 16, v179
	v_and_b32_e32 v93, 0xffff0000, v179
	v_pk_add_f32 v[92:93], v[94:95], v[92:93]
	v_lshlrev_b32_e32 v94, 16, v168
	v_and_b32_e32 v95, 0xffff0000, v168
	v_pk_add_f32 v[88:89], v[88:89], v[94:95]
	v_lshlrev_b32_e32 v94, 16, v169
	v_and_b32_e32 v95, 0xffff0000, v169
	v_pk_add_f32 v[90:91], v[90:91], v[94:95]
	v_cvt_pk_bf16_f32 v88, v88, v89
	v_cvt_pk_bf16_f32 v89, v90, v91
	v_lshlrev_b32_e32 v90, 16, v170
	v_and_b32_e32 v91, 0xffff0000, v170
	v_pk_add_f32 v[80:81], v[80:81], v[90:91]
	v_cvt_pk_bf16_f32 v99, v92, v93
	v_cvt_pk_bf16_f32 v90, v80, v81
	v_lshlrev_b32_e32 v80, 16, v171
	v_and_b32_e32 v81, 0xffff0000, v171
	v_pk_add_f32 v[80:81], v[82:83], v[80:81]
	v_lshlrev_b32_e32 v82, 16, v173
	v_cvt_pk_bf16_f32 v91, v80, v81
	v_lshlrev_b32_e32 v80, 16, v172
	v_and_b32_e32 v81, 0xffff0000, v172
	v_and_b32_e32 v83, 0xffff0000, v173
	v_pk_add_f32 v[80:81], v[84:85], v[80:81]
	v_pk_add_f32 v[82:83], v[86:87], v[82:83]
	v_cvt_pk_bf16_f32 v80, v80, v81
	v_cvt_pk_bf16_f32 v81, v82, v83
	v_lshlrev_b32_e32 v82, 16, v174
	v_and_b32_e32 v83, 0xffff0000, v174
	v_pk_add_f32 v[76:77], v[76:77], v[82:83]
	v_lshl_add_u64 v[92:93], s[88:89], 0, v[220:221]
	v_cvt_pk_bf16_f32 v82, v76, v77
	v_lshlrev_b32_e32 v76, 16, v175
	v_and_b32_e32 v77, 0xffff0000, v175
	v_pk_add_f32 v[76:77], v[78:79], v[76:77]
	v_lshlrev_b32_e32 v78, 16, v164
	v_and_b32_e32 v79, 0xffff0000, v164
	v_pk_add_f32 v[72:73], v[72:73], v[78:79]
	v_lshlrev_b32_e32 v78, 16, v165
	v_and_b32_e32 v79, 0xffff0000, v165
	v_pk_add_f32 v[74:75], v[74:75], v[78:79]
	v_cvt_pk_bf16_f32 v72, v72, v73
	v_cvt_pk_bf16_f32 v73, v74, v75
	v_lshlrev_b32_e32 v74, 16, v166
	v_and_b32_e32 v75, 0xffff0000, v166
	v_pk_add_f32 v[68:69], v[68:69], v[74:75]
	v_cvt_pk_bf16_f32 v83, v76, v77
	v_cvt_pk_bf16_f32 v74, v68, v69
	v_lshlrev_b32_e32 v68, 16, v167
	v_and_b32_e32 v69, 0xffff0000, v167
	v_pk_add_f32 v[68:69], v[70:71], v[68:69]
	v_lshl_add_u64 v[76:77], s[88:89], 0, v[212:213]
	v_cvt_pk_bf16_f32 v75, v68, v69
	v_lshlrev_b32_e32 v68, 16, v160
	v_and_b32_e32 v69, 0xffff0000, v160
	v_pk_add_f32 v[64:65], v[64:65], v[68:69]
	v_lshlrev_b32_e32 v68, 16, v161
	v_and_b32_e32 v69, 0xffff0000, v161
	v_pk_add_f32 v[66:67], v[66:67], v[68:69]
	v_cvt_pk_bf16_f32 v64, v64, v65
	v_cvt_pk_bf16_f32 v65, v66, v67
	v_lshlrev_b32_e32 v66, 16, v162
	v_and_b32_e32 v67, 0xffff0000, v162
	v_pk_add_f32 v[60:61], v[60:61], v[66:67]
	v_lshl_add_u64 v[108:109], v[108:109], 0, v[202:203]
	v_cvt_pk_bf16_f32 v66, v60, v61
	v_lshlrev_b32_e32 v60, 16, v163
; __device__ __forceinline__ unsigned cvt_pk_bf16(float lo, float hi) { const f32x2 v = {lo, hi}; const bf16v2_ r = __builtin_convertvector(v, bf16v2_); return __builtin_bit_cast(unsigned, r); }
; __device__ __forceinline__ float bflo(unsigned w) { return __uint_as_float(w << 16); }
; __device__ __forceinline__ float bfhi(unsigned w) { return __uint_as_float(w & 0xffff0000u); }
;     __device__ __forceinline__ void operator()(const f32x4 (&acc)[2][2][4][2], const Unit& u, int wr, int wc, int, int) const {
;     ...
; #pragma unroll
;         for (int ai = 0; ai < 2; ++ai)
; #pragma unroll
;             for (int m = 0; m < 4; ++m)
; #pragma unroll
;                 for (int bj = 0; bj < 2; ++bj) { const u32x4 c = cin[ai][m][bj]; const f32x4 v0 = acc[ai][bj][m][0], v1 = acc[ai][bj][m][1];
;                     u32x4 w; w.x = cvt_pk_bf16(bflo(c.x) + v0[0], bfhi(c.x) + v0[1]); w.y = cvt_pk_bf16(bflo(c.y) + v0[2], bfhi(c.y) + v0[3]);
;                     w.z = cvt_pk_bf16(bflo(c.z) + v1[0], bfhi(c.z) + v1[1]); w.w = cvt_pk_bf16(bflo(c.w) + v1[2], bfhi(c.w) + v1[3]);
;                     *(u32x4*)(C + (size_t)(row0 + ai * HALF + m * 16) * ldc + col0 + bj * HALF) = w; }
	v_and_b32_e32 v61, 0xffff0000, v163
	v_pk_add_f32 v[60:61], v[62:63], v[60:61]
	v_lshlrev_b32_e32 v62, 16, v156
	v_and_b32_e32 v63, 0xffff0000, v156
	v_pk_add_f32 v[56:57], v[56:57], v[62:63]
	v_lshlrev_b32_e32 v62, 16, v157
	v_and_b32_e32 v63, 0xffff0000, v157
	v_pk_add_f32 v[58:59], v[58:59], v[62:63]
	v_cvt_pk_bf16_f32 v56, v56, v57
	v_cvt_pk_bf16_f32 v57, v58, v59
	v_lshlrev_b32_e32 v58, 16, v158
	v_and_b32_e32 v59, 0xffff0000, v158
	v_pk_add_f32 v[48:49], v[48:49], v[58:59]
	v_cvt_pk_bf16_f32 v67, v60, v61
	v_cvt_pk_bf16_f32 v58, v48, v49
	v_lshlrev_b32_e32 v48, 16, v159
	v_and_b32_e32 v49, 0xffff0000, v159
	v_pk_add_f32 v[48:49], v[50:51], v[48:49]
	v_lshlrev_b32_e32 v50, 16, v153
	v_cvt_pk_bf16_f32 v59, v48, v49
	v_lshlrev_b32_e32 v48, 16, v152
	v_and_b32_e32 v49, 0xffff0000, v152
	v_and_b32_e32 v51, 0xffff0000, v153
	v_pk_add_f32 v[48:49], v[52:53], v[48:49]
	v_pk_add_f32 v[50:51], v[54:55], v[50:51]
	v_cvt_pk_bf16_f32 v48, v48, v49
	v_cvt_pk_bf16_f32 v49, v50, v51
	v_lshlrev_b32_e32 v50, 16, v154
	v_and_b32_e32 v51, 0xffff0000, v154
	v_pk_add_f32 v[44:45], v[44:45], v[50:51]
	v_lshl_add_u64 v[60:61], s[88:89], 0, v[210:211]
	v_cvt_pk_bf16_f32 v50, v44, v45
	v_lshlrev_b32_e32 v44, 16, v155
	v_and_b32_e32 v45, 0xffff0000, v155
	v_pk_add_f32 v[44:45], v[46:47], v[44:45]
	v_lshlrev_b32_e32 v46, 16, v148
	v_and_b32_e32 v47, 0xffff0000, v148
	v_pk_add_f32 v[40:41], v[40:41], v[46:47]
	v_lshlrev_b32_e32 v46, 16, v149
	v_and_b32_e32 v47, 0xffff0000, v149
	v_pk_add_f32 v[42:43], v[42:43], v[46:47]
	v_cvt_pk_bf16_f32 v40, v40, v41
	v_cvt_pk_bf16_f32 v41, v42, v43
	v_lshlrev_b32_e32 v42, 16, v150
	v_and_b32_e32 v43, 0xffff0000, v150
	v_pk_add_f32 v[32:33], v[32:33], v[42:43]
	v_cvt_pk_bf16_f32 v51, v44, v45
	v_cvt_pk_bf16_f32 v42, v32, v33
	v_lshlrev_b32_e32 v32, 16, v151
	v_and_b32_e32 v33, 0xffff0000, v151
	v_pk_add_f32 v[32:33], v[34:35], v[32:33]
	v_lshlrev_b32_e32 v34, 16, v145
	v_cvt_pk_bf16_f32 v43, v32, v33
	v_lshlrev_b32_e32 v32, 16, v144
	v_and_b32_e32 v33, 0xffff0000, v144
	v_and_b32_e32 v35, 0xffff0000, v145
	v_pk_add_f32 v[32:33], v[36:37], v[32:33]
	v_pk_add_f32 v[34:35], v[38:39], v[34:35]
	v_cvt_pk_bf16_f32 v32, v32, v33
	v_cvt_pk_bf16_f32 v33, v34, v35
	v_lshlrev_b32_e32 v34, 16, v146
	v_and_b32_e32 v35, 0xffff0000, v146
	v_pk_add_f32 v[28:29], v[28:29], v[34:35]
	v_lshl_add_u64 v[44:45], s[88:89], 0, v[208:209]
	v_cvt_pk_bf16_f32 v34, v28, v29
	v_lshlrev_b32_e32 v28, 16, v147
	v_and_b32_e32 v29, 0xffff0000, v147
	v_pk_add_f32 v[28:29], v[30:31], v[28:29]
	v_lshlrev_b32_e32 v30, 16, v140
	v_and_b32_e32 v31, 0xffff0000, v140
	v_pk_add_f32 v[24:25], v[24:25], v[30:31]
	v_lshlrev_b32_e32 v30, 16, v141
	v_and_b32_e32 v31, 0xffff0000, v141
	v_pk_add_f32 v[26:27], v[26:27], v[30:31]
	v_cvt_pk_bf16_f32 v24, v24, v25
	v_cvt_pk_bf16_f32 v25, v26, v27
	v_lshlrev_b32_e32 v26, 16, v142
	v_and_b32_e32 v27, 0xffff0000, v142
	v_pk_add_f32 v[16:17], v[16:17], v[26:27]
	v_cvt_pk_bf16_f32 v35, v28, v29
	v_cvt_pk_bf16_f32 v26, v16, v17
	v_lshlrev_b32_e32 v16, 16, v143
	v_and_b32_e32 v17, 0xffff0000, v143
	v_pk_add_f32 v[16:17], v[18:19], v[16:17]
	v_lshlrev_b32_e32 v18, 16, v137
	v_cvt_pk_bf16_f32 v27, v16, v17
	v_lshlrev_b32_e32 v16, 16, v136
	v_and_b32_e32 v17, 0xffff0000, v136
	v_and_b32_e32 v19, 0xffff0000, v137
	v_pk_add_f32 v[16:17], v[20:21], v[16:17]
	v_pk_add_f32 v[18:19], v[22:23], v[18:19]
	v_cvt_pk_bf16_f32 v16, v16, v17
	v_cvt_pk_bf16_f32 v17, v18, v19
	v_lshlrev_b32_e32 v18, 16, v138
	v_and_b32_e32 v19, 0xffff0000, v138
	v_pk_add_f32 v[12:13], v[12:13], v[18:19]
	v_lshl_add_u64 v[28:29], s[88:89], 0, v[206:207]
	v_cvt_pk_bf16_f32 v18, v12, v13
	v_lshlrev_b32_e32 v12, 16, v139
	v_and_b32_e32 v13, 0xffff0000, v139
	v_pk_add_f32 v[12:13], v[14:15], v[12:13]
	v_lshlrev_b32_e32 v14, 16, v132
	v_and_b32_e32 v15, 0xffff0000, v132
	v_pk_add_f32 v[8:9], v[8:9], v[14:15]
	v_lshlrev_b32_e32 v14, 16, v133
	v_and_b32_e32 v15, 0xffff0000, v133
	v_pk_add_f32 v[10:11], v[10:11], v[14:15]
	v_cvt_pk_bf16_f32 v8, v8, v9
	v_cvt_pk_bf16_f32 v9, v10, v11
	v_lshlrev_b32_e32 v10, 16, v134
	v_and_b32_e32 v11, 0xffff0000, v134
	v_pk_add_f32 v[4:5], v[4:5], v[10:11]
	v_cvt_pk_bf16_f32 v19, v12, v13
	v_cvt_pk_bf16_f32 v10, v4, v5
	v_lshlrev_b32_e32 v4, 16, v135
	v_and_b32_e32 v5, 0xffff0000, v135
	v_lshl_add_u64 v[12:13], s[88:89], 0, v[204:205]
	v_pk_add_f32 v[4:5], v[6:7], v[4:5]
	v_lshl_add_u64 v[92:93], v[92:93], 0, v[202:203]
	v_lshl_add_u64 v[76:77], v[76:77], 0, v[202:203]
	v_lshl_add_u64 v[60:61], v[60:61], 0, v[202:203]
	v_lshl_add_u64 v[44:45], v[44:45], 0, v[202:203]
	v_lshl_add_u64 v[28:29], v[28:29], 0, v[202:203]
	v_lshl_add_u64 v[12:13], v[12:13], 0, v[202:203]
	v_cvt_pk_bf16_f32 v11, v4, v5
	global_store_dwordx4 v[124:125], v[128:131], off
	global_store_dwordx4 v[124:125], v[120:123], off offset:256
	global_store_dwordx4 v[108:109], v[112:115], off
	global_store_dwordx4 v[108:109], v[104:107], off offset:256
	global_store_dwordx4 v[92:93], v[96:99], off
	global_store_dwordx4 v[92:93], v[88:91], off offset:256
	global_store_dwordx4 v[76:77], v[80:83], off
	global_store_dwordx4 v[76:77], v[72:75], off offset:256
	global_store_dwordx4 v[60:61], v[64:67], off
	global_store_dwordx4 v[60:61], v[56:59], off offset:256
	global_store_dwordx4 v[44:45], v[48:51], off
	global_store_dwordx4 v[44:45], v[40:43], off offset:256
	global_store_dwordx4 v[28:29], v[32:35], off
	global_store_dwordx4 v[28:29], v[24:27], off offset:256
	global_store_dwordx4 v[12:13], v[16:19], off
	global_store_dwordx4 v[12:13], v[8:11], off offset:256
	s_cbranch_vccz .LBB0_959
	s_waitcnt vmcnt(0)
	s_cmpk_gt_u32 s2, 0xff
	s_cbranch_scc1 .LBB0_970
	s_barrier

; #define PG8_STAGE(bufoff, gbase, voff) do { _Pragma("unroll") for (int _i = 0; _i < 2; ++_i) \
;         __builtin_amdgcn_global_load_lds((const unsigned*)((const char*)(gbase) + (voff)[_i]), (LAS unsigned*)(lds + (bufoff) + ldsw + _i * 8192), 16, 0, 0); } while (0)
; #define PG8_LDA(dst, b, h) do { _Pragma("unroll") for (int m = 0; m < 4; ++m) _Pragma("unroll") for (int k = 0; k < 2; ++k) dst[m][k] = *(const LAS bf16x8*)(lds + PG8_SA(b, h) + aoff + m * 2048 + k * 1024); } while (0)
; #define PG8_LDB(dst, b, h) do { _Pragma("unroll") for (int n = 0; n < 2; ++n) _Pragma("unroll") for (int k = 0; k < 2; ++k) dst[n][k] = *(const LAS bf16x8*)(lds + PG8_SB(b, h) + boff + n * 2048 + k * 1024); } while (0)
; #define PG8_MMA(ai, bj, At, Bt) do { __builtin_amdgcn_s_setprio(1); _Pragma("unroll") for (int m = 0; m < 4; ++m) _Pragma("unroll") for (int n = 0; n < 2; ++n) _Pragma("unroll") for (int k = 0; k < 2; ++k) \
;         acc[ai][bj][m][n] = __builtin_amdgcn_mfma_f32_16x16x32_bf16(Bt[n][k], At[m][k], acc[ai][bj][m][n], 0, 0, 0); __builtin_amdgcn_s_setprio(0); } while (0)
; template <class Epi, class Sched>
; __device__ __forceinline__ void gemm_phase(LAS unsigned char* lds, const Gemm g, const Sched& S, const Epi& E) {
;     ...
;         for (int t = 0; t < nt; t += 2) {
;             const bool last = (t == nt - 2);
;             const char* a1 = cA + (size_t)(t + 1) * kstep;
;             const char* a2 = last ? nA : cA + (size_t)(t + 2) * kstep; const char* b2 = last ? nB : cB + (size_t)(t + 2) * kstep;
;             const char* a3 = a2 + kstep; const char* b3 = b2 + kstep;
;             if (last && has_next) S.a_ready(nxt);
;             PG8_LDB(B0, 0, 0); PG8_SCHED; PG8_LDA(At, 0, 0); PG8_STAGE(PG8_SA(1, 1), a1 + hstepA, voffA);
;             PG8_WAIT_L(8); PG8_BAR; PG8_WAIT_L(0); PG8_MMA(0, 0, At, B0); PG8_BAR; PG8_SCHED;
;             PG8_LDB(B1, 0, 1); PG8_STAGE(PG8_SB(0, 0), b2, voffB);
;             PG8_BAR; PG8_WAIT_L(0); PG8_MMA(0, 1, At, B1); PG8_BAR;
;             PG8_LDA(At, 0, 1); PG8_STAGE(PG8_SA(0, 0), a2, voffA);
;             PG8_BAR; PG8_WAIT_L(0); PG8_MMA(1, 0, At, B0); PG8_BAR; PG8_SCHED;
;             PG8_STAGE(PG8_SB(0, 1), b2 + hstepB, voffB);
;             PG8_WAIT_V(6); PG8_BAR; PG8_MMA(1, 1, At, B1); PG8_BAR;
;             PG8_LDB(B0, 1, 0); PG8_SCHED; PG8_LDA(At, 1, 0); PG8_STAGE(PG8_SA(0, 1), a2 + hstepA, voffA);
.LBB0_1094:
	s_setprio 0
	s_add_u32 s20, s18, 0xfff80080
	s_addc_u32 s21, s19, -1
	s_add_i32 s54, 0, 0x10000
	v_add_u32_e32 v146, s54, v1
	ds_read_b128 v[142:145], v146
	ds_read_b128 v[150:153], v146 offset:1024
	ds_read_b128 v[154:157], v146 offset:2048
	ds_read_b128 v[158:161], v146 offset:3072
	s_cmp_eq_u32 s53, 28
	s_cselect_b32 s25, s5, s21
	s_cselect_b32 s24, s49, s20
	s_cselect_b32 s21, s1, s52
	s_cselect_b32 s20, s50, s51
	ds_read_b128 v[162:165], v148
	ds_read_b128 v[166:169], v148 offset:1024
	ds_read_b128 v[170:173], v148 offset:2048
	ds_read_b128 v[174:177], v148 offset:3072
	ds_read_b128 v[178:181], v148 offset:4096
	ds_read_b128 v[182:185], v148 offset:5120
	ds_read_b128 v[186:189], v148 offset:6144
	ds_read_b128 v[190:193], v148 offset:7168
	s_add_i32 s56, 0, 0x14000
	v_add_u32_e32 v146, s56, v1
	ds_read_b128 v[194:197], v146
	ds_read_b128 v[198:201], v146 offset:1024
	ds_read_b128 v[202:205], v146 offset:2048
	ds_read_b128 v[206:209], v146 offset:3072
	s_add_i32 m0, s31, 0xc000
	s_nop 0
	global_load_lds_dwordx4 v138, s[18:19]
	s_add_i32 m0, s31, 0xe000
	s_nop 0
	global_load_lds_dwordx4 v140, s[18:19]
	s_waitcnt lgkmcnt(0)
	s_setprio 1
	s_barrier
	v_mfma_f32_16x16x32_bf16 v[128:131], v[142:145], v[162:165], v[128:131]
	v_mfma_f32_16x16x32_bf16 v[124:127], v[154:157], v[162:165], v[124:127]
	v_mfma_f32_16x16x32_bf16 v[120:123], v[142:145], v[170:173], v[120:123]
	v_mfma_f32_16x16x32_bf16 v[112:115], v[154:157], v[170:173], v[112:115]
	v_mfma_f32_16x16x32_bf16 v[104:107], v[142:145], v[178:181], v[104:107]
	v_mfma_f32_16x16x32_bf16 v[96:99], v[154:157], v[178:181], v[96:99]
	v_mfma_f32_16x16x32_bf16 v[88:91], v[142:145], v[186:189], v[88:91]
	v_mfma_f32_16x16x32_bf16 v[80:83], v[154:157], v[186:189], v[80:83]
	v_mfma_f32_16x16x32_bf16 v[128:131], v[150:153], v[166:169], v[128:131]
	v_mfma_f32_16x16x32_bf16 v[124:127], v[158:161], v[166:169], v[124:127]
	v_mfma_f32_16x16x32_bf16 v[120:123], v[150:153], v[174:177], v[120:123]
	v_mfma_f32_16x16x32_bf16 v[112:115], v[158:161], v[174:177], v[112:115]
	v_mfma_f32_16x16x32_bf16 v[104:107], v[150:153], v[182:185], v[104:107]
	v_mfma_f32_16x16x32_bf16 v[96:99], v[158:161], v[182:185], v[96:99]
	v_mfma_f32_16x16x32_bf16 v[88:91], v[150:153], v[190:193], v[88:91]
	v_mfma_f32_16x16x32_bf16 v[80:83], v[158:161], v[190:193], v[80:83]
	v_mfma_f32_16x16x32_bf16 v[116:119], v[194:197], v[162:165], v[116:119]
	v_mfma_f32_16x16x32_bf16 v[108:111], v[202:205], v[162:165], v[108:111]
	v_mfma_f32_16x16x32_bf16 v[100:103], v[194:197], v[170:173], v[100:103]
	v_mfma_f32_16x16x32_bf16 v[92:95], v[202:205], v[170:173], v[92:95]
	v_mfma_f32_16x16x32_bf16 v[84:87], v[194:197], v[178:181], v[84:87]
	v_mfma_f32_16x16x32_bf16 v[76:79], v[202:205], v[178:181], v[76:79]
	v_mfma_f32_16x16x32_bf16 v[72:75], v[194:197], v[186:189], v[72:75]
	v_mfma_f32_16x16x32_bf16 v[68:71], v[202:205], v[186:189], v[68:71]
	v_mfma_f32_16x16x32_bf16 v[116:119], v[198:201], v[166:169], v[116:119]
	v_mfma_f32_16x16x32_bf16 v[108:111], v[206:209], v[166:169], v[108:111]
	v_mfma_f32_16x16x32_bf16 v[100:103], v[198:201], v[174:177], v[100:103]
	v_mfma_f32_16x16x32_bf16 v[92:95], v[206:209], v[174:177], v[92:95]
	v_mfma_f32_16x16x32_bf16 v[84:87], v[198:201], v[182:185], v[84:87]
	v_mfma_f32_16x16x32_bf16 v[76:79], v[206:209], v[182:185], v[76:79]
	v_mfma_f32_16x16x32_bf16 v[72:75], v[198:201], v[190:193], v[72:75]
	v_mfma_f32_16x16x32_bf16 v[68:71], v[206:209], v[190:193], v[68:71]
	s_barrier
	s_setprio 0
	ds_read_b128 v[162:165], v148 offset:16384
	ds_read_b128 v[166:169], v148 offset:17408
	ds_read_b128 v[170:173], v148 offset:18432
	ds_read_b128 v[174:177], v148 offset:19456
	ds_read_b128 v[178:181], v148 offset:20480
	ds_read_b128 v[182:185], v148 offset:21504
	ds_read_b128 v[186:189], v148 offset:22528
	ds_read_b128 v[190:193], v148 offset:23552
	s_add_i32 s54, s54, s30
	v_lshl_add_u64 v[146:147], s[20:21], 0, v[2:3]
	s_mov_b32 m0, s54
	v_lshl_add_u64 v[210:211], s[20:21], 0, v[132:133]
	global_load_lds_dwordx4 v[146:147], off
	s_add_i32 m0, s54, 0x2000
	s_nop 0
	global_load_lds_dwordx4 v[210:211], off
	s_mov_b32 m0, s31
	v_lshl_add_u64 v[212:213], s[24:25], 0, v[136:137]
	global_load_lds_dwordx4 v[212:213], off
	v_lshl_add_u64 v[216:217], s[24:25], 0, v[134:135]
	s_mov_b32 m0, s35
	s_nop 0
	global_load_lds_dwordx4 v[216:217], off
	s_add_u32 s54, s20, 0x80000
	s_addc_u32 s55, s21, 0
	s_add_i32 s56, s56, s30
	s_mov_b32 m0, s56
	s_nop 0
	global_load_lds_dwordx4 v2, s[54:55]
	s_add_i32 m0, s56, 0x2000
	s_nop 0
	global_load_lds_dwordx4 v132, s[54:55]
	s_waitcnt lgkmcnt(0)
	s_waitcnt vmcnt(6)
	s_setprio 1
	s_barrier
; #define PG8_STAGE(bufoff, gbase, voff) do { _Pragma("unroll") for (int _i = 0; _i < 2; ++_i) \
;         __builtin_amdgcn_global_load_lds((const unsigned*)((const char*)(gbase) + (voff)[_i]), (LAS unsigned*)(lds + (bufoff) + ldsw + _i * 8192), 16, 0, 0); } while (0)
; #define PG8_LDA(dst, b, h) do { _Pragma("unroll") for (int m = 0; m < 4; ++m) _Pragma("unroll") for (int k = 0; k < 2; ++k) dst[m][k] = *(const LAS bf16x8*)(lds + PG8_SA(b, h) + aoff + m * 2048 + k * 1024); } while (0)
; #define PG8_LDB(dst, b, h) do { _Pragma("unroll") for (int n = 0; n < 2; ++n) _Pragma("unroll") for (int k = 0; k < 2; ++k) dst[n][k] = *(const LAS bf16x8*)(lds + PG8_SB(b, h) + boff + n * 2048 + k * 1024); } while (0)
; #define PG8_MMA(ai, bj, At, Bt) do { __builtin_amdgcn_s_setprio(1); _Pragma("unroll") for (int m = 0; m < 4; ++m) _Pragma("unroll") for (int n = 0; n < 2; ++n) _Pragma("unroll") for (int k = 0; k < 2; ++k) \
;         acc[ai][bj][m][n] = __builtin_amdgcn_mfma_f32_16x16x32_bf16(Bt[n][k], At[m][k], acc[ai][bj][m][n], 0, 0, 0); __builtin_amdgcn_s_setprio(0); } while (0)
; #define PG8_WAIT_V(n) asm volatile("s_waitcnt vmcnt(" #n ")" ::: "memory")
; #define PG8_WAIT_L(n) asm volatile("s_waitcnt lgkmcnt(" #n ")" ::: "memory")
; #define PG8_BAR __builtin_amdgcn_s_barrier()
; #define PG8_SCHED __builtin_amdgcn_sched_barrier(0)
; template <class Epi, class Sched>
; __device__ __forceinline__ void gemm_phase(LAS unsigned char* lds, const Gemm g, const Sched& S, const Epi& E) {
;     ...
;             PG8_WAIT_V(6); PG8_BAR; PG8_MMA(1, 1, At, B1); PG8_BAR;
;             PG8_LDB(B0, 1, 0); PG8_SCHED; PG8_LDA(At, 1, 0); PG8_STAGE(PG8_SA(0, 1), a2 + hstepA, voffA);
;             PG8_WAIT_L(8); PG8_BAR; PG8_WAIT_L(0); PG8_MMA(0, 0, At, B0); PG8_BAR; PG8_SCHED;
;             PG8_LDB(B1, 1, 1); PG8_STAGE(PG8_SB(1, 0), b3, voffB);
;             PG8_BAR; PG8_WAIT_L(0); PG8_MMA(0, 1, At, B1); PG8_BAR;
;             PG8_LDA(At, 1, 1); PG8_STAGE(PG8_SA(1, 0), a3, voffA);
	v_mfma_f32_16x16x32_bf16 v[64:67], v[142:145], v[162:165], v[64:67]
	v_mfma_f32_16x16x32_bf16 v[60:63], v[154:157], v[162:165], v[60:63]
	v_mfma_f32_16x16x32_bf16 v[56:59], v[142:145], v[170:173], v[56:59]
	v_mfma_f32_16x16x32_bf16 v[48:51], v[154:157], v[170:173], v[48:51]
	v_mfma_f32_16x16x32_bf16 v[40:43], v[142:145], v[178:181], v[40:43]
	v_mfma_f32_16x16x32_bf16 v[32:35], v[154:157], v[178:181], v[32:35]
	v_mfma_f32_16x16x32_bf16 v[24:27], v[142:145], v[186:189], v[24:27]
	v_mfma_f32_16x16x32_bf16 v[16:19], v[154:157], v[186:189], v[16:19]
	v_mfma_f32_16x16x32_bf16 v[64:67], v[150:153], v[166:169], v[64:67]
	v_mfma_f32_16x16x32_bf16 v[60:63], v[158:161], v[166:169], v[60:63]
	v_mfma_f32_16x16x32_bf16 v[56:59], v[150:153], v[174:177], v[56:59]
	v_mfma_f32_16x16x32_bf16 v[48:51], v[158:161], v[174:177], v[48:51]
	v_mfma_f32_16x16x32_bf16 v[40:43], v[150:153], v[182:185], v[40:43]
	v_mfma_f32_16x16x32_bf16 v[32:35], v[158:161], v[182:185], v[32:35]
	v_mfma_f32_16x16x32_bf16 v[24:27], v[150:153], v[190:193], v[24:27]
	v_mfma_f32_16x16x32_bf16 v[16:19], v[158:161], v[190:193], v[16:19]
	v_mfma_f32_16x16x32_bf16 v[52:55], v[194:197], v[162:165], v[52:55]
	v_mfma_f32_16x16x32_bf16 v[44:47], v[202:205], v[162:165], v[44:47]
	v_mfma_f32_16x16x32_bf16 v[36:39], v[194:197], v[170:173], v[36:39]
	v_mfma_f32_16x16x32_bf16 v[28:31], v[202:205], v[170:173], v[28:31]
	v_mfma_f32_16x16x32_bf16 v[20:23], v[194:197], v[178:181], v[20:23]
	v_mfma_f32_16x16x32_bf16 v[12:15], v[202:205], v[178:181], v[12:15]
	v_mfma_f32_16x16x32_bf16 v[8:11], v[194:197], v[186:189], v[8:11]
	v_mfma_f32_16x16x32_bf16 v[4:7], v[202:205], v[186:189], v[4:7]
	v_mfma_f32_16x16x32_bf16 v[52:55], v[198:201], v[166:169], v[52:55]
	v_mfma_f32_16x16x32_bf16 v[44:47], v[206:209], v[166:169], v[44:47]
	v_mfma_f32_16x16x32_bf16 v[36:39], v[198:201], v[174:177], v[36:39]
	v_mfma_f32_16x16x32_bf16 v[28:31], v[206:209], v[174:177], v[28:31]
	v_mfma_f32_16x16x32_bf16 v[20:23], v[198:201], v[182:185], v[20:23]
	v_mfma_f32_16x16x32_bf16 v[12:15], v[206:209], v[182:185], v[12:15]
	v_mfma_f32_16x16x32_bf16 v[8:11], v[198:201], v[190:193], v[8:11]
	v_mfma_f32_16x16x32_bf16 v[4:7], v[206:209], v[190:193], v[4:7]
	s_barrier
	s_setprio 0
	s_add_i32 s54, 0, 0x18000
	v_add_u32_e32 v149, s54, v1
	ds_read_b128 v[142:145], v149
	ds_read_b128 v[150:153], v149 offset:1024
	ds_read_b128 v[154:157], v149 offset:2048
	ds_read_b128 v[158:161], v149 offset:3072
	s_add_u32 s24, s24, 0x80000
	s_addc_u32 s25, s25, 0
	ds_read_b128 v[162:165], v148 offset:32768
	ds_read_b128 v[166:169], v148 offset:33792
	ds_read_b128 v[170:173], v148 offset:34816
	ds_read_b128 v[174:177], v148 offset:35840
	ds_read_b128 v[178:181], v148 offset:36864
	ds_read_b128 v[182:185], v148 offset:37888
	ds_read_b128 v[186:189], v148 offset:38912
	ds_read_b128 v[190:193], v148 offset:39936
	s_mov_b32 m0, s36
	s_nop 0
	global_load_lds_dwordx4 v136, s[24:25]
	s_mov_b32 m0, s37
	s_nop 0
	global_load_lds_dwordx4 v134, s[24:25]
	s_add_i32 s24, 0, 0x1c000
	v_add_u32_e32 v149, s24, v1
	ds_read_b128 v[194:197], v149
	ds_read_b128 v[198:201], v149 offset:1024
	ds_read_b128 v[202:205], v149 offset:2048
	ds_read_b128 v[206:209], v149 offset:3072
	s_waitcnt lgkmcnt(0)
	s_setprio 1
	s_barrier
	v_mfma_f32_16x16x32_bf16 v[128:131], v[142:145], v[162:165], v[128:131]
	v_mfma_f32_16x16x32_bf16 v[124:127], v[154:157], v[162:165], v[124:127]
	v_mfma_f32_16x16x32_bf16 v[120:123], v[142:145], v[170:173], v[120:123]
	v_mfma_f32_16x16x32_bf16 v[112:115], v[154:157], v[170:173], v[112:115]
	v_mfma_f32_16x16x32_bf16 v[104:107], v[142:145], v[178:181], v[104:107]
	v_mfma_f32_16x16x32_bf16 v[96:99], v[154:157], v[178:181], v[96:99]
	v_mfma_f32_16x16x32_bf16 v[88:91], v[142:145], v[186:189], v[88:91]
	v_mfma_f32_16x16x32_bf16 v[80:83], v[154:157], v[186:189], v[80:83]
	v_mfma_f32_16x16x32_bf16 v[128:131], v[150:153], v[166:169], v[128:131]
	v_mfma_f32_16x16x32_bf16 v[124:127], v[158:161], v[166:169], v[124:127]
	v_mfma_f32_16x16x32_bf16 v[120:123], v[150:153], v[174:177], v[120:123]
	v_mfma_f32_16x16x32_bf16 v[112:115], v[158:161], v[174:177], v[112:115]
	v_mfma_f32_16x16x32_bf16 v[104:107], v[150:153], v[182:185], v[104:107]
	v_mfma_f32_16x16x32_bf16 v[96:99], v[158:161], v[182:185], v[96:99]
	v_mfma_f32_16x16x32_bf16 v[88:91], v[150:153], v[190:193], v[88:91]
	v_mfma_f32_16x16x32_bf16 v[80:83], v[158:161], v[190:193], v[80:83]
	v_mfma_f32_16x16x32_bf16 v[116:119], v[194:197], v[162:165], v[116:119]
	v_mfma_f32_16x16x32_bf16 v[108:111], v[202:205], v[162:165], v[108:111]
	v_mfma_f32_16x16x32_bf16 v[100:103], v[194:197], v[170:173], v[100:103]
	v_mfma_f32_16x16x32_bf16 v[92:95], v[202:205], v[170:173], v[92:95]
	v_mfma_f32_16x16x32_bf16 v[84:87], v[194:197], v[178:181], v[84:87]
	v_mfma_f32_16x16x32_bf16 v[76:79], v[202:205], v[178:181], v[76:79]
	v_mfma_f32_16x16x32_bf16 v[72:75], v[194:197], v[186:189], v[72:75]
	v_mfma_f32_16x16x32_bf16 v[68:71], v[202:205], v[186:189], v[68:71]
	v_mfma_f32_16x16x32_bf16 v[116:119], v[198:201], v[166:169], v[116:119]
	v_mfma_f32_16x16x32_bf16 v[108:111], v[206:209], v[166:169], v[108:111]
	v_mfma_f32_16x16x32_bf16 v[100:103], v[198:201], v[174:177], v[100:103]
	v_mfma_f32_16x16x32_bf16 v[92:95], v[206:209], v[174:177], v[92:95]
	v_mfma_f32_16x16x32_bf16 v[84:87], v[198:201], v[182:185], v[84:87]
	v_mfma_f32_16x16x32_bf16 v[76:79], v[206:209], v[182:185], v[76:79]
	v_mfma_f32_16x16x32_bf16 v[72:75], v[198:201], v[190:193], v[72:75]
	v_mfma_f32_16x16x32_bf16 v[68:71], v[206:209], v[190:193], v[68:71]
	s_barrier
; __device__ __forceinline__ int opaque_tid() { int t = threadIdx.x; asm volatile("" : "+v"(t)); return t; }
; #define PG8_STAGE(bufoff, gbase, voff) do { _Pragma("unroll") for (int _i = 0; _i < 2; ++_i) \
;         __builtin_amdgcn_global_load_lds((const unsigned*)((const char*)(gbase) + (voff)[_i]), (LAS unsigned*)(lds + (bufoff) + ldsw + _i * 8192), 16, 0, 0); } while (0)
; #define PG8_LDA(dst, b, h) do { _Pragma("unroll") for (int m = 0; m < 4; ++m) _Pragma("unroll") for (int k = 0; k < 2; ++k) dst[m][k] = *(const LAS bf16x8*)(lds + PG8_SA(b, h) + aoff + m * 2048 + k * 1024); } while (0)
; #define PG8_MMA(ai, bj, At, Bt) do { __builtin_amdgcn_s_setprio(1); _Pragma("unroll") for (int m = 0; m < 4; ++m) _Pragma("unroll") for (int n = 0; n < 2; ++n) _Pragma("unroll") for (int k = 0; k < 2; ++k) \
;         acc[ai][bj][m][n] = __builtin_amdgcn_mfma_f32_16x16x32_bf16(Bt[n][k], At[m][k], acc[ai][bj][m][n], 0, 0, 0); __builtin_amdgcn_s_setprio(0); } while (0)
; #define PG8_WAIT_V(n) asm volatile("s_waitcnt vmcnt(" #n ")" ::: "memory")
; #define PG8_WAIT_L(n) asm volatile("s_waitcnt lgkmcnt(" #n ")" ::: "memory")
; #define PG8_BAR __builtin_amdgcn_s_barrier()
; #define PG8_SCHED __builtin_amdgcn_sched_barrier(0)
;     __device__ __forceinline__ void operator()(const f32x4 (&acc)[2][2][4][2], const Unit& u, int wr, int wc, int ui, int) const {
;         const int ol_ = opaque_tid() & 63, fr = ol_ & 15, fq = ol_ >> 4;
;         const int row0 = u.pm * BM + wr * 64 + fr, col0 = u.pn * BM + wc * 32 + 8 * fq;
;         float r_[2][4];
;         if (rs) rs_read(r_, ui, wr, fr);
; template <class Epi, class Sched>
; __device__ __forceinline__ void gemm_phase(LAS unsigned char* lds, const Gemm g, const Sched& S, const Epi& E) {
;     ...
;             PG8_LDA(At, 1, 1); PG8_STAGE(PG8_SA(1, 0), a3, voffA);
;             PG8_BAR; PG8_WAIT_L(0); PG8_MMA(1, 0, At, B0); PG8_BAR; PG8_SCHED;
;             PG8_STAGE(PG8_SB(1, 1), b3 + hstepB, voffB);
;             PG8_WAIT_V(6); PG8_BAR; PG8_MMA(1, 1, At, B1); PG8_BAR;
;         }
;         E(acc, cur, wr, wc, ui, fq);
;         S.done(cur);
;         if (!has_next) break;
	s_setprio 0
	ds_read_b128 v[162:165], v148 offset:49152
	ds_read_b128 v[166:169], v148 offset:50176
	ds_read_b128 v[170:173], v148 offset:51200
	ds_read_b128 v[174:177], v148 offset:52224
	ds_read_b128 v[178:181], v148 offset:53248
	ds_read_b128 v[182:185], v148 offset:54272
	ds_read_b128 v[186:189], v148 offset:55296
	ds_read_b128 v[190:193], v148 offset:56320
	s_add_i32 s25, s54, s30
	v_lshl_add_u64 v[146:147], v[146:147], 0, s[8:9]
	s_mov_b32 m0, s25
	s_nop 0
	global_load_lds_dwordx4 v[146:147], off
	v_lshl_add_u64 v[146:147], v[210:211], 0, s[8:9]
	s_add_i32 m0, s25, 0x2000
	s_nop 0
	global_load_lds_dwordx4 v[146:147], off
	s_mov_b32 m0, s42
	v_lshl_add_u64 v[146:147], v[212:213], 0, s[8:9]
	global_load_lds_dwordx4 v[146:147], off
	v_lshl_add_u64 v[146:147], v[216:217], 0, s[8:9]
	s_mov_b32 m0, s43
	s_nop 0
	global_load_lds_dwordx4 v[146:147], off
	s_add_u32 s20, s20, 0x80080
	s_addc_u32 s21, s21, 0
	s_add_i32 s24, s24, s30
	s_mov_b32 m0, s24
	s_nop 0
	global_load_lds_dwordx4 v2, s[20:21]
	s_add_i32 m0, s24, 0x2000
	s_nop 0
	global_load_lds_dwordx4 v132, s[20:21]
	s_add_i32 s53, s53, 2
	s_add_u32 s18, s18, 0x100
	s_addc_u32 s19, s19, 0
	s_add_u32 s51, s51, 0x100
	s_addc_u32 s52, s52, 0
	s_cmp_gt_u32 s53, 29
	s_waitcnt lgkmcnt(0)
	s_waitcnt vmcnt(6)
	s_setprio 1
	s_barrier
	v_mfma_f32_16x16x32_bf16 v[64:67], v[142:145], v[162:165], v[64:67]
	v_mfma_f32_16x16x32_bf16 v[60:63], v[154:157], v[162:165], v[60:63]
	v_mfma_f32_16x16x32_bf16 v[56:59], v[142:145], v[170:173], v[56:59]
	v_mfma_f32_16x16x32_bf16 v[48:51], v[154:157], v[170:173], v[48:51]
	v_mfma_f32_16x16x32_bf16 v[40:43], v[142:145], v[178:181], v[40:43]
	v_mfma_f32_16x16x32_bf16 v[32:35], v[154:157], v[178:181], v[32:35]
	v_mfma_f32_16x16x32_bf16 v[24:27], v[142:145], v[186:189], v[24:27]
	v_mfma_f32_16x16x32_bf16 v[16:19], v[154:157], v[186:189], v[16:19]
	v_mfma_f32_16x16x32_bf16 v[64:67], v[150:153], v[166:169], v[64:67]
	v_mfma_f32_16x16x32_bf16 v[60:63], v[158:161], v[166:169], v[60:63]
	v_mfma_f32_16x16x32_bf16 v[56:59], v[150:153], v[174:177], v[56:59]
	v_mfma_f32_16x16x32_bf16 v[48:51], v[158:161], v[174:177], v[48:51]
	v_mfma_f32_16x16x32_bf16 v[40:43], v[150:153], v[182:185], v[40:43]
	v_mfma_f32_16x16x32_bf16 v[32:35], v[158:161], v[182:185], v[32:35]
	v_mfma_f32_16x16x32_bf16 v[24:27], v[150:153], v[190:193], v[24:27]
	v_mfma_f32_16x16x32_bf16 v[16:19], v[158:161], v[190:193], v[16:19]
	v_mfma_f32_16x16x32_bf16 v[52:55], v[194:197], v[162:165], v[52:55]
	v_mfma_f32_16x16x32_bf16 v[44:47], v[202:205], v[162:165], v[44:47]
	v_mfma_f32_16x16x32_bf16 v[36:39], v[194:197], v[170:173], v[36:39]
	v_mfma_f32_16x16x32_bf16 v[28:31], v[202:205], v[170:173], v[28:31]
	v_mfma_f32_16x16x32_bf16 v[20:23], v[194:197], v[178:181], v[20:23]
	v_mfma_f32_16x16x32_bf16 v[12:15], v[202:205], v[178:181], v[12:15]
	v_mfma_f32_16x16x32_bf16 v[8:11], v[194:197], v[186:189], v[8:11]
	v_mfma_f32_16x16x32_bf16 v[4:7], v[202:205], v[186:189], v[4:7]
	v_mfma_f32_16x16x32_bf16 v[52:55], v[198:201], v[166:169], v[52:55]
	v_mfma_f32_16x16x32_bf16 v[44:47], v[206:209], v[166:169], v[44:47]
	v_mfma_f32_16x16x32_bf16 v[36:39], v[198:201], v[174:177], v[36:39]
	v_mfma_f32_16x16x32_bf16 v[28:31], v[206:209], v[174:177], v[28:31]
	v_mfma_f32_16x16x32_bf16 v[20:23], v[198:201], v[182:185], v[20:23]
	v_mfma_f32_16x16x32_bf16 v[12:15], v[206:209], v[182:185], v[12:15]
	v_mfma_f32_16x16x32_bf16 v[8:11], v[198:201], v[190:193], v[8:11]
	v_mfma_f32_16x16x32_bf16 v[4:7], v[206:209], v[190:193], v[4:7]
	s_barrier
	s_cbranch_scc0 .LBB0_1094
	s_setprio 0
	s_lshl_b32 s1, s48, 10
	v_mov_b32_e32 v144, v0
	s_and_b32 s1, s1, 0x400
	s_add_i32 s1, s44, s1
	v_and_b32_e32 v145, 15, v144
	v_lshl_add_u32 v142, v145, 2, s1
	s_lshl_b32 s1, s47, 8
	v_lshrrev_b32_e32 v144, 1, v144
	v_and_or_b32 v144, v144, 24, s1
	ds_read2_b32 v[150:151], v142 offset1:16
	ds_read2_b32 v[152:153], v142 offset0:32 offset1:48
	ds_read2_b32 v[154:155], v142 offset0:128 offset1:144
	ds_read2_b32 v[142:143], v142 offset0:160 offset1:176
	v_or_b32_e32 v146, s39, v144
	v_or_b32_e32 v144, s38, v145
	v_lshl_add_u32 v149, s46, 8, v144
	v_ashrrev_i32_e32 v147, 31, v146
	v_mov_b64_e32 v[144:145], s[92:93]
	v_mad_i64_i32 v[156:157], s[18:19], v149, s11, v[144:145]
	v_lshlrev_b64 v[146:147], 1, v[146:147]
	s_waitcnt lgkmcnt(0)
; __device__ __forceinline__ unsigned cvt_pk_bf16(float lo, float hi) { const f32x2 v = {lo, hi}; const bf16v2_ r = __builtin_convertvector(v, bf16v2_); return __builtin_bit_cast(unsigned, r); }
;     __device__ __forceinline__ void operator()(const f32x4 (&acc)[2][2][4][2], const Unit& u, int wr, int wc, int ui, int) const {
;     ...
; #pragma unroll
;         for (int ai = 0; ai < 2; ++ai)
; #pragma unroll
;             for (int m = 0; m < 4; ++m) { bf16_t* rowp = O + (size_t)(row0 + ai * HALF + m * 16) * ldc + col0; const float r = r_[ai][m];
; #pragma unroll
;                 for (int bj = 0; bj < 2; ++bj) { const f32x4 v0 = acc[ai][bj][m][0] * r, v1 = acc[ai][bj][m][1] * r;
;                     u32x4 w; w.x = cvt_pk_bf16(v0[0], v0[1]); w.y = cvt_pk_bf16(v0[2], v0[3]); w.z = cvt_pk_bf16(v1[0], v1[1]); w.w = cvt_pk_bf16(v1[2], v1[3]);
;                     *(u32x4*)(rowp + bj * HALF) = w; } }
	v_pk_mul_f32 v[130:131], v[130:131], v[150:151] op_sel_hi:[1,0]
	v_pk_mul_f32 v[128:129], v[128:129], v[150:151] op_sel_hi:[1,0]
	v_pk_mul_f32 v[158:159], v[126:127], v[150:151] op_sel_hi:[1,0]
	v_pk_mul_f32 v[126:127], v[124:125], v[150:151] op_sel_hi:[1,0]
	v_lshl_add_u64 v[156:157], v[156:157], 0, v[146:147]
	v_cvt_pk_bf16_f32 v124, v128, v129
	v_cvt_pk_bf16_f32 v125, v130, v131
	v_cvt_pk_bf16_f32 v126, v126, v127
	v_cvt_pk_bf16_f32 v127, v158, v159
	global_store_dwordx4 v[156:157], v[124:127], off
	v_pk_mul_f32 v[118:119], v[118:119], v[150:151] op_sel_hi:[1,0]
	v_pk_mul_f32 v[116:117], v[116:117], v[150:151] op_sel_hi:[1,0]
	v_pk_mul_f32 v[124:125], v[110:111], v[150:151] op_sel_hi:[1,0]
	v_pk_mul_f32 v[110:111], v[108:109], v[150:151] op_sel_hi:[1,0]
	v_cvt_pk_bf16_f32 v108, v116, v117
	v_cvt_pk_bf16_f32 v109, v118, v119
	v_cvt_pk_bf16_f32 v110, v110, v111
	v_cvt_pk_bf16_f32 v111, v124, v125
	global_store_dwordx4 v[156:157], v[108:111], off offset:256
	v_mov_b32_e32 v118, v151
	v_pk_mul_f32 v[114:115], v[114:115], v[118:119] op_sel_hi:[1,0]
	v_or_b32_e32 v108, 16, v149
	v_mad_i64_i32 v[108:109], s[18:19], v108, s11, v[144:145]
	v_lshl_add_u64 v[116:117], v[108:109], 0, v[146:147]
	v_pk_mul_f32 v[110:111], v[122:123], v[118:119] op_sel_hi:[1,0]
	v_pk_mul_f32 v[108:109], v[120:121], v[118:119] op_sel_hi:[1,0]
	v_pk_mul_f32 v[112:113], v[112:113], v[118:119] op_sel_hi:[1,0]
	v_cvt_pk_bf16_f32 v108, v108, v109
	v_cvt_pk_bf16_f32 v109, v110, v111
	v_cvt_pk_bf16_f32 v110, v112, v113
	v_cvt_pk_bf16_f32 v111, v114, v115
	global_store_dwordx4 v[116:117], v[108:111], off
	v_pk_mul_f32 v[102:103], v[102:103], v[118:119] op_sel_hi:[1,0]
	v_pk_mul_f32 v[100:101], v[100:101], v[118:119] op_sel_hi:[1,0]
	v_pk_mul_f32 v[108:109], v[94:95], v[118:119] op_sel_hi:[1,0]
	v_pk_mul_f32 v[94:95], v[92:93], v[118:119] op_sel_hi:[1,0]
	v_cvt_pk_bf16_f32 v92, v100, v101
	v_cvt_pk_bf16_f32 v93, v102, v103
	v_cvt_pk_bf16_f32 v94, v94, v95
	v_cvt_pk_bf16_f32 v95, v108, v109
	global_store_dwordx4 v[116:117], v[92:95], off offset:256
	v_pk_mul_f32 v[98:99], v[98:99], v[152:153] op_sel_hi:[1,0]
	v_pk_mul_f32 v[96:97], v[96:97], v[152:153] op_sel_hi:[1,0]
	v_or_b32_e32 v92, 32, v149
	v_mad_i64_i32 v[92:93], s[18:19], v92, s11, v[144:145]
	v_lshl_add_u64 v[100:101], v[92:93], 0, v[146:147]
	v_pk_mul_f32 v[94:95], v[106:107], v[152:153] op_sel_hi:[1,0]
	v_pk_mul_f32 v[92:93], v[104:105], v[152:153] op_sel_hi:[1,0]
	v_pk_mul_f32 v[86:87], v[86:87], v[152:153] op_sel_hi:[1,0]
	v_cvt_pk_bf16_f32 v92, v92, v93
	v_cvt_pk_bf16_f32 v93, v94, v95
	v_cvt_pk_bf16_f32 v94, v96, v97
	v_cvt_pk_bf16_f32 v95, v98, v99
	global_store_dwordx4 v[100:101], v[92:95], off
	v_pk_mul_f32 v[84:85], v[84:85], v[152:153] op_sel_hi:[1,0]
	v_pk_mul_f32 v[66:67], v[66:67], v[154:155] op_sel_hi:[1,0]
	v_pk_mul_f32 v[92:93], v[78:79], v[152:153] op_sel_hi:[1,0]
	v_pk_mul_f32 v[78:79], v[76:77], v[152:153] op_sel_hi:[1,0]
	v_cvt_pk_bf16_f32 v76, v84, v85
	v_cvt_pk_bf16_f32 v77, v86, v87
	v_cvt_pk_bf16_f32 v78, v78, v79
	v_cvt_pk_bf16_f32 v79, v92, v93
	global_store_dwordx4 v[100:101], v[76:79], off offset:256
	v_mov_b32_e32 v86, v153
	v_pk_mul_f32 v[82:83], v[82:83], v[86:87] op_sel_hi:[1,0]
	v_or_b32_e32 v76, 48, v149
	v_mad_i64_i32 v[76:77], s[18:19], v76, s11, v[144:145]
	v_lshl_add_u64 v[84:85], v[76:77], 0, v[146:147]
	v_pk_mul_f32 v[78:79], v[90:91], v[86:87] op_sel_hi:[1,0]
	v_pk_mul_f32 v[76:77], v[88:89], v[86:87] op_sel_hi:[1,0]
	v_pk_mul_f32 v[80:81], v[80:81], v[86:87] op_sel_hi:[1,0]
	v_cvt_pk_bf16_f32 v76, v76, v77
	v_cvt_pk_bf16_f32 v77, v78, v79
	v_cvt_pk_bf16_f32 v78, v80, v81
	v_cvt_pk_bf16_f32 v79, v82, v83
	global_store_dwordx4 v[84:85], v[76:79], off
	v_pk_mul_f32 v[74:75], v[74:75], v[86:87] op_sel_hi:[1,0]
	v_pk_mul_f32 v[72:73], v[72:73], v[86:87] op_sel_hi:[1,0]
	v_pk_mul_f32 v[76:77], v[70:71], v[86:87] op_sel_hi:[1,0]
	v_pk_mul_f32 v[70:71], v[68:69], v[86:87] op_sel_hi:[1,0]
	v_cvt_pk_bf16_f32 v68, v72, v73
	v_cvt_pk_bf16_f32 v69, v74, v75
	v_cvt_pk_bf16_f32 v70, v70, v71
	v_cvt_pk_bf16_f32 v71, v76, v77
	global_store_dwordx4 v[84:85], v[68:71], off offset:256
; __device__ __forceinline__ unsigned cvt_pk_bf16(float lo, float hi) { const f32x2 v = {lo, hi}; const bf16v2_ r = __builtin_convertvector(v, bf16v2_); return __builtin_bit_cast(unsigned, r); }
;     __device__ __forceinline__ void operator()(const f32x4 (&acc)[2][2][4][2], const Unit& u, int wr, int wc, int ui, int) const {
;     ...
; #pragma unroll
;         for (int ai = 0; ai < 2; ++ai)
; #pragma unroll
;             for (int m = 0; m < 4; ++m) { bf16_t* rowp = O + (size_t)(row0 + ai * HALF + m * 16) * ldc + col0; const float r = r_[ai][m];
; #pragma unroll
;                 for (int bj = 0; bj < 2; ++bj) { const f32x4 v0 = acc[ai][bj][m][0] * r, v1 = acc[ai][bj][m][1] * r;
;                     u32x4 w; w.x = cvt_pk_bf16(v0[0], v0[1]); w.y = cvt_pk_bf16(v0[2], v0[3]); w.z = cvt_pk_bf16(v1[0], v1[1]); w.w = cvt_pk_bf16(v1[2], v1[3]);
;                     *(u32x4*)(rowp + bj * HALF) = w; } }
	v_pk_mul_f32 v[64:65], v[64:65], v[154:155] op_sel_hi:[1,0]
	v_pk_mul_f32 v[54:55], v[54:55], v[154:155] op_sel_hi:[1,0]
	v_add_u32_e32 v68, 0x80, v149
	v_mad_i64_i32 v[68:69], s[18:19], v68, s11, v[144:145]
	v_pk_mul_f32 v[70:71], v[62:63], v[154:155] op_sel_hi:[1,0]
	v_pk_mul_f32 v[62:63], v[60:61], v[154:155] op_sel_hi:[1,0]
	v_lshl_add_u64 v[68:69], v[68:69], 0, v[146:147]
	v_cvt_pk_bf16_f32 v60, v64, v65
	v_cvt_pk_bf16_f32 v61, v66, v67
	v_cvt_pk_bf16_f32 v62, v62, v63
	v_cvt_pk_bf16_f32 v63, v70, v71
	global_store_dwordx4 v[68:69], v[60:63], off
	v_pk_mul_f32 v[52:53], v[52:53], v[154:155] op_sel_hi:[1,0]
	v_pk_mul_f32 v[34:35], v[34:35], v[142:143] op_sel_hi:[1,0]
	v_pk_mul_f32 v[60:61], v[46:47], v[154:155] op_sel_hi:[1,0]
	v_pk_mul_f32 v[46:47], v[44:45], v[154:155] op_sel_hi:[1,0]
	v_cvt_pk_bf16_f32 v44, v52, v53
	v_cvt_pk_bf16_f32 v45, v54, v55
	v_cvt_pk_bf16_f32 v46, v46, v47
	v_cvt_pk_bf16_f32 v47, v60, v61
	global_store_dwordx4 v[68:69], v[44:47], off offset:256
	v_mov_b32_e32 v54, v155
	v_pk_mul_f32 v[50:51], v[50:51], v[54:55] op_sel_hi:[1,0]
	v_add_u32_e32 v44, 0x90, v149
	v_mad_i64_i32 v[44:45], s[18:19], v44, s11, v[144:145]
	v_lshl_add_u64 v[52:53], v[44:45], 0, v[146:147]
	v_pk_mul_f32 v[46:47], v[58:59], v[54:55] op_sel_hi:[1,0]
	v_pk_mul_f32 v[44:45], v[56:57], v[54:55] op_sel_hi:[1,0]
	v_pk_mul_f32 v[48:49], v[48:49], v[54:55] op_sel_hi:[1,0]
	v_cvt_pk_bf16_f32 v44, v44, v45
	v_cvt_pk_bf16_f32 v45, v46, v47
	v_cvt_pk_bf16_f32 v46, v48, v49
	v_cvt_pk_bf16_f32 v47, v50, v51
	global_store_dwordx4 v[52:53], v[44:47], off
	v_pk_mul_f32 v[38:39], v[38:39], v[54:55] op_sel_hi:[1,0]
	v_pk_mul_f32 v[36:37], v[36:37], v[54:55] op_sel_hi:[1,0]
	v_pk_mul_f32 v[44:45], v[30:31], v[54:55] op_sel_hi:[1,0]
	v_pk_mul_f32 v[30:31], v[28:29], v[54:55] op_sel_hi:[1,0]
	v_cvt_pk_bf16_f32 v28, v36, v37
	v_cvt_pk_bf16_f32 v29, v38, v39
	v_cvt_pk_bf16_f32 v30, v30, v31
	v_cvt_pk_bf16_f32 v31, v44, v45
	global_store_dwordx4 v[52:53], v[28:31], off offset:256
	v_pk_mul_f32 v[32:33], v[32:33], v[142:143] op_sel_hi:[1,0]
	v_pk_mul_f32 v[22:23], v[22:23], v[142:143] op_sel_hi:[1,0]
	v_add_u32_e32 v28, 0xa0, v149
	v_mad_i64_i32 v[28:29], s[18:19], v28, s11, v[144:145]
	v_lshl_add_u64 v[36:37], v[28:29], 0, v[146:147]
	v_pk_mul_f32 v[30:31], v[42:43], v[142:143] op_sel_hi:[1,0]
	v_pk_mul_f32 v[28:29], v[40:41], v[142:143] op_sel_hi:[1,0]
	v_pk_mul_f32 v[20:21], v[20:21], v[142:143] op_sel_hi:[1,0]
	v_cvt_pk_bf16_f32 v28, v28, v29
	v_cvt_pk_bf16_f32 v29, v30, v31
	v_cvt_pk_bf16_f32 v30, v32, v33
	v_cvt_pk_bf16_f32 v31, v34, v35
	global_store_dwordx4 v[36:37], v[28:31], off
	s_and_b64 vcc, exec, s[40:41]
	s_mov_b32 s47, s0
	v_pk_mul_f32 v[28:29], v[14:15], v[142:143] op_sel_hi:[1,0]
	v_pk_mul_f32 v[14:15], v[12:13], v[142:143] op_sel_hi:[1,0]
	v_cvt_pk_bf16_f32 v12, v20, v21
	v_cvt_pk_bf16_f32 v13, v22, v23
	v_cvt_pk_bf16_f32 v14, v14, v15
	v_cvt_pk_bf16_f32 v15, v28, v29
	global_store_dwordx4 v[36:37], v[12:15], off offset:256
	v_mov_b32_e32 v22, v143
	v_pk_mul_f32 v[18:19], v[18:19], v[22:23] op_sel_hi:[1,0]
	v_add_u32_e32 v12, 0xb0, v149
	v_mad_i64_i32 v[12:13], s[18:19], v12, s11, v[144:145]
	v_lshl_add_u64 v[20:21], v[12:13], 0, v[146:147]
	v_pk_mul_f32 v[14:15], v[26:27], v[22:23] op_sel_hi:[1,0]
	v_pk_mul_f32 v[12:13], v[24:25], v[22:23] op_sel_hi:[1,0]
	v_pk_mul_f32 v[16:17], v[16:17], v[22:23] op_sel_hi:[1,0]
	v_cvt_pk_bf16_f32 v12, v12, v13
	v_cvt_pk_bf16_f32 v13, v14, v15
	v_cvt_pk_bf16_f32 v14, v16, v17
	v_cvt_pk_bf16_f32 v15, v18, v19
	global_store_dwordx4 v[20:21], v[12:15], off
	v_pk_mul_f32 v[10:11], v[10:11], v[22:23] op_sel_hi:[1,0]
	v_pk_mul_f32 v[8:9], v[8:9], v[22:23] op_sel_hi:[1,0]
	v_pk_mul_f32 v[12:13], v[6:7], v[22:23] op_sel_hi:[1,0]
	v_pk_mul_f32 v[6:7], v[4:5], v[22:23] op_sel_hi:[1,0]
	v_cvt_pk_bf16_f32 v4, v8, v9
	v_cvt_pk_bf16_f32 v5, v10, v11
	v_cvt_pk_bf16_f32 v6, v6, v7
	v_cvt_pk_bf16_f32 v7, v12, v13
	s_mov_b32 s46, s4
	s_mov_b64 s[20:21], s[14:15]
	s_mov_b64 s[18:19], s[6:7]
	s_mov_b32 s48, s45
	global_store_dwordx4 v[20:21], v[4:7], off offset:256
	s_cbranch_vccz .LBB0_1089
	s_waitcnt vmcnt(0)
	s_cmpk_gt_u32 s2, 0xff
	s_cbranch_scc1 .LBB0_1098
	s_barrier

; #define PG8_STAGE(bufoff, gbase, voff) do { _Pragma("unroll") for (int _i = 0; _i < 2; ++_i) \
;         __builtin_amdgcn_global_load_lds((const unsigned*)((const char*)(gbase) + (voff)[_i]), (LAS unsigned*)(lds + (bufoff) + ldsw + _i * 8192), 16, 0, 0); } while (0)
; #define PG8_LDA(dst, b, h) do { _Pragma("unroll") for (int m = 0; m < 4; ++m) _Pragma("unroll") for (int k = 0; k < 2; ++k) dst[m][k] = *(const LAS bf16x8*)(lds + PG8_SA(b, h) + aoff + m * 2048 + k * 1024); } while (0)
; #define PG8_LDB(dst, b, h) do { _Pragma("unroll") for (int n = 0; n < 2; ++n) _Pragma("unroll") for (int k = 0; k < 2; ++k) dst[n][k] = *(const LAS bf16x8*)(lds + PG8_SB(b, h) + boff + n * 2048 + k * 1024); } while (0)
; #define PG8_MMA(ai, bj, At, Bt) do { __builtin_amdgcn_s_setprio(1); _Pragma("unroll") for (int m = 0; m < 4; ++m) _Pragma("unroll") for (int n = 0; n < 2; ++n) _Pragma("unroll") for (int k = 0; k < 2; ++k) \
;         acc[ai][bj][m][n] = __builtin_amdgcn_mfma_f32_16x16x32_bf16(Bt[n][k], At[m][k], acc[ai][bj][m][n], 0, 0, 0); __builtin_amdgcn_s_setprio(0); } while (0)
; template <class Epi, class Sched>
; __device__ __forceinline__ void gemm_phase(LAS unsigned char* lds, const Gemm g, const Sched& S, const Epi& E) {
;     ...
;         for (int t = 0; t < nt; t += 2) {
;             const bool last = (t == nt - 2);
;             const char* a1 = cA + (size_t)(t + 1) * kstep;
;             const char* a2 = last ? nA : cA + (size_t)(t + 2) * kstep; const char* b2 = last ? nB : cB + (size_t)(t + 2) * kstep;
;             const char* a3 = a2 + kstep; const char* b3 = b2 + kstep;
;             if (last && has_next) S.a_ready(nxt);
;             PG8_LDB(B0, 0, 0); PG8_SCHED; PG8_LDA(At, 0, 0); PG8_STAGE(PG8_SA(1, 1), a1 + hstepA, voffA);
;             PG8_WAIT_L(8); PG8_BAR; PG8_WAIT_L(0); PG8_MMA(0, 0, At, B0); PG8_BAR; PG8_SCHED;
;             PG8_LDB(B1, 0, 1); PG8_STAGE(PG8_SB(0, 0), b2, voffB);
;             PG8_BAR; PG8_WAIT_L(0); PG8_MMA(0, 1, At, B1); PG8_BAR;
;             PG8_LDA(At, 0, 1); PG8_STAGE(PG8_SA(0, 0), a2, voffA);
;             PG8_BAR; PG8_WAIT_L(0); PG8_MMA(1, 0, At, B0); PG8_BAR; PG8_SCHED;
;             PG8_STAGE(PG8_SB(0, 1), b2 + hstepB, voffB);
;             PG8_WAIT_V(6); PG8_BAR; PG8_MMA(1, 1, At, B1); PG8_BAR;
;             PG8_LDB(B0, 1, 0); PG8_SCHED; PG8_LDA(At, 1, 0); PG8_STAGE(PG8_SA(0, 1), a2 + hstepA, voffA);
.LBB0_1396:
	s_setprio 0
	s_add_u32 s20, s6, 0xfff80080
	s_addc_u32 s21, s7, -1
	s_add_i32 s52, 0, 0x10000
	v_add_u32_e32 v144, s52, v1
	ds_read_b128 v[132:135], v144
	ds_read_b128 v[136:139], v144 offset:1024
	ds_read_b128 v[140:143], v144 offset:2048
	ds_read_b128 v[144:147], v144 offset:3072
	s_cmp_eq_u32 s51, 28
	s_cselect_b32 s25, s15, s21
	s_cselect_b32 s24, s47, s20
	s_cselect_b32 s21, s1, s50
	s_cselect_b32 s20, s48, s49
	ds_read_b128 v[148:151], v224
	ds_read_b128 v[152:155], v224 offset:1024
	ds_read_b128 v[156:159], v224 offset:2048
	ds_read_b128 v[160:163], v224 offset:3072
	ds_read_b128 v[164:167], v224 offset:4096
	ds_read_b128 v[168:171], v224 offset:5120
	ds_read_b128 v[172:175], v224 offset:6144
	ds_read_b128 v[176:179], v224 offset:7168
	s_add_i32 s54, 0, 0x14000
	v_add_u32_e32 v202, s54, v1
	ds_read_b128 v[180:183], v202
	ds_read_b128 v[184:187], v202 offset:1024
	ds_read_b128 v[188:191], v202 offset:2048
	ds_read_b128 v[202:205], v202 offset:3072
	s_add_i32 m0, s31, 0xc000
	s_nop 0
	global_load_lds_dwordx4 v198, s[6:7]
	s_add_i32 m0, s31, 0xe000
	s_nop 0
	global_load_lds_dwordx4 v200, s[6:7]
	s_waitcnt lgkmcnt(0)
	s_setprio 1
	s_barrier
	v_mfma_f32_16x16x32_bf16 v[128:131], v[132:135], v[148:151], v[128:131]
	v_mfma_f32_16x16x32_bf16 v[124:127], v[140:143], v[148:151], v[124:127]
	v_mfma_f32_16x16x32_bf16 v[112:115], v[132:135], v[156:159], v[112:115]
	v_mfma_f32_16x16x32_bf16 v[108:111], v[140:143], v[156:159], v[108:111]
	v_mfma_f32_16x16x32_bf16 v[100:103], v[132:135], v[164:167], v[100:103]
	v_mfma_f32_16x16x32_bf16 v[92:95], v[140:143], v[164:167], v[92:95]
	v_mfma_f32_16x16x32_bf16 v[84:87], v[132:135], v[172:175], v[84:87]
	v_mfma_f32_16x16x32_bf16 v[76:79], v[140:143], v[172:175], v[76:79]
	v_mfma_f32_16x16x32_bf16 v[128:131], v[136:139], v[152:155], v[128:131]
	v_mfma_f32_16x16x32_bf16 v[124:127], v[144:147], v[152:155], v[124:127]
	v_mfma_f32_16x16x32_bf16 v[112:115], v[136:139], v[160:163], v[112:115]
	v_mfma_f32_16x16x32_bf16 v[108:111], v[144:147], v[160:163], v[108:111]
	v_mfma_f32_16x16x32_bf16 v[100:103], v[136:139], v[168:171], v[100:103]
	v_mfma_f32_16x16x32_bf16 v[92:95], v[144:147], v[168:171], v[92:95]
	v_mfma_f32_16x16x32_bf16 v[84:87], v[136:139], v[176:179], v[84:87]
	v_mfma_f32_16x16x32_bf16 v[76:79], v[144:147], v[176:179], v[76:79]
	v_mfma_f32_16x16x32_bf16 v[120:123], v[180:183], v[148:151], v[120:123]
	v_mfma_f32_16x16x32_bf16 v[116:119], v[188:191], v[148:151], v[116:119]
	v_mfma_f32_16x16x32_bf16 v[104:107], v[180:183], v[156:159], v[104:107]
	v_mfma_f32_16x16x32_bf16 v[96:99], v[188:191], v[156:159], v[96:99]
	v_mfma_f32_16x16x32_bf16 v[88:91], v[180:183], v[164:167], v[88:91]
	v_mfma_f32_16x16x32_bf16 v[80:83], v[188:191], v[164:167], v[80:83]
	v_mfma_f32_16x16x32_bf16 v[72:75], v[180:183], v[172:175], v[72:75]
	v_mfma_f32_16x16x32_bf16 v[68:71], v[188:191], v[172:175], v[68:71]
	v_mfma_f32_16x16x32_bf16 v[120:123], v[184:187], v[152:155], v[120:123]
	v_mfma_f32_16x16x32_bf16 v[116:119], v[202:205], v[152:155], v[116:119]
	v_mfma_f32_16x16x32_bf16 v[104:107], v[184:187], v[160:163], v[104:107]
	v_mfma_f32_16x16x32_bf16 v[96:99], v[202:205], v[160:163], v[96:99]
	v_mfma_f32_16x16x32_bf16 v[88:91], v[184:187], v[168:171], v[88:91]
	v_mfma_f32_16x16x32_bf16 v[80:83], v[202:205], v[168:171], v[80:83]
	v_mfma_f32_16x16x32_bf16 v[72:75], v[184:187], v[176:179], v[72:75]
	v_mfma_f32_16x16x32_bf16 v[68:71], v[202:205], v[176:179], v[68:71]
	s_barrier
	s_setprio 0
	ds_read_b128 v[148:151], v224 offset:16384
	ds_read_b128 v[152:155], v224 offset:17408
	ds_read_b128 v[156:159], v224 offset:18432
	ds_read_b128 v[160:163], v224 offset:19456
	ds_read_b128 v[164:167], v224 offset:20480
	ds_read_b128 v[168:171], v224 offset:21504
	ds_read_b128 v[172:175], v224 offset:22528
	ds_read_b128 v[176:179], v224 offset:23552
	s_add_i32 s52, s52, s30
	v_lshl_add_u64 v[206:207], s[20:21], 0, v[2:3]
	s_mov_b32 m0, s52
	s_nop 0
	global_load_lds_dwordx4 v[206:207], off
	v_lshl_add_u64 v[208:209], s[20:21], 0, v[192:193]
	s_add_i32 m0, s52, 0x2000
	s_nop 0
	global_load_lds_dwordx4 v[208:209], off
	s_mov_b32 m0, s31
	v_lshl_add_u64 v[210:211], s[24:25], 0, v[196:197]
	global_load_lds_dwordx4 v[210:211], off
	v_lshl_add_u64 v[212:213], s[24:25], 0, v[194:195]
	s_mov_b32 m0, s35
	s_nop 0
	global_load_lds_dwordx4 v[212:213], off
	s_add_u32 s52, s20, 0x80000
	s_addc_u32 s53, s21, 0
	s_add_i32 s54, s54, s30
	s_mov_b32 m0, s54
	s_nop 0
	global_load_lds_dwordx4 v2, s[52:53]
	s_add_i32 m0, s54, 0x2000
	s_nop 0
	global_load_lds_dwordx4 v192, s[52:53]
	s_waitcnt lgkmcnt(0)
	s_waitcnt vmcnt(6)
	s_setprio 1
	s_barrier
; #define PG8_STAGE(bufoff, gbase, voff) do { _Pragma("unroll") for (int _i = 0; _i < 2; ++_i) \
;         __builtin_amdgcn_global_load_lds((const unsigned*)((const char*)(gbase) + (voff)[_i]), (LAS unsigned*)(lds + (bufoff) + ldsw + _i * 8192), 16, 0, 0); } while (0)
; #define PG8_LDA(dst, b, h) do { _Pragma("unroll") for (int m = 0; m < 4; ++m) _Pragma("unroll") for (int k = 0; k < 2; ++k) dst[m][k] = *(const LAS bf16x8*)(lds + PG8_SA(b, h) + aoff + m * 2048 + k * 1024); } while (0)
; #define PG8_LDB(dst, b, h) do { _Pragma("unroll") for (int n = 0; n < 2; ++n) _Pragma("unroll") for (int k = 0; k < 2; ++k) dst[n][k] = *(const LAS bf16x8*)(lds + PG8_SB(b, h) + boff + n * 2048 + k * 1024); } while (0)
; #define PG8_MMA(ai, bj, At, Bt) do { __builtin_amdgcn_s_setprio(1); _Pragma("unroll") for (int m = 0; m < 4; ++m) _Pragma("unroll") for (int n = 0; n < 2; ++n) _Pragma("unroll") for (int k = 0; k < 2; ++k) \
;         acc[ai][bj][m][n] = __builtin_amdgcn_mfma_f32_16x16x32_bf16(Bt[n][k], At[m][k], acc[ai][bj][m][n], 0, 0, 0); __builtin_amdgcn_s_setprio(0); } while (0)
; #define PG8_WAIT_V(n) asm volatile("s_waitcnt vmcnt(" #n ")" ::: "memory")
; #define PG8_WAIT_L(n) asm volatile("s_waitcnt lgkmcnt(" #n ")" ::: "memory")
; #define PG8_BAR __builtin_amdgcn_s_barrier()
; #define PG8_SCHED __builtin_amdgcn_sched_barrier(0)
; template <class Epi, class Sched>
; __device__ __forceinline__ void gemm_phase(LAS unsigned char* lds, const Gemm g, const Sched& S, const Epi& E) {
;     ...
;             PG8_WAIT_V(6); PG8_BAR; PG8_MMA(1, 1, At, B1); PG8_BAR;
;             PG8_LDB(B0, 1, 0); PG8_SCHED; PG8_LDA(At, 1, 0); PG8_STAGE(PG8_SA(0, 1), a2 + hstepA, voffA);
;             PG8_WAIT_L(8); PG8_BAR; PG8_WAIT_L(0); PG8_MMA(0, 0, At, B0); PG8_BAR; PG8_SCHED;
;             PG8_LDB(B1, 1, 1); PG8_STAGE(PG8_SB(1, 0), b3, voffB);
;             PG8_BAR; PG8_WAIT_L(0); PG8_MMA(0, 1, At, B1); PG8_BAR;
;             PG8_LDA(At, 1, 1); PG8_STAGE(PG8_SA(1, 0), a3, voffA);
	v_mfma_f32_16x16x32_bf16 v[64:67], v[132:135], v[148:151], v[64:67]
	v_mfma_f32_16x16x32_bf16 v[60:63], v[140:143], v[148:151], v[60:63]
	v_mfma_f32_16x16x32_bf16 v[52:55], v[132:135], v[156:159], v[52:55]
	v_mfma_f32_16x16x32_bf16 v[44:47], v[140:143], v[156:159], v[44:47]
	v_mfma_f32_16x16x32_bf16 v[36:39], v[132:135], v[164:167], v[36:39]
	v_mfma_f32_16x16x32_bf16 v[28:31], v[140:143], v[164:167], v[28:31]
	v_mfma_f32_16x16x32_bf16 v[20:23], v[132:135], v[172:175], v[20:23]
	v_mfma_f32_16x16x32_bf16 v[12:15], v[140:143], v[172:175], v[12:15]
	v_mfma_f32_16x16x32_bf16 v[64:67], v[136:139], v[152:155], v[64:67]
	v_mfma_f32_16x16x32_bf16 v[60:63], v[144:147], v[152:155], v[60:63]
	v_mfma_f32_16x16x32_bf16 v[52:55], v[136:139], v[160:163], v[52:55]
	v_mfma_f32_16x16x32_bf16 v[44:47], v[144:147], v[160:163], v[44:47]
	v_mfma_f32_16x16x32_bf16 v[36:39], v[136:139], v[168:171], v[36:39]
	v_mfma_f32_16x16x32_bf16 v[28:31], v[144:147], v[168:171], v[28:31]
	v_mfma_f32_16x16x32_bf16 v[20:23], v[136:139], v[176:179], v[20:23]
	v_mfma_f32_16x16x32_bf16 v[12:15], v[144:147], v[176:179], v[12:15]
	v_mfma_f32_16x16x32_bf16 v[56:59], v[180:183], v[148:151], v[56:59]
	v_mfma_f32_16x16x32_bf16 v[48:51], v[188:191], v[148:151], v[48:51]
	v_mfma_f32_16x16x32_bf16 v[40:43], v[180:183], v[156:159], v[40:43]
	v_mfma_f32_16x16x32_bf16 v[32:35], v[188:191], v[156:159], v[32:35]
	v_mfma_f32_16x16x32_bf16 v[24:27], v[180:183], v[164:167], v[24:27]
	v_mfma_f32_16x16x32_bf16 v[16:19], v[188:191], v[164:167], v[16:19]
	v_mfma_f32_16x16x32_bf16 v[8:11], v[180:183], v[172:175], v[8:11]
	v_mfma_f32_16x16x32_bf16 v[4:7], v[188:191], v[172:175], v[4:7]
	v_mfma_f32_16x16x32_bf16 v[56:59], v[184:187], v[152:155], v[56:59]
	v_mfma_f32_16x16x32_bf16 v[48:51], v[202:205], v[152:155], v[48:51]
	v_mfma_f32_16x16x32_bf16 v[40:43], v[184:187], v[160:163], v[40:43]
	v_mfma_f32_16x16x32_bf16 v[32:35], v[202:205], v[160:163], v[32:35]
	v_mfma_f32_16x16x32_bf16 v[24:27], v[184:187], v[168:171], v[24:27]
	v_mfma_f32_16x16x32_bf16 v[16:19], v[202:205], v[168:171], v[16:19]
	v_mfma_f32_16x16x32_bf16 v[8:11], v[184:187], v[176:179], v[8:11]
	v_mfma_f32_16x16x32_bf16 v[4:7], v[202:205], v[176:179], v[4:7]
	s_barrier
	s_setprio 0
	s_add_i32 s52, 0, 0x18000
	v_add_u32_e32 v144, s52, v1
	ds_read_b128 v[132:135], v144
	ds_read_b128 v[136:139], v144 offset:1024
	ds_read_b128 v[140:143], v144 offset:2048
	ds_read_b128 v[144:147], v144 offset:3072
	s_add_u32 s24, s24, 0x80000
	s_addc_u32 s25, s25, 0
	ds_read_b128 v[148:151], v224 offset:32768
	ds_read_b128 v[152:155], v224 offset:33792
	ds_read_b128 v[156:159], v224 offset:34816
	ds_read_b128 v[160:163], v224 offset:35840
	ds_read_b128 v[164:167], v224 offset:36864
	ds_read_b128 v[168:171], v224 offset:37888
	ds_read_b128 v[172:175], v224 offset:38912
	ds_read_b128 v[176:179], v224 offset:39936
	s_mov_b32 m0, s36
	s_nop 0
	global_load_lds_dwordx4 v196, s[24:25]
	s_mov_b32 m0, s37
	s_nop 0
	global_load_lds_dwordx4 v194, s[24:25]
	s_add_i32 s24, 0, 0x1c000
	v_add_u32_e32 v202, s24, v1
	ds_read_b128 v[180:183], v202
	ds_read_b128 v[184:187], v202 offset:1024
	ds_read_b128 v[188:191], v202 offset:2048
	ds_read_b128 v[202:205], v202 offset:3072
	s_waitcnt lgkmcnt(0)
	s_setprio 1
	s_barrier
	v_mfma_f32_16x16x32_bf16 v[128:131], v[132:135], v[148:151], v[128:131]
	v_mfma_f32_16x16x32_bf16 v[124:127], v[140:143], v[148:151], v[124:127]
	v_mfma_f32_16x16x32_bf16 v[112:115], v[132:135], v[156:159], v[112:115]
	v_mfma_f32_16x16x32_bf16 v[108:111], v[140:143], v[156:159], v[108:111]
	v_mfma_f32_16x16x32_bf16 v[100:103], v[132:135], v[164:167], v[100:103]
	v_mfma_f32_16x16x32_bf16 v[92:95], v[140:143], v[164:167], v[92:95]
	v_mfma_f32_16x16x32_bf16 v[84:87], v[132:135], v[172:175], v[84:87]
	v_mfma_f32_16x16x32_bf16 v[76:79], v[140:143], v[172:175], v[76:79]
	v_mfma_f32_16x16x32_bf16 v[128:131], v[136:139], v[152:155], v[128:131]
	v_mfma_f32_16x16x32_bf16 v[124:127], v[144:147], v[152:155], v[124:127]
	v_mfma_f32_16x16x32_bf16 v[112:115], v[136:139], v[160:163], v[112:115]
	v_mfma_f32_16x16x32_bf16 v[108:111], v[144:147], v[160:163], v[108:111]
	v_mfma_f32_16x16x32_bf16 v[100:103], v[136:139], v[168:171], v[100:103]
	v_mfma_f32_16x16x32_bf16 v[92:95], v[144:147], v[168:171], v[92:95]
	v_mfma_f32_16x16x32_bf16 v[84:87], v[136:139], v[176:179], v[84:87]
	v_mfma_f32_16x16x32_bf16 v[76:79], v[144:147], v[176:179], v[76:79]
	v_mfma_f32_16x16x32_bf16 v[120:123], v[180:183], v[148:151], v[120:123]
	v_mfma_f32_16x16x32_bf16 v[116:119], v[188:191], v[148:151], v[116:119]
	v_mfma_f32_16x16x32_bf16 v[104:107], v[180:183], v[156:159], v[104:107]
	v_mfma_f32_16x16x32_bf16 v[96:99], v[188:191], v[156:159], v[96:99]
	v_mfma_f32_16x16x32_bf16 v[88:91], v[180:183], v[164:167], v[88:91]
	v_mfma_f32_16x16x32_bf16 v[80:83], v[188:191], v[164:167], v[80:83]
	v_mfma_f32_16x16x32_bf16 v[72:75], v[180:183], v[172:175], v[72:75]
	v_mfma_f32_16x16x32_bf16 v[68:71], v[188:191], v[172:175], v[68:71]
	v_mfma_f32_16x16x32_bf16 v[120:123], v[184:187], v[152:155], v[120:123]
	v_mfma_f32_16x16x32_bf16 v[116:119], v[202:205], v[152:155], v[116:119]
	v_mfma_f32_16x16x32_bf16 v[104:107], v[184:187], v[160:163], v[104:107]
	v_mfma_f32_16x16x32_bf16 v[96:99], v[202:205], v[160:163], v[96:99]
	v_mfma_f32_16x16x32_bf16 v[88:91], v[184:187], v[168:171], v[88:91]
	v_mfma_f32_16x16x32_bf16 v[80:83], v[202:205], v[168:171], v[80:83]
	v_mfma_f32_16x16x32_bf16 v[72:75], v[184:187], v[176:179], v[72:75]
	v_mfma_f32_16x16x32_bf16 v[68:71], v[202:205], v[176:179], v[68:71]
	s_barrier
; __device__ __forceinline__ int opaque_tid() { int t = threadIdx.x; asm volatile("" : "+v"(t)); return t; }
; #define PG8_STAGE(bufoff, gbase, voff) do { _Pragma("unroll") for (int _i = 0; _i < 2; ++_i) \
;         __builtin_amdgcn_global_load_lds((const unsigned*)((const char*)(gbase) + (voff)[_i]), (LAS unsigned*)(lds + (bufoff) + ldsw + _i * 8192), 16, 0, 0); } while (0)
; #define PG8_LDA(dst, b, h) do { _Pragma("unroll") for (int m = 0; m < 4; ++m) _Pragma("unroll") for (int k = 0; k < 2; ++k) dst[m][k] = *(const LAS bf16x8*)(lds + PG8_SA(b, h) + aoff + m * 2048 + k * 1024); } while (0)
; #define PG8_MMA(ai, bj, At, Bt) do { __builtin_amdgcn_s_setprio(1); _Pragma("unroll") for (int m = 0; m < 4; ++m) _Pragma("unroll") for (int n = 0; n < 2; ++n) _Pragma("unroll") for (int k = 0; k < 2; ++k) \
;         acc[ai][bj][m][n] = __builtin_amdgcn_mfma_f32_16x16x32_bf16(Bt[n][k], At[m][k], acc[ai][bj][m][n], 0, 0, 0); __builtin_amdgcn_s_setprio(0); } while (0)
; #define PG8_WAIT_V(n) asm volatile("s_waitcnt vmcnt(" #n ")" ::: "memory")
; #define PG8_WAIT_L(n) asm volatile("s_waitcnt lgkmcnt(" #n ")" ::: "memory")
; #define PG8_BAR __builtin_amdgcn_s_barrier()
; #define PG8_SCHED __builtin_amdgcn_sched_barrier(0)
;     __device__ __forceinline__ void operator()(const f32x4 (&acc)[2][2][4][2], const Unit& u, int wr, int wc, int, int) const {
;         const int ol_ = opaque_tid() & 63, fr = ol_ & 15, fq = ol_ >> 4;
;         const int row0 = u.pm * BM + wr * 64 + fr, col0 = u.pn * BM + wc * 32 + 8 * fq;
;         u32x4 cin[2][4][2];
; #pragma unroll
;         for (int ai = 0; ai < 2; ++ai)
; #pragma unroll
;             for (int m = 0; m < 4; ++m)
; #pragma unroll
;                 for (int bj = 0; bj < 2; ++bj) cin[ai][m][bj] = *(const u32x4*)(C + (size_t)(row0 + ai * HALF + m * 16) * ldc + col0 + bj * HALF);
; template <class Epi, class Sched>
; __device__ __forceinline__ void gemm_phase(LAS unsigned char* lds, const Gemm g, const Sched& S, const Epi& E) {
;     ...
;             PG8_LDA(At, 1, 1); PG8_STAGE(PG8_SA(1, 0), a3, voffA);
;             PG8_BAR; PG8_WAIT_L(0); PG8_MMA(1, 0, At, B0); PG8_BAR; PG8_SCHED;
;             PG8_STAGE(PG8_SB(1, 1), b3 + hstepB, voffB);
;             PG8_WAIT_V(6); PG8_BAR; PG8_MMA(1, 1, At, B1); PG8_BAR;
;         }
;         E(acc, cur, wr, wc, ui, fq);
;         S.done(cur);
;         if (!has_next) break;
	s_setprio 0
	ds_read_b128 v[148:151], v224 offset:49152
	ds_read_b128 v[152:155], v224 offset:50176
	ds_read_b128 v[156:159], v224 offset:51200
	ds_read_b128 v[160:163], v224 offset:52224
	ds_read_b128 v[164:167], v224 offset:53248
	ds_read_b128 v[168:171], v224 offset:54272
	ds_read_b128 v[172:175], v224 offset:55296
	ds_read_b128 v[176:179], v224 offset:56320
	s_add_i32 s25, s52, s30
	v_lshl_add_u64 v[206:207], v[206:207], 0, s[8:9]
	s_mov_b32 m0, s25
	s_nop 0
	global_load_lds_dwordx4 v[206:207], off
	v_lshl_add_u64 v[206:207], v[208:209], 0, s[8:9]
	s_add_i32 m0, s25, 0x2000
	s_nop 0
	global_load_lds_dwordx4 v[206:207], off
	s_mov_b32 m0, s42
	v_lshl_add_u64 v[206:207], v[210:211], 0, s[8:9]
	global_load_lds_dwordx4 v[206:207], off
	v_lshl_add_u64 v[206:207], v[212:213], 0, s[8:9]
	s_mov_b32 m0, s43
	s_nop 0
	global_load_lds_dwordx4 v[206:207], off
	s_add_u32 s20, s20, 0x80080
	s_addc_u32 s21, s21, 0
	s_add_i32 s24, s24, s30
	s_mov_b32 m0, s24
	s_nop 0
	global_load_lds_dwordx4 v2, s[20:21]
	s_add_i32 m0, s24, 0x2000
	s_nop 0
	global_load_lds_dwordx4 v192, s[20:21]
	s_add_i32 s51, s51, 2
	s_add_u32 s6, s6, 0x100
	s_addc_u32 s7, s7, 0
	s_add_u32 s49, s49, 0x100
	s_addc_u32 s50, s50, 0
	s_cmp_gt_u32 s51, 29
	s_waitcnt lgkmcnt(0)
	s_waitcnt vmcnt(6)
	s_setprio 1
	s_barrier
	v_mfma_f32_16x16x32_bf16 v[64:67], v[132:135], v[148:151], v[64:67]
	v_mfma_f32_16x16x32_bf16 v[60:63], v[140:143], v[148:151], v[60:63]
	v_mfma_f32_16x16x32_bf16 v[52:55], v[132:135], v[156:159], v[52:55]
	v_mfma_f32_16x16x32_bf16 v[44:47], v[140:143], v[156:159], v[44:47]
	v_mfma_f32_16x16x32_bf16 v[36:39], v[132:135], v[164:167], v[36:39]
	v_mfma_f32_16x16x32_bf16 v[28:31], v[140:143], v[164:167], v[28:31]
	v_mfma_f32_16x16x32_bf16 v[20:23], v[132:135], v[172:175], v[20:23]
	v_mfma_f32_16x16x32_bf16 v[12:15], v[140:143], v[172:175], v[12:15]
	v_mfma_f32_16x16x32_bf16 v[64:67], v[136:139], v[152:155], v[64:67]
	v_mfma_f32_16x16x32_bf16 v[60:63], v[144:147], v[152:155], v[60:63]
	v_mfma_f32_16x16x32_bf16 v[52:55], v[136:139], v[160:163], v[52:55]
	v_mfma_f32_16x16x32_bf16 v[44:47], v[144:147], v[160:163], v[44:47]
	v_mfma_f32_16x16x32_bf16 v[36:39], v[136:139], v[168:171], v[36:39]
	v_mfma_f32_16x16x32_bf16 v[28:31], v[144:147], v[168:171], v[28:31]
	v_mfma_f32_16x16x32_bf16 v[20:23], v[136:139], v[176:179], v[20:23]
	v_mfma_f32_16x16x32_bf16 v[12:15], v[144:147], v[176:179], v[12:15]
	v_mfma_f32_16x16x32_bf16 v[56:59], v[180:183], v[148:151], v[56:59]
	v_mfma_f32_16x16x32_bf16 v[48:51], v[188:191], v[148:151], v[48:51]
	v_mfma_f32_16x16x32_bf16 v[40:43], v[180:183], v[156:159], v[40:43]
	v_mfma_f32_16x16x32_bf16 v[32:35], v[188:191], v[156:159], v[32:35]
	v_mfma_f32_16x16x32_bf16 v[24:27], v[180:183], v[164:167], v[24:27]
	v_mfma_f32_16x16x32_bf16 v[16:19], v[188:191], v[164:167], v[16:19]
	v_mfma_f32_16x16x32_bf16 v[8:11], v[180:183], v[172:175], v[8:11]
	v_mfma_f32_16x16x32_bf16 v[4:7], v[188:191], v[172:175], v[4:7]
	v_mfma_f32_16x16x32_bf16 v[56:59], v[184:187], v[152:155], v[56:59]
	v_mfma_f32_16x16x32_bf16 v[48:51], v[202:205], v[152:155], v[48:51]
	v_mfma_f32_16x16x32_bf16 v[40:43], v[184:187], v[160:163], v[40:43]
	v_mfma_f32_16x16x32_bf16 v[32:35], v[202:205], v[160:163], v[32:35]
	v_mfma_f32_16x16x32_bf16 v[24:27], v[184:187], v[168:171], v[24:27]
	v_mfma_f32_16x16x32_bf16 v[16:19], v[202:205], v[168:171], v[16:19]
	v_mfma_f32_16x16x32_bf16 v[8:11], v[184:187], v[176:179], v[8:11]
	v_mfma_f32_16x16x32_bf16 v[4:7], v[202:205], v[176:179], v[4:7]
	s_barrier
	s_cbranch_scc0 .LBB0_1396
	s_setprio 0
	v_mov_b32_e32 v133, v0
	s_lshl_b32 s1, s46, 8
	s_add_i32 s1, s1, s38
	v_and_or_b32 v132, v133, 15, s1
	s_lshl_b32 s1, s45, 8
	v_lshrrev_b32_e32 v133, 1, v133
	v_and_or_b32 v133, v133, 24, s1
	v_or_b32_e32 v134, s39, v133
	v_ashrrev_i32_e32 v135, 31, v134
	v_lshlrev_b64 v[202:203], 1, v[134:135]
	v_ashrrev_i32_e32 v133, 31, v132
	v_lshl_add_u64 v[134:135], s[88:89], 0, v[202:203]
	v_lshlrev_b64 v[216:217], 12, v[132:133]
	v_lshl_add_u64 v[136:137], v[134:135], 0, v[216:217]
	global_load_dwordx4 v[226:229], v[136:137], off
	global_load_dwordx4 v[188:191], v[136:137], off offset:256
	v_or_b32_e32 v136, 16, v132
	v_ashrrev_i32_e32 v137, 31, v136
	v_lshlrev_b64 v[222:223], 12, v[136:137]
	v_lshl_add_u64 v[136:137], v[134:135], 0, v[222:223]
	global_load_dwordx4 v[184:187], v[136:137], off
	global_load_dwordx4 v[180:183], v[136:137], off offset:256
	v_or_b32_e32 v136, 32, v132
	v_ashrrev_i32_e32 v137, 31, v136
	v_lshlrev_b64 v[220:221], 12, v[136:137]
	v_lshl_add_u64 v[136:137], v[134:135], 0, v[220:221]
	global_load_dwordx4 v[176:179], v[136:137], off
	global_load_dwordx4 v[168:171], v[136:137], off offset:256
	v_or_b32_e32 v132, 48, v132
	v_ashrrev_i32_e32 v133, 31, v132
	v_lshlrev_b64 v[212:213], 12, v[132:133]
	v_lshl_add_u64 v[132:133], v[134:135], 0, v[212:213]
	global_load_dwordx4 v[172:175], v[132:133], off
	global_load_dwordx4 v[164:167], v[132:133], off offset:256
	s_mov_b64 s[6:7], 0x80000
	v_lshl_add_u64 v[210:211], v[216:217], 0, s[6:7]
	v_lshl_add_u64 v[132:133], v[134:135], 0, v[210:211]
	global_load_dwordx4 v[160:163], v[132:133], off
	global_load_dwordx4 v[156:159], v[132:133], off offset:256
	s_mov_b64 s[6:7], 0x90000
	v_lshl_add_u64 v[208:209], v[216:217], 0, s[6:7]
	v_lshl_add_u64 v[132:133], v[134:135], 0, v[208:209]
	global_load_dwordx4 v[152:155], v[132:133], off
	global_load_dwordx4 v[148:151], v[132:133], off offset:256
	s_mov_b64 s[6:7], 0xa0000
	v_lshl_add_u64 v[206:207], v[216:217], 0, s[6:7]
	v_lshl_add_u64 v[132:133], v[134:135], 0, v[206:207]
	global_load_dwordx4 v[144:147], v[132:133], off
	global_load_dwordx4 v[140:143], v[132:133], off offset:256
	s_mov_b64 s[6:7], 0xb0000
	v_lshl_add_u64 v[204:205], v[216:217], 0, s[6:7]
	v_lshl_add_u64 v[132:133], v[134:135], 0, v[204:205]
	global_load_dwordx4 v[136:139], v[132:133], off
	s_nop 0
	global_load_dwordx4 v[132:135], v[132:133], off offset:256
	s_and_b64 vcc, exec, s[40:41]
	s_mov_b32 s45, s0
	s_mov_b32 s46, s14
	s_mov_b64 s[20:21], s[18:19]
	s_mov_b64 s[6:7], s[4:5]
	s_waitcnt vmcnt(0)
; __device__ __forceinline__ unsigned cvt_pk_bf16(float lo, float hi) { const f32x2 v = {lo, hi}; const bf16v2_ r = __builtin_convertvector(v, bf16v2_); return __builtin_bit_cast(unsigned, r); }
; __device__ __forceinline__ float bflo(unsigned w) { return __uint_as_float(w << 16); }
; __device__ __forceinline__ float bfhi(unsigned w) { return __uint_as_float(w & 0xffff0000u); }
;     __device__ __forceinline__ void operator()(const f32x4 (&acc)[2][2][4][2], const Unit& u, int wr, int wc, int, int) const {
;     ...
; #pragma unroll
;         for (int ai = 0; ai < 2; ++ai)
; #pragma unroll
;             for (int m = 0; m < 4; ++m)
; #pragma unroll
;                 for (int bj = 0; bj < 2; ++bj) { const u32x4 c = cin[ai][m][bj]; const f32x4 v0 = acc[ai][bj][m][0], v1 = acc[ai][bj][m][1];
;                     u32x4 w; w.x = cvt_pk_bf16(bflo(c.x) + v0[0], bfhi(c.x) + v0[1]); w.y = cvt_pk_bf16(bflo(c.y) + v0[2], bfhi(c.y) + v0[3]);
;                     w.z = cvt_pk_bf16(bflo(c.z) + v1[0], bfhi(c.z) + v1[1]); w.w = cvt_pk_bf16(bflo(c.w) + v1[2], bfhi(c.w) + v1[3]);
;                     *(u32x4*)(C + (size_t)(row0 + ai * HALF + m * 16) * ldc + col0 + bj * HALF) = w; }
	v_lshlrev_b32_e32 v218, 16, v226
	v_and_b32_e32 v219, 0xffff0000, v226
	v_pk_add_f32 v[128:129], v[128:129], v[218:219]
	v_lshlrev_b32_e32 v218, 16, v227
	v_and_b32_e32 v219, 0xffff0000, v227
	v_pk_add_f32 v[130:131], v[130:131], v[218:219]
	v_cvt_pk_bf16_f32 v128, v128, v129
	v_cvt_pk_bf16_f32 v129, v130, v131
	v_lshlrev_b32_e32 v130, 16, v228
	v_and_b32_e32 v131, 0xffff0000, v228
	v_pk_add_f32 v[124:125], v[124:125], v[130:131]
	s_nop 0
	v_cvt_pk_bf16_f32 v130, v124, v125
	v_lshlrev_b32_e32 v124, 16, v229
	v_and_b32_e32 v125, 0xffff0000, v229
	v_pk_add_f32 v[124:125], v[126:127], v[124:125]
	v_lshlrev_b32_e32 v126, 16, v188
	v_and_b32_e32 v127, 0xffff0000, v188
	v_pk_add_f32 v[120:121], v[120:121], v[126:127]
	v_lshlrev_b32_e32 v126, 16, v189
	v_and_b32_e32 v127, 0xffff0000, v189
	v_pk_add_f32 v[122:123], v[122:123], v[126:127]
	v_cvt_pk_bf16_f32 v120, v120, v121
	v_cvt_pk_bf16_f32 v121, v122, v123
	v_lshlrev_b32_e32 v122, 16, v190
	v_and_b32_e32 v123, 0xffff0000, v190
	v_pk_add_f32 v[116:117], v[116:117], v[122:123]
	v_cvt_pk_bf16_f32 v131, v124, v125
	v_cvt_pk_bf16_f32 v122, v116, v117
	v_lshlrev_b32_e32 v116, 16, v191
	v_and_b32_e32 v117, 0xffff0000, v191
	v_pk_add_f32 v[116:117], v[118:119], v[116:117]
	v_lshl_add_u64 v[124:125], s[88:89], 0, v[216:217]
	v_cvt_pk_bf16_f32 v123, v116, v117
	v_lshlrev_b32_e32 v116, 16, v184
	v_and_b32_e32 v117, 0xffff0000, v184
	v_pk_add_f32 v[112:113], v[112:113], v[116:117]
	v_lshlrev_b32_e32 v116, 16, v185
	v_and_b32_e32 v117, 0xffff0000, v185
	v_pk_add_f32 v[114:115], v[114:115], v[116:117]
	v_cvt_pk_bf16_f32 v112, v112, v113
	v_cvt_pk_bf16_f32 v113, v114, v115
	v_lshlrev_b32_e32 v114, 16, v186
	v_and_b32_e32 v115, 0xffff0000, v186
	v_pk_add_f32 v[108:109], v[108:109], v[114:115]
	v_lshl_add_u64 v[124:125], v[124:125], 0, v[202:203]
	v_cvt_pk_bf16_f32 v114, v108, v109
	v_lshlrev_b32_e32 v108, 16, v187
	v_and_b32_e32 v109, 0xffff0000, v187
	v_pk_add_f32 v[108:109], v[110:111], v[108:109]
	v_lshlrev_b32_e32 v110, 16, v180
	v_and_b32_e32 v111, 0xffff0000, v180
	v_pk_add_f32 v[104:105], v[104:105], v[110:111]
	v_lshlrev_b32_e32 v110, 16, v181
	v_and_b32_e32 v111, 0xffff0000, v181
	v_pk_add_f32 v[106:107], v[106:107], v[110:111]
	v_cvt_pk_bf16_f32 v104, v104, v105
	v_cvt_pk_bf16_f32 v105, v106, v107
	v_lshlrev_b32_e32 v106, 16, v182
	v_and_b32_e32 v107, 0xffff0000, v182
	v_pk_add_f32 v[96:97], v[96:97], v[106:107]
	v_cvt_pk_bf16_f32 v115, v108, v109
	v_cvt_pk_bf16_f32 v106, v96, v97
	v_lshlrev_b32_e32 v96, 16, v183
	v_and_b32_e32 v97, 0xffff0000, v183
	v_pk_add_f32 v[96:97], v[98:99], v[96:97]
	v_lshlrev_b32_e32 v98, 16, v177
	v_cvt_pk_bf16_f32 v107, v96, v97
	v_lshlrev_b32_e32 v96, 16, v176
	v_and_b32_e32 v97, 0xffff0000, v176
	v_and_b32_e32 v99, 0xffff0000, v177
	v_pk_add_f32 v[96:97], v[100:101], v[96:97]
	v_pk_add_f32 v[98:99], v[102:103], v[98:99]
	v_cvt_pk_bf16_f32 v96, v96, v97
	v_cvt_pk_bf16_f32 v97, v98, v99
	v_lshlrev_b32_e32 v98, 16, v178
	v_and_b32_e32 v99, 0xffff0000, v178
	v_pk_add_f32 v[92:93], v[92:93], v[98:99]
	v_lshl_add_u64 v[108:109], s[88:89], 0, v[222:223]
	v_cvt_pk_bf16_f32 v98, v92, v93
	v_lshlrev_b32_e32 v92, 16, v179
	v_and_b32_e32 v93, 0xffff0000, v179
	v_pk_add_f32 v[92:93], v[94:95], v[92:93]
	v_lshlrev_b32_e32 v94, 16, v168
	v_and_b32_e32 v95, 0xffff0000, v168
	v_pk_add_f32 v[88:89], v[88:89], v[94:95]
	v_lshlrev_b32_e32 v94, 16, v169
	v_and_b32_e32 v95, 0xffff0000, v169
	v_pk_add_f32 v[90:91], v[90:91], v[94:95]
	v_cvt_pk_bf16_f32 v88, v88, v89
	v_cvt_pk_bf16_f32 v89, v90, v91
	v_lshlrev_b32_e32 v90, 16, v170
	v_and_b32_e32 v91, 0xffff0000, v170
	v_pk_add_f32 v[80:81], v[80:81], v[90:91]
	v_cvt_pk_bf16_f32 v99, v92, v93
	v_cvt_pk_bf16_f32 v90, v80, v81
	v_lshlrev_b32_e32 v80, 16, v171
	v_and_b32_e32 v81, 0xffff0000, v171
	v_pk_add_f32 v[80:81], v[82:83], v[80:81]
	v_lshlrev_b32_e32 v82, 16, v173
	v_cvt_pk_bf16_f32 v91, v80, v81
	v_lshlrev_b32_e32 v80, 16, v172
	v_and_b32_e32 v81, 0xffff0000, v172
	v_and_b32_e32 v83, 0xffff0000, v173
	v_pk_add_f32 v[80:81], v[84:85], v[80:81]
	v_pk_add_f32 v[82:83], v[86:87], v[82:83]
	v_cvt_pk_bf16_f32 v80, v80, v81
	v_cvt_pk_bf16_f32 v81, v82, v83
	v_lshlrev_b32_e32 v82, 16, v174
	v_and_b32_e32 v83, 0xffff0000, v174
	v_pk_add_f32 v[76:77], v[76:77], v[82:83]
	v_lshl_add_u64 v[92:93], s[88:89], 0, v[220:221]
	v_cvt_pk_bf16_f32 v82, v76, v77
	v_lshlrev_b32_e32 v76, 16, v175
	v_and_b32_e32 v77, 0xffff0000, v175
	v_pk_add_f32 v[76:77], v[78:79], v[76:77]
	v_lshlrev_b32_e32 v78, 16, v164
	v_and_b32_e32 v79, 0xffff0000, v164
	v_pk_add_f32 v[72:73], v[72:73], v[78:79]
	v_lshlrev_b32_e32 v78, 16, v165
	v_and_b32_e32 v79, 0xffff0000, v165
	v_pk_add_f32 v[74:75], v[74:75], v[78:79]
	v_cvt_pk_bf16_f32 v72, v72, v73
	v_cvt_pk_bf16_f32 v73, v74, v75
	v_lshlrev_b32_e32 v74, 16, v166
	v_and_b32_e32 v75, 0xffff0000, v166
	v_pk_add_f32 v[68:69], v[68:69], v[74:75]
	v_cvt_pk_bf16_f32 v83, v76, v77
	v_cvt_pk_bf16_f32 v74, v68, v69
	v_lshlrev_b32_e32 v68, 16, v167
	v_and_b32_e32 v69, 0xffff0000, v167
	v_pk_add_f32 v[68:69], v[70:71], v[68:69]
	v_lshl_add_u64 v[76:77], s[88:89], 0, v[212:213]
	v_cvt_pk_bf16_f32 v75, v68, v69
	v_lshlrev_b32_e32 v68, 16, v160
	v_and_b32_e32 v69, 0xffff0000, v160
	v_pk_add_f32 v[64:65], v[64:65], v[68:69]
	v_lshlrev_b32_e32 v68, 16, v161
	v_and_b32_e32 v69, 0xffff0000, v161
	v_pk_add_f32 v[66:67], v[66:67], v[68:69]
	v_cvt_pk_bf16_f32 v64, v64, v65
	v_cvt_pk_bf16_f32 v65, v66, v67
	v_lshlrev_b32_e32 v66, 16, v162
	v_and_b32_e32 v67, 0xffff0000, v162
	v_pk_add_f32 v[60:61], v[60:61], v[66:67]
	v_lshl_add_u64 v[108:109], v[108:109], 0, v[202:203]
	v_cvt_pk_bf16_f32 v66, v60, v61
	v_lshlrev_b32_e32 v60, 16, v163
; __device__ __forceinline__ unsigned cvt_pk_bf16(float lo, float hi) { const f32x2 v = {lo, hi}; const bf16v2_ r = __builtin_convertvector(v, bf16v2_); return __builtin_bit_cast(unsigned, r); }
; __device__ __forceinline__ float bflo(unsigned w) { return __uint_as_float(w << 16); }
; __device__ __forceinline__ float bfhi(unsigned w) { return __uint_as_float(w & 0xffff0000u); }
; #define PG8_WAIT_V(n) asm volatile("s_waitcnt vmcnt(" #n ")" ::: "memory")
; #define PG8_BAR __builtin_amdgcn_s_barrier()
;     __device__ __forceinline__ void operator()(const f32x4 (&acc)[2][2][4][2], const Unit& u, int wr, int wc, int, int) const {
;     ...
; #pragma unroll
;         for (int ai = 0; ai < 2; ++ai)
; #pragma unroll
;             for (int m = 0; m < 4; ++m)
; #pragma unroll
;                 for (int bj = 0; bj < 2; ++bj) { const u32x4 c = cin[ai][m][bj]; const f32x4 v0 = acc[ai][bj][m][0], v1 = acc[ai][bj][m][1];
;                     u32x4 w; w.x = cvt_pk_bf16(bflo(c.x) + v0[0], bfhi(c.x) + v0[1]); w.y = cvt_pk_bf16(bflo(c.y) + v0[2], bfhi(c.y) + v0[3]);
;                     w.z = cvt_pk_bf16(bflo(c.z) + v1[0], bfhi(c.z) + v1[1]); w.w = cvt_pk_bf16(bflo(c.w) + v1[2], bfhi(c.w) + v1[3]);
;                     *(u32x4*)(C + (size_t)(row0 + ai * HALF + m * 16) * ldc + col0 + bj * HALF) = w; }
; template <class Epi, class Sched>
; __device__ __forceinline__ void gemm_phase(LAS unsigned char* lds, const Gemm g, const Sched& S, const Epi& E) {
;     ...
;         if (!has_next) break;
; #pragma unroll
;         for (int a = 0; a < 2; ++a)
; #pragma unroll
;             for (int b = 0; b < 2; ++b)
; #pragma unroll
;                 for (int m = 0; m < 4; ++m)
; #pragma unroll
;                     for (int n = 0; n < 2; ++n) acc[a][b][m][n] = (f32x4){0.f, 0.f, 0.f, 0.f};
;         cur = nxt; cA = nA; cB = nB; ++ui;
;     }
;     PG8_WAIT_V(0);
;     if (wr == 0) PG8_BAR;
;     PG8_BAR;
	v_and_b32_e32 v61, 0xffff0000, v163
	v_pk_add_f32 v[60:61], v[62:63], v[60:61]
	v_lshlrev_b32_e32 v62, 16, v156
	v_and_b32_e32 v63, 0xffff0000, v156
	v_pk_add_f32 v[56:57], v[56:57], v[62:63]
	v_lshlrev_b32_e32 v62, 16, v157
	v_and_b32_e32 v63, 0xffff0000, v157
	v_pk_add_f32 v[58:59], v[58:59], v[62:63]
	v_cvt_pk_bf16_f32 v56, v56, v57
	v_cvt_pk_bf16_f32 v57, v58, v59
	v_lshlrev_b32_e32 v58, 16, v158
	v_and_b32_e32 v59, 0xffff0000, v158
	v_pk_add_f32 v[48:49], v[48:49], v[58:59]
	v_cvt_pk_bf16_f32 v67, v60, v61
	v_cvt_pk_bf16_f32 v58, v48, v49
	v_lshlrev_b32_e32 v48, 16, v159
	v_and_b32_e32 v49, 0xffff0000, v159
	v_pk_add_f32 v[48:49], v[50:51], v[48:49]
	v_lshlrev_b32_e32 v50, 16, v153
	v_cvt_pk_bf16_f32 v59, v48, v49
	v_lshlrev_b32_e32 v48, 16, v152
	v_and_b32_e32 v49, 0xffff0000, v152
	v_and_b32_e32 v51, 0xffff0000, v153
	v_pk_add_f32 v[48:49], v[52:53], v[48:49]
	v_pk_add_f32 v[50:51], v[54:55], v[50:51]
	v_cvt_pk_bf16_f32 v48, v48, v49
	v_cvt_pk_bf16_f32 v49, v50, v51
	v_lshlrev_b32_e32 v50, 16, v154
	v_and_b32_e32 v51, 0xffff0000, v154
	v_pk_add_f32 v[44:45], v[44:45], v[50:51]
	v_lshl_add_u64 v[60:61], s[88:89], 0, v[210:211]
	v_cvt_pk_bf16_f32 v50, v44, v45
	v_lshlrev_b32_e32 v44, 16, v155
	v_and_b32_e32 v45, 0xffff0000, v155
	v_pk_add_f32 v[44:45], v[46:47], v[44:45]
	v_lshlrev_b32_e32 v46, 16, v148
	v_and_b32_e32 v47, 0xffff0000, v148
	v_pk_add_f32 v[40:41], v[40:41], v[46:47]
	v_lshlrev_b32_e32 v46, 16, v149
	v_and_b32_e32 v47, 0xffff0000, v149
	v_pk_add_f32 v[42:43], v[42:43], v[46:47]
	v_cvt_pk_bf16_f32 v40, v40, v41
	v_cvt_pk_bf16_f32 v41, v42, v43
	v_lshlrev_b32_e32 v42, 16, v150
	v_and_b32_e32 v43, 0xffff0000, v150
	v_pk_add_f32 v[32:33], v[32:33], v[42:43]
	v_cvt_pk_bf16_f32 v51, v44, v45
	v_cvt_pk_bf16_f32 v42, v32, v33
	v_lshlrev_b32_e32 v32, 16, v151
	v_and_b32_e32 v33, 0xffff0000, v151
	v_pk_add_f32 v[32:33], v[34:35], v[32:33]
	v_lshlrev_b32_e32 v34, 16, v145
	v_cvt_pk_bf16_f32 v43, v32, v33
	v_lshlrev_b32_e32 v32, 16, v144
	v_and_b32_e32 v33, 0xffff0000, v144
	v_and_b32_e32 v35, 0xffff0000, v145
	v_pk_add_f32 v[32:33], v[36:37], v[32:33]
	v_pk_add_f32 v[34:35], v[38:39], v[34:35]
	v_cvt_pk_bf16_f32 v32, v32, v33
	v_cvt_pk_bf16_f32 v33, v34, v35
	v_lshlrev_b32_e32 v34, 16, v146
	v_and_b32_e32 v35, 0xffff0000, v146
	v_pk_add_f32 v[28:29], v[28:29], v[34:35]
	v_lshl_add_u64 v[44:45], s[88:89], 0, v[208:209]
	v_cvt_pk_bf16_f32 v34, v28, v29
	v_lshlrev_b32_e32 v28, 16, v147
	v_and_b32_e32 v29, 0xffff0000, v147
	v_pk_add_f32 v[28:29], v[30:31], v[28:29]
	v_lshlrev_b32_e32 v30, 16, v140
	v_and_b32_e32 v31, 0xffff0000, v140
	v_pk_add_f32 v[24:25], v[24:25], v[30:31]
	v_lshlrev_b32_e32 v30, 16, v141
	v_and_b32_e32 v31, 0xffff0000, v141
	v_pk_add_f32 v[26:27], v[26:27], v[30:31]
	v_cvt_pk_bf16_f32 v24, v24, v25
	v_cvt_pk_bf16_f32 v25, v26, v27
	v_lshlrev_b32_e32 v26, 16, v142
	v_and_b32_e32 v27, 0xffff0000, v142
	v_pk_add_f32 v[16:17], v[16:17], v[26:27]
	v_cvt_pk_bf16_f32 v35, v28, v29
	v_cvt_pk_bf16_f32 v26, v16, v17
	v_lshlrev_b32_e32 v16, 16, v143
	v_and_b32_e32 v17, 0xffff0000, v143
	v_pk_add_f32 v[16:17], v[18:19], v[16:17]
	v_lshlrev_b32_e32 v18, 16, v137
	v_cvt_pk_bf16_f32 v27, v16, v17
	v_lshlrev_b32_e32 v16, 16, v136
	v_and_b32_e32 v17, 0xffff0000, v136
	v_and_b32_e32 v19, 0xffff0000, v137
	v_pk_add_f32 v[16:17], v[20:21], v[16:17]
	v_pk_add_f32 v[18:19], v[22:23], v[18:19]
	v_cvt_pk_bf16_f32 v16, v16, v17
	v_cvt_pk_bf16_f32 v17, v18, v19
	v_lshlrev_b32_e32 v18, 16, v138
	v_and_b32_e32 v19, 0xffff0000, v138
	v_pk_add_f32 v[12:13], v[12:13], v[18:19]
	v_lshl_add_u64 v[28:29], s[88:89], 0, v[206:207]
	v_cvt_pk_bf16_f32 v18, v12, v13
	v_lshlrev_b32_e32 v12, 16, v139
	v_and_b32_e32 v13, 0xffff0000, v139
	v_pk_add_f32 v[12:13], v[14:15], v[12:13]
	v_lshlrev_b32_e32 v14, 16, v132
	v_and_b32_e32 v15, 0xffff0000, v132
	v_pk_add_f32 v[8:9], v[8:9], v[14:15]
	v_lshlrev_b32_e32 v14, 16, v133
	v_and_b32_e32 v15, 0xffff0000, v133
	v_pk_add_f32 v[10:11], v[10:11], v[14:15]
	v_cvt_pk_bf16_f32 v8, v8, v9
	v_cvt_pk_bf16_f32 v9, v10, v11
	v_lshlrev_b32_e32 v10, 16, v134
	v_and_b32_e32 v11, 0xffff0000, v134
	v_pk_add_f32 v[4:5], v[4:5], v[10:11]
	v_cvt_pk_bf16_f32 v19, v12, v13
	v_cvt_pk_bf16_f32 v10, v4, v5
	v_lshlrev_b32_e32 v4, 16, v135
	v_and_b32_e32 v5, 0xffff0000, v135
	v_lshl_add_u64 v[12:13], s[88:89], 0, v[204:205]
	v_pk_add_f32 v[4:5], v[6:7], v[4:5]
	v_lshl_add_u64 v[92:93], v[92:93], 0, v[202:203]
	v_lshl_add_u64 v[76:77], v[76:77], 0, v[202:203]
	v_lshl_add_u64 v[60:61], v[60:61], 0, v[202:203]
	v_lshl_add_u64 v[44:45], v[44:45], 0, v[202:203]
	v_lshl_add_u64 v[28:29], v[28:29], 0, v[202:203]
	v_lshl_add_u64 v[12:13], v[12:13], 0, v[202:203]
	v_cvt_pk_bf16_f32 v11, v4, v5
	global_store_dwordx4 v[124:125], v[128:131], off
	global_store_dwordx4 v[124:125], v[120:123], off offset:256
	global_store_dwordx4 v[108:109], v[112:115], off
	global_store_dwordx4 v[108:109], v[104:107], off offset:256
	global_store_dwordx4 v[92:93], v[96:99], off
	global_store_dwordx4 v[92:93], v[88:91], off offset:256
	global_store_dwordx4 v[76:77], v[80:83], off
	global_store_dwordx4 v[76:77], v[72:75], off offset:256
	global_store_dwordx4 v[60:61], v[64:67], off
	global_store_dwordx4 v[60:61], v[56:59], off offset:256
	global_store_dwordx4 v[44:45], v[48:51], off
	global_store_dwordx4 v[44:45], v[40:43], off offset:256
	global_store_dwordx4 v[28:29], v[32:35], off
	global_store_dwordx4 v[28:29], v[24:27], off offset:256
	global_store_dwordx4 v[12:13], v[16:19], off
	global_store_dwordx4 v[12:13], v[8:11], off offset:256
	s_cbranch_vccz .LBB0_1389
	s_waitcnt vmcnt(0)
	s_cmpk_gt_u32 s2, 0xff
	s_cbranch_scc1 .LBB0_1400
	s_barrier

; #define PG8_STAGE(bufoff, gbase, voff) do { _Pragma("unroll") for (int _i = 0; _i < 2; ++_i) \
;         __builtin_amdgcn_global_load_lds((const unsigned*)((const char*)(gbase) + (voff)[_i]), (LAS unsigned*)(lds + (bufoff) + ldsw + _i * 8192), 16, 0, 0); } while (0)
; #define PG8_LDA(dst, b, h) do { _Pragma("unroll") for (int m = 0; m < 4; ++m) _Pragma("unroll") for (int k = 0; k < 2; ++k) dst[m][k] = *(const LAS bf16x8*)(lds + PG8_SA(b, h) + aoff + m * 2048 + k * 1024); } while (0)
; #define PG8_LDB(dst, b, h) do { _Pragma("unroll") for (int n = 0; n < 2; ++n) _Pragma("unroll") for (int k = 0; k < 2; ++k) dst[n][k] = *(const LAS bf16x8*)(lds + PG8_SB(b, h) + boff + n * 2048 + k * 1024); } while (0)
; #define PG8_MMA(ai, bj, At, Bt) do { __builtin_amdgcn_s_setprio(1); _Pragma("unroll") for (int m = 0; m < 4; ++m) _Pragma("unroll") for (int n = 0; n < 2; ++n) _Pragma("unroll") for (int k = 0; k < 2; ++k) \
;         acc[ai][bj][m][n] = __builtin_amdgcn_mfma_f32_16x16x32_bf16(Bt[n][k], At[m][k], acc[ai][bj][m][n], 0, 0, 0); __builtin_amdgcn_s_setprio(0); } while (0)
; #define PG8_WAIT_V(n) asm volatile("s_waitcnt vmcnt(" #n ")" ::: "memory")
; #define PG8_WAIT_L(n) asm volatile("s_waitcnt lgkmcnt(" #n ")" ::: "memory")
; #define PG8_BAR __builtin_amdgcn_s_barrier()
; #define PG8_SCHED __builtin_amdgcn_sched_barrier(0)
; template <class Epi, class Sched>
; __device__ __forceinline__ void gemm_phase(LAS unsigned char* lds, const Gemm g, const Sched& S, const Epi& E) {
;     ...
;             PG8_LDB(B0, 0, 0); PG8_SCHED; PG8_LDA(At, 0, 0); PG8_STAGE(PG8_SA(1, 1), a1 + hstepA, voffA);
;             PG8_WAIT_L(8); PG8_BAR; PG8_WAIT_L(0); PG8_MMA(0, 0, At, B0); PG8_BAR; PG8_SCHED;
;             PG8_LDB(B1, 0, 1); PG8_STAGE(PG8_SB(0, 0), b2, voffB);
;             PG8_BAR; PG8_WAIT_L(0); PG8_MMA(0, 1, At, B1); PG8_BAR;
;             PG8_LDA(At, 0, 1); PG8_STAGE(PG8_SA(0, 0), a2, voffA);
;             PG8_BAR; PG8_WAIT_L(0); PG8_MMA(1, 0, At, B0); PG8_BAR; PG8_SCHED;
;             PG8_STAGE(PG8_SB(0, 1), b2 + hstepB, voffB);
;             PG8_WAIT_V(6); PG8_BAR; PG8_MMA(1, 1, At, B1); PG8_BAR;
.LBB0_1526:
	s_setprio 0
	s_add_u32 s6, s4, 0xfff80080
	s_addc_u32 s7, s5, -1
	s_add_i32 s72, 0, 0x10000
	v_add_u32_e32 v2, s72, v1
	ds_read_b128 v[132:135], v2
	ds_read_b128 v[136:139], v2 offset:1024
	ds_read_b128 v[140:143], v2 offset:2048
	ds_read_b128 v[144:147], v2 offset:3072
	s_cmp_eq_u32 s71, 28
	s_cselect_b32 s15, s57, s7
	s_cselect_b32 s14, s67, s6
	s_cselect_b32 s7, s55, s70
	s_cselect_b32 s6, s68, s69
	ds_read_b128 v[148:151], v207
	ds_read_b128 v[152:155], v207 offset:1024
	ds_read_b128 v[156:159], v207 offset:2048
	ds_read_b128 v[160:163], v207 offset:3072
	ds_read_b128 v[164:167], v207 offset:4096
	ds_read_b128 v[168:171], v207 offset:5120
	ds_read_b128 v[186:189], v207 offset:6144
	ds_read_b128 v[190:193], v207 offset:7168
	s_add_i32 s74, 0, 0x14000
	v_add_u32_e32 v2, s74, v1
	ds_read_b128 v[194:197], v2
	ds_read_b128 v[198:201], v2 offset:1024
	ds_read_b128 v[202:205], v2 offset:2048
	ds_read_b128 v[208:211], v2 offset:3072
	s_add_i32 m0, s20, 0xc000
	s_nop 0
	global_load_lds_dwordx4 v182, s[4:5]
	s_add_i32 m0, s20, 0xe000
	s_nop 0
	global_load_lds_dwordx4 v184, s[4:5]
	s_waitcnt lgkmcnt(0)
	s_setprio 1
	s_barrier
	v_mfma_f32_16x16x32_bf16 v[68:71], v[132:135], v[148:151], v[68:71]
	v_mfma_f32_16x16x32_bf16 v[72:75], v[140:143], v[148:151], v[72:75]
	v_mfma_f32_16x16x32_bf16 v[120:123], v[132:135], v[156:159], v[120:123]
	v_mfma_f32_16x16x32_bf16 v[116:119], v[140:143], v[156:159], v[116:119]
	v_mfma_f32_16x16x32_bf16 v[112:115], v[132:135], v[164:167], v[112:115]
	v_mfma_f32_16x16x32_bf16 v[108:111], v[140:143], v[164:167], v[108:111]
	v_mfma_f32_16x16x32_bf16 v[104:107], v[132:135], v[186:189], v[104:107]
	v_mfma_f32_16x16x32_bf16 v[100:103], v[140:143], v[186:189], v[100:103]
	v_mfma_f32_16x16x32_bf16 v[68:71], v[136:139], v[152:155], v[68:71]
	v_mfma_f32_16x16x32_bf16 v[72:75], v[144:147], v[152:155], v[72:75]
	v_mfma_f32_16x16x32_bf16 v[120:123], v[136:139], v[160:163], v[120:123]
	v_mfma_f32_16x16x32_bf16 v[116:119], v[144:147], v[160:163], v[116:119]
	v_mfma_f32_16x16x32_bf16 v[112:115], v[136:139], v[168:171], v[112:115]
	v_mfma_f32_16x16x32_bf16 v[108:111], v[144:147], v[168:171], v[108:111]
	v_mfma_f32_16x16x32_bf16 v[104:107], v[136:139], v[190:193], v[104:107]
	v_mfma_f32_16x16x32_bf16 v[100:103], v[144:147], v[190:193], v[100:103]
	v_mfma_f32_16x16x32_bf16 v[76:79], v[194:197], v[148:151], v[76:79]
	v_mfma_f32_16x16x32_bf16 v[80:83], v[202:205], v[148:151], v[80:83]
	v_mfma_f32_16x16x32_bf16 v[96:99], v[194:197], v[156:159], v[96:99]
	v_mfma_f32_16x16x32_bf16 v[92:95], v[202:205], v[156:159], v[92:95]
	v_mfma_f32_16x16x32_bf16 v[88:91], v[194:197], v[164:167], v[88:91]
	v_mfma_f32_16x16x32_bf16 v[84:87], v[202:205], v[164:167], v[84:87]
	v_mfma_f32_16x16x32_bf16 v[128:131], v[194:197], v[186:189], v[128:131]
	v_mfma_f32_16x16x32_bf16 v[124:127], v[202:205], v[186:189], v[124:127]
	v_mfma_f32_16x16x32_bf16 v[76:79], v[198:201], v[152:155], v[76:79]
	v_mfma_f32_16x16x32_bf16 v[80:83], v[208:211], v[152:155], v[80:83]
	v_mfma_f32_16x16x32_bf16 v[96:99], v[198:201], v[160:163], v[96:99]
	v_mfma_f32_16x16x32_bf16 v[92:95], v[208:211], v[160:163], v[92:95]
	v_mfma_f32_16x16x32_bf16 v[88:91], v[198:201], v[168:171], v[88:91]
	v_mfma_f32_16x16x32_bf16 v[84:87], v[208:211], v[168:171], v[84:87]
	v_mfma_f32_16x16x32_bf16 v[128:131], v[198:201], v[190:193], v[128:131]
	v_mfma_f32_16x16x32_bf16 v[124:127], v[208:211], v[190:193], v[124:127]
	s_barrier
	s_setprio 0
	ds_read_b128 v[148:151], v207 offset:16384
	ds_read_b128 v[152:155], v207 offset:17408
	ds_read_b128 v[156:159], v207 offset:18432
	ds_read_b128 v[160:163], v207 offset:19456
	ds_read_b128 v[164:167], v207 offset:20480
	ds_read_b128 v[168:171], v207 offset:21504
	ds_read_b128 v[186:189], v207 offset:22528
	ds_read_b128 v[190:193], v207 offset:23552
	s_add_i32 s72, s72, s19
	v_lshl_add_u64 v[172:173], s[6:7], 0, v[178:179]
	s_mov_b32 m0, s72
	s_nop 0
	global_load_lds_dwordx4 v[172:173], off
	v_lshl_add_u64 v[212:213], s[6:7], 0, v[174:175]
	s_add_i32 m0, s72, 0x2000
	s_nop 0
	global_load_lds_dwordx4 v[212:213], off
	s_mov_b32 m0, s20
	v_lshl_add_u64 v[216:217], s[14:15], 0, v[180:181]
	global_load_lds_dwordx4 v[216:217], off
	v_lshl_add_u64 v[218:219], s[14:15], 0, v[176:177]
	s_mov_b32 m0, s21
	s_nop 0
	global_load_lds_dwordx4 v[218:219], off
	s_add_u32 s72, s6, 0x80000
	s_addc_u32 s73, s7, 0
	s_add_i32 s74, s74, s19
	s_mov_b32 m0, s74
	s_nop 0
	global_load_lds_dwordx4 v178, s[72:73]
	s_add_i32 m0, s74, 0x2000
	s_nop 0
	global_load_lds_dwordx4 v174, s[72:73]
	s_waitcnt lgkmcnt(0)
	s_waitcnt vmcnt(6)
	s_setprio 1
	s_barrier
; #define PG8_STAGE(bufoff, gbase, voff) do { _Pragma("unroll") for (int _i = 0; _i < 2; ++_i) \
;         __builtin_amdgcn_global_load_lds((const unsigned*)((const char*)(gbase) + (voff)[_i]), (LAS unsigned*)(lds + (bufoff) + ldsw + _i * 8192), 16, 0, 0); } while (0)
; #define PG8_LDA(dst, b, h) do { _Pragma("unroll") for (int m = 0; m < 4; ++m) _Pragma("unroll") for (int k = 0; k < 2; ++k) dst[m][k] = *(const LAS bf16x8*)(lds + PG8_SA(b, h) + aoff + m * 2048 + k * 1024); } while (0)
; #define PG8_LDB(dst, b, h) do { _Pragma("unroll") for (int n = 0; n < 2; ++n) _Pragma("unroll") for (int k = 0; k < 2; ++k) dst[n][k] = *(const LAS bf16x8*)(lds + PG8_SB(b, h) + boff + n * 2048 + k * 1024); } while (0)
; #define PG8_MMA(ai, bj, At, Bt) do { __builtin_amdgcn_s_setprio(1); _Pragma("unroll") for (int m = 0; m < 4; ++m) _Pragma("unroll") for (int n = 0; n < 2; ++n) _Pragma("unroll") for (int k = 0; k < 2; ++k) \
;         acc[ai][bj][m][n] = __builtin_amdgcn_mfma_f32_16x16x32_bf16(Bt[n][k], At[m][k], acc[ai][bj][m][n], 0, 0, 0); __builtin_amdgcn_s_setprio(0); } while (0)
; #define PG8_WAIT_V(n) asm volatile("s_waitcnt vmcnt(" #n ")" ::: "memory")
; #define PG8_WAIT_L(n) asm volatile("s_waitcnt lgkmcnt(" #n ")" ::: "memory")
; #define PG8_BAR __builtin_amdgcn_s_barrier()
; #define PG8_SCHED __builtin_amdgcn_sched_barrier(0)
; template <class Epi, class Sched>
; __device__ __forceinline__ void gemm_phase(LAS unsigned char* lds, const Gemm g, const Sched& S, const Epi& E) {
;     ...
;             PG8_WAIT_V(6); PG8_BAR; PG8_MMA(1, 1, At, B1); PG8_BAR;
;             PG8_LDB(B0, 1, 0); PG8_SCHED; PG8_LDA(At, 1, 0); PG8_STAGE(PG8_SA(0, 1), a2 + hstepA, voffA);
;             PG8_WAIT_L(8); PG8_BAR; PG8_WAIT_L(0); PG8_MMA(0, 0, At, B0); PG8_BAR; PG8_SCHED;
;             PG8_LDB(B1, 1, 1); PG8_STAGE(PG8_SB(1, 0), b3, voffB);
;             PG8_BAR; PG8_WAIT_L(0); PG8_MMA(0, 1, At, B1); PG8_BAR;
;             PG8_LDA(At, 1, 1); PG8_STAGE(PG8_SA(1, 0), a3, voffA);
;             PG8_BAR; PG8_WAIT_L(0); PG8_MMA(1, 0, At, B0); PG8_BAR; PG8_SCHED;
	v_mfma_f32_16x16x32_bf16 v[56:59], v[132:135], v[148:151], v[56:59]
	v_mfma_f32_16x16x32_bf16 v[52:55], v[140:143], v[148:151], v[52:55]
	v_mfma_f32_16x16x32_bf16 v[48:51], v[132:135], v[156:159], v[48:51]
	v_mfma_f32_16x16x32_bf16 v[44:47], v[140:143], v[156:159], v[44:47]
	v_mfma_f32_16x16x32_bf16 v[40:43], v[132:135], v[164:167], v[40:43]
	v_mfma_f32_16x16x32_bf16 v[36:39], v[140:143], v[164:167], v[36:39]
	v_mfma_f32_16x16x32_bf16 v[32:35], v[132:135], v[186:189], v[32:35]
	v_mfma_f32_16x16x32_bf16 v[28:31], v[140:143], v[186:189], v[28:31]
	v_mfma_f32_16x16x32_bf16 v[56:59], v[136:139], v[152:155], v[56:59]
	v_mfma_f32_16x16x32_bf16 v[52:55], v[144:147], v[152:155], v[52:55]
	v_mfma_f32_16x16x32_bf16 v[48:51], v[136:139], v[160:163], v[48:51]
	v_mfma_f32_16x16x32_bf16 v[44:47], v[144:147], v[160:163], v[44:47]
	v_mfma_f32_16x16x32_bf16 v[40:43], v[136:139], v[168:171], v[40:43]
	v_mfma_f32_16x16x32_bf16 v[36:39], v[144:147], v[168:171], v[36:39]
	v_mfma_f32_16x16x32_bf16 v[32:35], v[136:139], v[190:193], v[32:35]
	v_mfma_f32_16x16x32_bf16 v[28:31], v[144:147], v[190:193], v[28:31]
	v_mfma_f32_16x16x32_bf16 v[24:27], v[194:197], v[148:151], v[24:27]
	v_mfma_f32_16x16x32_bf16 v[20:23], v[202:205], v[148:151], v[20:23]
	v_mfma_f32_16x16x32_bf16 v[16:19], v[194:197], v[156:159], v[16:19]
	v_mfma_f32_16x16x32_bf16 v[12:15], v[202:205], v[156:159], v[12:15]
	v_mfma_f32_16x16x32_bf16 v[8:11], v[194:197], v[164:167], v[8:11]
	v_mfma_f32_16x16x32_bf16 v[4:7], v[202:205], v[164:167], v[4:7]
	v_mfma_f32_16x16x32_bf16 v[60:63], v[194:197], v[186:189], v[60:63]
	v_mfma_f32_16x16x32_bf16 v[64:67], v[202:205], v[186:189], v[64:67]
	v_mfma_f32_16x16x32_bf16 v[24:27], v[198:201], v[152:155], v[24:27]
	v_mfma_f32_16x16x32_bf16 v[20:23], v[208:211], v[152:155], v[20:23]
	v_mfma_f32_16x16x32_bf16 v[16:19], v[198:201], v[160:163], v[16:19]
	v_mfma_f32_16x16x32_bf16 v[12:15], v[208:211], v[160:163], v[12:15]
	v_mfma_f32_16x16x32_bf16 v[8:11], v[198:201], v[168:171], v[8:11]
	v_mfma_f32_16x16x32_bf16 v[4:7], v[208:211], v[168:171], v[4:7]
	v_mfma_f32_16x16x32_bf16 v[60:63], v[198:201], v[190:193], v[60:63]
	v_mfma_f32_16x16x32_bf16 v[64:67], v[208:211], v[190:193], v[64:67]
	s_barrier
	s_setprio 0
	s_add_i32 s72, 0, 0x18000
	v_add_u32_e32 v2, s72, v1
	ds_read_b128 v[132:135], v2
	ds_read_b128 v[136:139], v2 offset:1024
	ds_read_b128 v[140:143], v2 offset:2048
	ds_read_b128 v[144:147], v2 offset:3072
	s_add_u32 s14, s14, 0x80000
	s_addc_u32 s15, s15, 0
	ds_read_b128 v[148:151], v207 offset:32768
	ds_read_b128 v[152:155], v207 offset:33792
	ds_read_b128 v[156:159], v207 offset:34816
	ds_read_b128 v[160:163], v207 offset:35840
	ds_read_b128 v[164:167], v207 offset:36864
	ds_read_b128 v[168:171], v207 offset:37888
	ds_read_b128 v[186:189], v207 offset:38912
	ds_read_b128 v[190:193], v207 offset:39936
	s_mov_b32 m0, s24
	s_nop 0
	global_load_lds_dwordx4 v180, s[14:15]
	s_mov_b32 m0, s25
	s_nop 0
	global_load_lds_dwordx4 v176, s[14:15]
	s_add_i32 s14, 0, 0x1c000
	v_add_u32_e32 v2, s14, v1
	ds_read_b128 v[194:197], v2
	ds_read_b128 v[198:201], v2 offset:1024
	ds_read_b128 v[202:205], v2 offset:2048
	ds_read_b128 v[208:211], v2 offset:3072
	s_waitcnt lgkmcnt(0)
	s_setprio 1
	s_barrier
	v_mfma_f32_16x16x32_bf16 v[68:71], v[132:135], v[148:151], v[68:71]
	v_mfma_f32_16x16x32_bf16 v[72:75], v[140:143], v[148:151], v[72:75]
	v_mfma_f32_16x16x32_bf16 v[120:123], v[132:135], v[156:159], v[120:123]
	v_mfma_f32_16x16x32_bf16 v[116:119], v[140:143], v[156:159], v[116:119]
	v_mfma_f32_16x16x32_bf16 v[112:115], v[132:135], v[164:167], v[112:115]
	v_mfma_f32_16x16x32_bf16 v[108:111], v[140:143], v[164:167], v[108:111]
	v_mfma_f32_16x16x32_bf16 v[104:107], v[132:135], v[186:189], v[104:107]
	v_mfma_f32_16x16x32_bf16 v[100:103], v[140:143], v[186:189], v[100:103]
	v_mfma_f32_16x16x32_bf16 v[68:71], v[136:139], v[152:155], v[68:71]
	v_mfma_f32_16x16x32_bf16 v[72:75], v[144:147], v[152:155], v[72:75]
	v_mfma_f32_16x16x32_bf16 v[120:123], v[136:139], v[160:163], v[120:123]
	v_mfma_f32_16x16x32_bf16 v[116:119], v[144:147], v[160:163], v[116:119]
	v_mfma_f32_16x16x32_bf16 v[112:115], v[136:139], v[168:171], v[112:115]
	v_mfma_f32_16x16x32_bf16 v[108:111], v[144:147], v[168:171], v[108:111]
	v_mfma_f32_16x16x32_bf16 v[104:107], v[136:139], v[190:193], v[104:107]
	v_mfma_f32_16x16x32_bf16 v[100:103], v[144:147], v[190:193], v[100:103]
	v_mfma_f32_16x16x32_bf16 v[76:79], v[194:197], v[148:151], v[76:79]
	v_mfma_f32_16x16x32_bf16 v[80:83], v[202:205], v[148:151], v[80:83]
	v_mfma_f32_16x16x32_bf16 v[96:99], v[194:197], v[156:159], v[96:99]
	v_mfma_f32_16x16x32_bf16 v[92:95], v[202:205], v[156:159], v[92:95]
	v_mfma_f32_16x16x32_bf16 v[88:91], v[194:197], v[164:167], v[88:91]
	v_mfma_f32_16x16x32_bf16 v[84:87], v[202:205], v[164:167], v[84:87]
	v_mfma_f32_16x16x32_bf16 v[128:131], v[194:197], v[186:189], v[128:131]
	v_mfma_f32_16x16x32_bf16 v[124:127], v[202:205], v[186:189], v[124:127]
	v_mfma_f32_16x16x32_bf16 v[76:79], v[198:201], v[152:155], v[76:79]
	v_mfma_f32_16x16x32_bf16 v[80:83], v[208:211], v[152:155], v[80:83]
	v_mfma_f32_16x16x32_bf16 v[96:99], v[198:201], v[160:163], v[96:99]
	v_mfma_f32_16x16x32_bf16 v[92:95], v[208:211], v[160:163], v[92:95]
	v_mfma_f32_16x16x32_bf16 v[88:91], v[198:201], v[168:171], v[88:91]
	v_mfma_f32_16x16x32_bf16 v[84:87], v[208:211], v[168:171], v[84:87]
	v_mfma_f32_16x16x32_bf16 v[128:131], v[198:201], v[190:193], v[128:131]
	v_mfma_f32_16x16x32_bf16 v[124:127], v[208:211], v[190:193], v[124:127]
	s_barrier
; #define LAS __attribute__((address_space(3)))
; __device__ __forceinline__ int opaque_tid() { int t = threadIdx.x; asm volatile("" : "+v"(t)); return t; }
; #define PG8_STAGE(bufoff, gbase, voff) do { _Pragma("unroll") for (int _i = 0; _i < 2; ++_i) \
;         __builtin_amdgcn_global_load_lds((const unsigned*)((const char*)(gbase) + (voff)[_i]), (LAS unsigned*)(lds + (bufoff) + ldsw + _i * 8192), 16, 0, 0); } while (0)
; #define PG8_MMA(ai, bj, At, Bt) do { __builtin_amdgcn_s_setprio(1); _Pragma("unroll") for (int m = 0; m < 4; ++m) _Pragma("unroll") for (int n = 0; n < 2; ++n) _Pragma("unroll") for (int k = 0; k < 2; ++k) \
;         acc[ai][bj][m][n] = __builtin_amdgcn_mfma_f32_16x16x32_bf16(Bt[n][k], At[m][k], acc[ai][bj][m][n], 0, 0, 0); __builtin_amdgcn_s_setprio(0); } while (0)
; #define PG8_WAIT_V(n) asm volatile("s_waitcnt vmcnt(" #n ")" ::: "memory")
; #define PG8_WAIT_L(n) asm volatile("s_waitcnt lgkmcnt(" #n ")" ::: "memory")
; #define PG8_BAR __builtin_amdgcn_s_barrier()
; #define PG8_SCHED __builtin_amdgcn_sched_barrier(0)
;     __device__ __forceinline__ void operator()(f32x4 (&acc)[2][2][4][2], const Unit& u, int wr, int wc, int ui, int) const {
;         const int ol_ = opaque_tid() & 63, fr = ol_ & 15, fq = ol_ >> 4;
;         { float r_[2][4];
;           rs_read(r_, ui, wr, fr);
; #pragma unroll
;           for (int ai = 0; ai < 2; ++ai)
; #pragma unroll
;               for (int bj = 0; bj < 2; ++bj)
; #pragma unroll
;                   for (int m = 0; m < 4; ++m) { acc[ai][bj][m][0] *= r_[ai][m]; acc[ai][bj][m][1] *= r_[ai][m]; } }
;         const int col = u.pn * 128 + wc * 32 + 8 * fq;
;         if (fr >= 14) {
; #pragma unroll
;             for (int ai = 0; ai < 2; ++ai) { LAS f32x4* s = (LAS f32x4*)(hl + ((((ai * 2 + wr) * 4 + wc) * 8 + fq * 2 + (fr - 14)) * 32));
;                 s[0] = acc[ai][1][3][0]; s[1] = acc[ai][1][3][1]; }
; template <class Epi, class Sched>
; __device__ __forceinline__ void gemm_phase(LAS unsigned char* lds, const Gemm g, const Sched& S, const Epi& E) {
;     ...
;             PG8_BAR; PG8_WAIT_L(0); PG8_MMA(1, 0, At, B0); PG8_BAR; PG8_SCHED;
;             PG8_STAGE(PG8_SB(1, 1), b3 + hstepB, voffB);
;             PG8_WAIT_V(6); PG8_BAR; PG8_MMA(1, 1, At, B1); PG8_BAR;
;         }
	s_setprio 0
	ds_read_b128 v[148:151], v207 offset:49152
	ds_read_b128 v[152:155], v207 offset:50176
	ds_read_b128 v[156:159], v207 offset:51200
	ds_read_b128 v[160:163], v207 offset:52224
	ds_read_b128 v[164:167], v207 offset:53248
	ds_read_b128 v[168:171], v207 offset:54272
	ds_read_b128 v[186:189], v207 offset:55296
	ds_read_b128 v[190:193], v207 offset:56320
	s_add_i32 s15, s72, s19
	v_lshl_add_u64 v[172:173], v[172:173], 0, s[8:9]
	s_mov_b32 m0, s15
	s_nop 0
	global_load_lds_dwordx4 v[172:173], off
	v_lshl_add_u64 v[172:173], v[212:213], 0, s[8:9]
	s_add_i32 m0, s15, 0x2000
	s_nop 0
	global_load_lds_dwordx4 v[172:173], off
	s_mov_b32 m0, s30
	v_lshl_add_u64 v[172:173], v[216:217], 0, s[8:9]
	global_load_lds_dwordx4 v[172:173], off
	v_lshl_add_u64 v[172:173], v[218:219], 0, s[8:9]
	s_mov_b32 m0, s31
	s_nop 0
	global_load_lds_dwordx4 v[172:173], off
	s_add_u32 s6, s6, 0x80080
	s_addc_u32 s7, s7, 0
	s_add_i32 s14, s14, s19
	s_mov_b32 m0, s14
	s_nop 0
	global_load_lds_dwordx4 v178, s[6:7]
	s_add_i32 m0, s14, 0x2000
	s_nop 0
	global_load_lds_dwordx4 v174, s[6:7]
	s_add_i32 s71, s71, 2
	s_add_u32 s4, s4, 0x100
	s_addc_u32 s5, s5, 0
	s_add_u32 s69, s69, 0x100
	s_addc_u32 s70, s70, 0
	s_cmp_gt_u32 s71, 29
	s_waitcnt lgkmcnt(0)
	s_waitcnt vmcnt(6)
	s_setprio 1
	s_barrier
	v_mfma_f32_16x16x32_bf16 v[56:59], v[132:135], v[148:151], v[56:59]
	v_mfma_f32_16x16x32_bf16 v[52:55], v[140:143], v[148:151], v[52:55]
	v_mfma_f32_16x16x32_bf16 v[48:51], v[132:135], v[156:159], v[48:51]
	v_mfma_f32_16x16x32_bf16 v[44:47], v[140:143], v[156:159], v[44:47]
	v_mfma_f32_16x16x32_bf16 v[40:43], v[132:135], v[164:167], v[40:43]
	v_mfma_f32_16x16x32_bf16 v[36:39], v[140:143], v[164:167], v[36:39]
	v_mfma_f32_16x16x32_bf16 v[32:35], v[132:135], v[186:189], v[32:35]
	v_mfma_f32_16x16x32_bf16 v[28:31], v[140:143], v[186:189], v[28:31]
	v_mfma_f32_16x16x32_bf16 v[56:59], v[136:139], v[152:155], v[56:59]
	v_mfma_f32_16x16x32_bf16 v[52:55], v[144:147], v[152:155], v[52:55]
	v_mfma_f32_16x16x32_bf16 v[48:51], v[136:139], v[160:163], v[48:51]
	v_mfma_f32_16x16x32_bf16 v[44:47], v[144:147], v[160:163], v[44:47]
	v_mfma_f32_16x16x32_bf16 v[40:43], v[136:139], v[168:171], v[40:43]
	v_mfma_f32_16x16x32_bf16 v[36:39], v[144:147], v[168:171], v[36:39]
	v_mfma_f32_16x16x32_bf16 v[32:35], v[136:139], v[190:193], v[32:35]
	v_mfma_f32_16x16x32_bf16 v[28:31], v[144:147], v[190:193], v[28:31]
	v_mfma_f32_16x16x32_bf16 v[24:27], v[194:197], v[148:151], v[24:27]
	v_mfma_f32_16x16x32_bf16 v[20:23], v[202:205], v[148:151], v[20:23]
	v_mfma_f32_16x16x32_bf16 v[16:19], v[194:197], v[156:159], v[16:19]
	v_mfma_f32_16x16x32_bf16 v[12:15], v[202:205], v[156:159], v[12:15]
	v_mfma_f32_16x16x32_bf16 v[8:11], v[194:197], v[164:167], v[8:11]
	v_mfma_f32_16x16x32_bf16 v[4:7], v[202:205], v[164:167], v[4:7]
	v_mfma_f32_16x16x32_bf16 v[60:63], v[194:197], v[186:189], v[60:63]
	v_mfma_f32_16x16x32_bf16 v[64:67], v[202:205], v[186:189], v[64:67]
	v_mfma_f32_16x16x32_bf16 v[24:27], v[198:201], v[152:155], v[24:27]
	v_mfma_f32_16x16x32_bf16 v[20:23], v[208:211], v[152:155], v[20:23]
	v_mfma_f32_16x16x32_bf16 v[16:19], v[198:201], v[160:163], v[16:19]
	v_mfma_f32_16x16x32_bf16 v[12:15], v[208:211], v[160:163], v[12:15]
	v_mfma_f32_16x16x32_bf16 v[8:11], v[198:201], v[168:171], v[8:11]
	v_mfma_f32_16x16x32_bf16 v[4:7], v[208:211], v[168:171], v[4:7]
	v_mfma_f32_16x16x32_bf16 v[60:63], v[198:201], v[190:193], v[60:63]
	v_mfma_f32_16x16x32_bf16 v[64:67], v[208:211], v[190:193], v[64:67]
	s_barrier
	s_cbranch_scc0 .LBB0_1526
	s_setprio 0
	s_lshl_b32 s4, s66, 10
	v_mov_b32_e32 v134, v0
	s_and_b32 s4, s4, 0x400
	s_add_i32 s4, s35, s4
	v_and_b32_e32 v210, 15, v134
	v_lshl_add_u32 v2, v210, 2, s4
	ds_read2_b32 v[204:205], v2 offset1:16
	ds_read2_b32 v[202:203], v2 offset0:32 offset1:48
	ds_read2_b32 v[198:199], v2 offset0:128 offset1:144
	ds_read2_b32 v[196:197], v2 offset0:160 offset1:176
	v_cmp_lt_u32_e32 vcc, 13, v210
	s_waitcnt lgkmcnt(0)
	v_mov_b32_e32 v206, v205
	v_mov_b32_e32 v208, v203
	v_mov_b32_e32 v2, v199
	v_mov_b32_e32 v200, v197
	v_pk_mul_f32 v[132:133], v[130:131], v[208:209] op_sel_hi:[1,0]
	v_pk_mul_f32 v[130:131], v[128:129], v[208:209] op_sel_hi:[1,0]
	v_pk_mul_f32 v[128:129], v[126:127], v[208:209] op_sel_hi:[1,0]
	v_pk_mul_f32 v[126:127], v[124:125], v[208:209] op_sel_hi:[1,0]
	v_pk_mul_f32 v[62:63], v[62:63], v[200:201] op_sel_hi:[1,0]
	v_pk_mul_f32 v[60:61], v[60:61], v[200:201] op_sel_hi:[1,0]
	v_pk_mul_f32 v[66:67], v[66:67], v[200:201] op_sel_hi:[1,0]
	v_pk_mul_f32 v[64:65], v[64:65], v[200:201] op_sel_hi:[1,0]
	v_bfe_u32 v125, v134, 4, 2
	s_and_saveexec_b64 s[4:5], vcc
	s_cbranch_execz .LBB0_1529
	v_lshlrev_b32_e32 v124, 1, v125
	v_add3_u32 v124, v210, v124, -14
	v_add_u32_e32 v134, s39, v124
	v_add_u32_e32 v124, s38, v124
	v_lshl_add_u32 v124, v124, 5, s62
	v_lshl_add_u32 v134, v134, 5, s62
	ds_write_b128 v124, v[130:133]
	ds_write_b128 v124, v[126:129] offset:16
	ds_write_b128 v134, v[60:63]
	ds_write_b128 v134, v[64:67] offset:16

; #define PG8_STAGE(bufoff, gbase, voff) do { _Pragma("unroll") for (int _i = 0; _i < 2; ++_i) \
;         __builtin_amdgcn_global_load_lds((const unsigned*)((const char*)(gbase) + (voff)[_i]), (LAS unsigned*)(lds + (bufoff) + ldsw + _i * 8192), 16, 0, 0); } while (0)
; #define PG8_LDA(dst, b, h) do { _Pragma("unroll") for (int m = 0; m < 4; ++m) _Pragma("unroll") for (int k = 0; k < 2; ++k) dst[m][k] = *(const LAS bf16x8*)(lds + PG8_SA(b, h) + aoff + m * 2048 + k * 1024); } while (0)
; #define PG8_LDB(dst, b, h) do { _Pragma("unroll") for (int n = 0; n < 2; ++n) _Pragma("unroll") for (int k = 0; k < 2; ++k) dst[n][k] = *(const LAS bf16x8*)(lds + PG8_SB(b, h) + boff + n * 2048 + k * 1024); } while (0)
; #define PG8_MMA(ai, bj, At, Bt) do { __builtin_amdgcn_s_setprio(1); _Pragma("unroll") for (int m = 0; m < 4; ++m) _Pragma("unroll") for (int n = 0; n < 2; ++n) _Pragma("unroll") for (int k = 0; k < 2; ++k) \
;         acc[ai][bj][m][n] = __builtin_amdgcn_mfma_f32_16x16x32_bf16(Bt[n][k], At[m][k], acc[ai][bj][m][n], 0, 0, 0); __builtin_amdgcn_s_setprio(0); } while (0)
; #define PG8_WAIT_V(n) asm volatile("s_waitcnt vmcnt(" #n ")" ::: "memory")
; #define PG8_WAIT_L(n) asm volatile("s_waitcnt lgkmcnt(" #n ")" ::: "memory")
; #define PG8_BAR __builtin_amdgcn_s_barrier()
; #define PG8_SCHED __builtin_amdgcn_sched_barrier(0)
; template <class Epi, class Sched>
; __device__ __forceinline__ void gemm_phase(LAS unsigned char* lds, const Gemm g, const Sched& S, const Epi& E) {
;     ...
;             PG8_LDB(B0, 0, 0); PG8_SCHED; PG8_LDA(At, 0, 0); PG8_STAGE(PG8_SA(1, 1), a1 + hstepA, voffA);
;             PG8_WAIT_L(8); PG8_BAR; PG8_WAIT_L(0); PG8_MMA(0, 0, At, B0); PG8_BAR; PG8_SCHED;
;             PG8_LDB(B1, 0, 1); PG8_STAGE(PG8_SB(0, 0), b2, voffB);
;             PG8_BAR; PG8_WAIT_L(0); PG8_MMA(0, 1, At, B1); PG8_BAR;
;             PG8_LDA(At, 0, 1); PG8_STAGE(PG8_SA(0, 0), a2, voffA);
;             PG8_BAR; PG8_WAIT_L(0); PG8_MMA(1, 0, At, B0); PG8_BAR; PG8_SCHED;
;             PG8_STAGE(PG8_SB(0, 1), b2 + hstepB, voffB);
;             PG8_WAIT_V(6); PG8_BAR; PG8_MMA(1, 1, At, B1); PG8_BAR;
.LBB0_1666:
	s_setprio 0
	s_add_u32 s14, s6, 0x100
	s_addc_u32 s15, s7, 0
	s_add_i32 s45, 0, 0x10000
	v_add_u32_e32 v144, s45, v1
	ds_read_b128 v[132:135], v144
	ds_read_b128 v[136:139], v144 offset:1024
	ds_read_b128 v[140:143], v144 offset:2048
	ds_read_b128 v[144:147], v144 offset:3072
	s_cmpk_eq_i32 s44, 0x54
	s_cselect_b32 s21, s1, s15
	s_cselect_b32 s20, s0, s14
	s_cselect_b32 s19, s5, s43
	s_cselect_b32 s18, s4, s42
	ds_read_b128 v[148:151], v224
	ds_read_b128 v[152:155], v224 offset:1024
	ds_read_b128 v[156:159], v224 offset:2048
	ds_read_b128 v[160:163], v224 offset:3072
	ds_read_b128 v[164:167], v224 offset:4096
	ds_read_b128 v[168:171], v224 offset:5120
	ds_read_b128 v[172:175], v224 offset:6144
	ds_read_b128 v[176:179], v224 offset:7168
	s_add_i32 s51, 0, 0x14000
	v_add_u32_e32 v202, s51, v1
	ds_read_b128 v[180:183], v202
	ds_read_b128 v[184:187], v202 offset:1024
	ds_read_b128 v[188:191], v202 offset:2048
	ds_read_b128 v[202:205], v202 offset:3072
	s_add_i32 m0, s29, 0xc000
	s_nop 0
	global_load_lds_dwordx4 v198, s[6:7]
	s_add_i32 m0, s29, 0xe000
	s_nop 0
	global_load_lds_dwordx4 v200, s[6:7]
	s_waitcnt lgkmcnt(0)
	s_setprio 1
	s_barrier
	v_mfma_f32_16x16x32_bf16 v[128:131], v[132:135], v[148:151], v[128:131]
	v_mfma_f32_16x16x32_bf16 v[124:127], v[140:143], v[148:151], v[124:127]
	v_mfma_f32_16x16x32_bf16 v[112:115], v[132:135], v[156:159], v[112:115]
	v_mfma_f32_16x16x32_bf16 v[108:111], v[140:143], v[156:159], v[108:111]
	v_mfma_f32_16x16x32_bf16 v[100:103], v[132:135], v[164:167], v[100:103]
	v_mfma_f32_16x16x32_bf16 v[92:95], v[140:143], v[164:167], v[92:95]
	v_mfma_f32_16x16x32_bf16 v[84:87], v[132:135], v[172:175], v[84:87]
	v_mfma_f32_16x16x32_bf16 v[76:79], v[140:143], v[172:175], v[76:79]
	v_mfma_f32_16x16x32_bf16 v[128:131], v[136:139], v[152:155], v[128:131]
	v_mfma_f32_16x16x32_bf16 v[124:127], v[144:147], v[152:155], v[124:127]
	v_mfma_f32_16x16x32_bf16 v[112:115], v[136:139], v[160:163], v[112:115]
	v_mfma_f32_16x16x32_bf16 v[108:111], v[144:147], v[160:163], v[108:111]
	v_mfma_f32_16x16x32_bf16 v[100:103], v[136:139], v[168:171], v[100:103]
	v_mfma_f32_16x16x32_bf16 v[92:95], v[144:147], v[168:171], v[92:95]
	v_mfma_f32_16x16x32_bf16 v[84:87], v[136:139], v[176:179], v[84:87]
	v_mfma_f32_16x16x32_bf16 v[76:79], v[144:147], v[176:179], v[76:79]
	v_mfma_f32_16x16x32_bf16 v[120:123], v[180:183], v[148:151], v[120:123]
	v_mfma_f32_16x16x32_bf16 v[116:119], v[188:191], v[148:151], v[116:119]
	v_mfma_f32_16x16x32_bf16 v[104:107], v[180:183], v[156:159], v[104:107]
	v_mfma_f32_16x16x32_bf16 v[96:99], v[188:191], v[156:159], v[96:99]
	v_mfma_f32_16x16x32_bf16 v[88:91], v[180:183], v[164:167], v[88:91]
	v_mfma_f32_16x16x32_bf16 v[80:83], v[188:191], v[164:167], v[80:83]
	v_mfma_f32_16x16x32_bf16 v[72:75], v[180:183], v[172:175], v[72:75]
	v_mfma_f32_16x16x32_bf16 v[68:71], v[188:191], v[172:175], v[68:71]
	v_mfma_f32_16x16x32_bf16 v[120:123], v[184:187], v[152:155], v[120:123]
	v_mfma_f32_16x16x32_bf16 v[116:119], v[202:205], v[152:155], v[116:119]
	v_mfma_f32_16x16x32_bf16 v[104:107], v[184:187], v[160:163], v[104:107]
	v_mfma_f32_16x16x32_bf16 v[96:99], v[202:205], v[160:163], v[96:99]
	v_mfma_f32_16x16x32_bf16 v[88:91], v[184:187], v[168:171], v[88:91]
	v_mfma_f32_16x16x32_bf16 v[80:83], v[202:205], v[168:171], v[80:83]
	v_mfma_f32_16x16x32_bf16 v[72:75], v[184:187], v[176:179], v[72:75]
	v_mfma_f32_16x16x32_bf16 v[68:71], v[202:205], v[176:179], v[68:71]
	s_barrier
	s_setprio 0
	ds_read_b128 v[148:151], v224 offset:16384
	ds_read_b128 v[152:155], v224 offset:17408
	ds_read_b128 v[156:159], v224 offset:18432
	ds_read_b128 v[160:163], v224 offset:19456
	ds_read_b128 v[164:167], v224 offset:20480
	ds_read_b128 v[168:171], v224 offset:21504
	ds_read_b128 v[172:175], v224 offset:22528
	ds_read_b128 v[176:179], v224 offset:23552
	s_add_i32 s6, s45, s28
	v_lshl_add_u64 v[206:207], s[18:19], 0, v[2:3]
	s_mov_b32 m0, s6
	s_nop 0
	global_load_lds_dwordx4 v[206:207], off
	v_lshl_add_u64 v[208:209], s[18:19], 0, v[192:193]
	s_add_i32 m0, s6, 0x2000
	s_nop 0
	global_load_lds_dwordx4 v[208:209], off
	s_mov_b32 m0, s29
	v_lshl_add_u64 v[210:211], s[20:21], 0, v[196:197]
	global_load_lds_dwordx4 v[210:211], off
	v_lshl_add_u64 v[212:213], s[20:21], 0, v[194:195]
	s_mov_b32 m0, s30
	s_nop 0
	global_load_lds_dwordx4 v[212:213], off
	s_add_u32 s6, s18, 0x160000
	s_addc_u32 s7, s19, 0
	s_add_i32 s45, s51, s28
	s_mov_b32 m0, s45
	s_nop 0
	global_load_lds_dwordx4 v2, s[6:7]
	s_add_i32 m0, s45, 0x2000
	s_nop 0
	global_load_lds_dwordx4 v192, s[6:7]
	s_waitcnt lgkmcnt(0)
	s_waitcnt vmcnt(6)
	s_setprio 1
	s_barrier
; #define PG8_STAGE(bufoff, gbase, voff) do { _Pragma("unroll") for (int _i = 0; _i < 2; ++_i) \
;         __builtin_amdgcn_global_load_lds((const unsigned*)((const char*)(gbase) + (voff)[_i]), (LAS unsigned*)(lds + (bufoff) + ldsw + _i * 8192), 16, 0, 0); } while (0)
; #define PG8_LDA(dst, b, h) do { _Pragma("unroll") for (int m = 0; m < 4; ++m) _Pragma("unroll") for (int k = 0; k < 2; ++k) dst[m][k] = *(const LAS bf16x8*)(lds + PG8_SA(b, h) + aoff + m * 2048 + k * 1024); } while (0)
; #define PG8_LDB(dst, b, h) do { _Pragma("unroll") for (int n = 0; n < 2; ++n) _Pragma("unroll") for (int k = 0; k < 2; ++k) dst[n][k] = *(const LAS bf16x8*)(lds + PG8_SB(b, h) + boff + n * 2048 + k * 1024); } while (0)
; #define PG8_MMA(ai, bj, At, Bt) do { __builtin_amdgcn_s_setprio(1); _Pragma("unroll") for (int m = 0; m < 4; ++m) _Pragma("unroll") for (int n = 0; n < 2; ++n) _Pragma("unroll") for (int k = 0; k < 2; ++k) \
;         acc[ai][bj][m][n] = __builtin_amdgcn_mfma_f32_16x16x32_bf16(Bt[n][k], At[m][k], acc[ai][bj][m][n], 0, 0, 0); __builtin_amdgcn_s_setprio(0); } while (0)
; #define PG8_WAIT_V(n) asm volatile("s_waitcnt vmcnt(" #n ")" ::: "memory")
; #define PG8_WAIT_L(n) asm volatile("s_waitcnt lgkmcnt(" #n ")" ::: "memory")
; #define PG8_BAR __builtin_amdgcn_s_barrier()
; #define PG8_SCHED __builtin_amdgcn_sched_barrier(0)
; template <class Epi, class Sched>
; __device__ __forceinline__ void gemm_phase(LAS unsigned char* lds, const Gemm g, const Sched& S, const Epi& E) {
;     ...
;             PG8_WAIT_V(6); PG8_BAR; PG8_MMA(1, 1, At, B1); PG8_BAR;
;             PG8_LDB(B0, 1, 0); PG8_SCHED; PG8_LDA(At, 1, 0); PG8_STAGE(PG8_SA(0, 1), a2 + hstepA, voffA);
;             PG8_WAIT_L(8); PG8_BAR; PG8_WAIT_L(0); PG8_MMA(0, 0, At, B0); PG8_BAR; PG8_SCHED;
;             PG8_LDB(B1, 1, 1); PG8_STAGE(PG8_SB(1, 0), b3, voffB);
;             PG8_BAR; PG8_WAIT_L(0); PG8_MMA(0, 1, At, B1); PG8_BAR;
;             PG8_LDA(At, 1, 1); PG8_STAGE(PG8_SA(1, 0), a3, voffA);
;             PG8_BAR; PG8_WAIT_L(0); PG8_MMA(1, 0, At, B0); PG8_BAR; PG8_SCHED;
	v_mfma_f32_16x16x32_bf16 v[64:67], v[132:135], v[148:151], v[64:67]
	v_mfma_f32_16x16x32_bf16 v[60:63], v[140:143], v[148:151], v[60:63]
	v_mfma_f32_16x16x32_bf16 v[52:55], v[132:135], v[156:159], v[52:55]
	v_mfma_f32_16x16x32_bf16 v[44:47], v[140:143], v[156:159], v[44:47]
	v_mfma_f32_16x16x32_bf16 v[36:39], v[132:135], v[164:167], v[36:39]
	v_mfma_f32_16x16x32_bf16 v[28:31], v[140:143], v[164:167], v[28:31]
	v_mfma_f32_16x16x32_bf16 v[20:23], v[132:135], v[172:175], v[20:23]
	v_mfma_f32_16x16x32_bf16 v[12:15], v[140:143], v[172:175], v[12:15]
	v_mfma_f32_16x16x32_bf16 v[64:67], v[136:139], v[152:155], v[64:67]
	v_mfma_f32_16x16x32_bf16 v[60:63], v[144:147], v[152:155], v[60:63]
	v_mfma_f32_16x16x32_bf16 v[52:55], v[136:139], v[160:163], v[52:55]
	v_mfma_f32_16x16x32_bf16 v[44:47], v[144:147], v[160:163], v[44:47]
	v_mfma_f32_16x16x32_bf16 v[36:39], v[136:139], v[168:171], v[36:39]
	v_mfma_f32_16x16x32_bf16 v[28:31], v[144:147], v[168:171], v[28:31]
	v_mfma_f32_16x16x32_bf16 v[20:23], v[136:139], v[176:179], v[20:23]
	v_mfma_f32_16x16x32_bf16 v[12:15], v[144:147], v[176:179], v[12:15]
	v_mfma_f32_16x16x32_bf16 v[56:59], v[180:183], v[148:151], v[56:59]
	v_mfma_f32_16x16x32_bf16 v[48:51], v[188:191], v[148:151], v[48:51]
	v_mfma_f32_16x16x32_bf16 v[40:43], v[180:183], v[156:159], v[40:43]
	v_mfma_f32_16x16x32_bf16 v[32:35], v[188:191], v[156:159], v[32:35]
	v_mfma_f32_16x16x32_bf16 v[24:27], v[180:183], v[164:167], v[24:27]
	v_mfma_f32_16x16x32_bf16 v[16:19], v[188:191], v[164:167], v[16:19]
	v_mfma_f32_16x16x32_bf16 v[8:11], v[180:183], v[172:175], v[8:11]
	v_mfma_f32_16x16x32_bf16 v[4:7], v[188:191], v[172:175], v[4:7]
	v_mfma_f32_16x16x32_bf16 v[56:59], v[184:187], v[152:155], v[56:59]
	v_mfma_f32_16x16x32_bf16 v[48:51], v[202:205], v[152:155], v[48:51]
	v_mfma_f32_16x16x32_bf16 v[40:43], v[184:187], v[160:163], v[40:43]
	v_mfma_f32_16x16x32_bf16 v[32:35], v[202:205], v[160:163], v[32:35]
	v_mfma_f32_16x16x32_bf16 v[24:27], v[184:187], v[168:171], v[24:27]
	v_mfma_f32_16x16x32_bf16 v[16:19], v[202:205], v[168:171], v[16:19]
	v_mfma_f32_16x16x32_bf16 v[8:11], v[184:187], v[176:179], v[8:11]
	v_mfma_f32_16x16x32_bf16 v[4:7], v[202:205], v[176:179], v[4:7]
	s_barrier
	s_setprio 0
	s_add_i32 s45, 0, 0x18000
	v_add_u32_e32 v144, s45, v1
	ds_read_b128 v[132:135], v144
	ds_read_b128 v[136:139], v144 offset:1024
	ds_read_b128 v[140:143], v144 offset:2048
	ds_read_b128 v[144:147], v144 offset:3072
	s_add_u32 s6, s20, 0x160000
	s_addc_u32 s7, s21, 0
	ds_read_b128 v[148:151], v224 offset:32768
	ds_read_b128 v[152:155], v224 offset:33792
	ds_read_b128 v[156:159], v224 offset:34816
	ds_read_b128 v[160:163], v224 offset:35840
	ds_read_b128 v[164:167], v224 offset:36864
	ds_read_b128 v[168:171], v224 offset:37888
	ds_read_b128 v[172:175], v224 offset:38912
	ds_read_b128 v[176:179], v224 offset:39936
	s_mov_b32 m0, s31
	s_nop 0
	global_load_lds_dwordx4 v196, s[6:7]
	s_mov_b32 m0, s35
	s_nop 0
	global_load_lds_dwordx4 v194, s[6:7]
	s_add_i32 s20, 0, 0x1c000
	v_add_u32_e32 v202, s20, v1
	ds_read_b128 v[180:183], v202
	ds_read_b128 v[184:187], v202 offset:1024
	ds_read_b128 v[188:191], v202 offset:2048
	ds_read_b128 v[202:205], v202 offset:3072
	s_waitcnt lgkmcnt(0)
	s_setprio 1
	s_barrier
	v_mfma_f32_16x16x32_bf16 v[128:131], v[132:135], v[148:151], v[128:131]
	v_mfma_f32_16x16x32_bf16 v[124:127], v[140:143], v[148:151], v[124:127]
	v_mfma_f32_16x16x32_bf16 v[112:115], v[132:135], v[156:159], v[112:115]
	v_mfma_f32_16x16x32_bf16 v[108:111], v[140:143], v[156:159], v[108:111]
	v_mfma_f32_16x16x32_bf16 v[100:103], v[132:135], v[164:167], v[100:103]
	v_mfma_f32_16x16x32_bf16 v[92:95], v[140:143], v[164:167], v[92:95]
	v_mfma_f32_16x16x32_bf16 v[84:87], v[132:135], v[172:175], v[84:87]
	v_mfma_f32_16x16x32_bf16 v[76:79], v[140:143], v[172:175], v[76:79]
	v_mfma_f32_16x16x32_bf16 v[128:131], v[136:139], v[152:155], v[128:131]
	v_mfma_f32_16x16x32_bf16 v[124:127], v[144:147], v[152:155], v[124:127]
	v_mfma_f32_16x16x32_bf16 v[112:115], v[136:139], v[160:163], v[112:115]
	v_mfma_f32_16x16x32_bf16 v[108:111], v[144:147], v[160:163], v[108:111]
	v_mfma_f32_16x16x32_bf16 v[100:103], v[136:139], v[168:171], v[100:103]
	v_mfma_f32_16x16x32_bf16 v[92:95], v[144:147], v[168:171], v[92:95]
	v_mfma_f32_16x16x32_bf16 v[84:87], v[136:139], v[176:179], v[84:87]
	v_mfma_f32_16x16x32_bf16 v[76:79], v[144:147], v[176:179], v[76:79]
	v_mfma_f32_16x16x32_bf16 v[120:123], v[180:183], v[148:151], v[120:123]
	v_mfma_f32_16x16x32_bf16 v[116:119], v[188:191], v[148:151], v[116:119]
	v_mfma_f32_16x16x32_bf16 v[104:107], v[180:183], v[156:159], v[104:107]
	v_mfma_f32_16x16x32_bf16 v[96:99], v[188:191], v[156:159], v[96:99]
	v_mfma_f32_16x16x32_bf16 v[88:91], v[180:183], v[164:167], v[88:91]
	v_mfma_f32_16x16x32_bf16 v[80:83], v[188:191], v[164:167], v[80:83]
	v_mfma_f32_16x16x32_bf16 v[72:75], v[180:183], v[172:175], v[72:75]
	v_mfma_f32_16x16x32_bf16 v[68:71], v[188:191], v[172:175], v[68:71]
	v_mfma_f32_16x16x32_bf16 v[120:123], v[184:187], v[152:155], v[120:123]
	v_mfma_f32_16x16x32_bf16 v[116:119], v[202:205], v[152:155], v[116:119]
	v_mfma_f32_16x16x32_bf16 v[104:107], v[184:187], v[160:163], v[104:107]
	v_mfma_f32_16x16x32_bf16 v[96:99], v[202:205], v[160:163], v[96:99]
	v_mfma_f32_16x16x32_bf16 v[88:91], v[184:187], v[168:171], v[88:91]
	v_mfma_f32_16x16x32_bf16 v[80:83], v[202:205], v[168:171], v[80:83]
	v_mfma_f32_16x16x32_bf16 v[72:75], v[184:187], v[176:179], v[72:75]
	v_mfma_f32_16x16x32_bf16 v[68:71], v[202:205], v[176:179], v[68:71]
	s_barrier
; __device__ __forceinline__ int opaque_tid() { int t = threadIdx.x; asm volatile("" : "+v"(t)); return t; }
; #define PG8_STAGE(bufoff, gbase, voff) do { _Pragma("unroll") for (int _i = 0; _i < 2; ++_i) \
;         __builtin_amdgcn_global_load_lds((const unsigned*)((const char*)(gbase) + (voff)[_i]), (LAS unsigned*)(lds + (bufoff) + ldsw + _i * 8192), 16, 0, 0); } while (0)
; #define PG8_MMA(ai, bj, At, Bt) do { __builtin_amdgcn_s_setprio(1); _Pragma("unroll") for (int m = 0; m < 4; ++m) _Pragma("unroll") for (int n = 0; n < 2; ++n) _Pragma("unroll") for (int k = 0; k < 2; ++k) \
;         acc[ai][bj][m][n] = __builtin_amdgcn_mfma_f32_16x16x32_bf16(Bt[n][k], At[m][k], acc[ai][bj][m][n], 0, 0, 0); __builtin_amdgcn_s_setprio(0); } while (0)
; #define PG8_WAIT_V(n) asm volatile("s_waitcnt vmcnt(" #n ")" ::: "memory")
; #define PG8_WAIT_L(n) asm volatile("s_waitcnt lgkmcnt(" #n ")" ::: "memory")
; #define PG8_BAR __builtin_amdgcn_s_barrier()
; #define PG8_SCHED __builtin_amdgcn_sched_barrier(0)
;     __device__ __forceinline__ void operator()(const f32x4 (&acc)[2][2][4][2], const Unit& u, int wr, int wc, int, int) const {
;         const int ol_ = opaque_tid() & 63, fr = ol_ & 15, fq = ol_ >> 4;
;         const int row0 = u.pm * BM + wr * 64 + fr, col0 = u.pn * BM + wc * 32 + 8 * fq;
;         u32x4 cin[2][4][2];
; #pragma unroll
;         for (int ai = 0; ai < 2; ++ai)
; #pragma unroll
;             for (int m = 0; m < 4; ++m)
; #pragma unroll
;                 for (int bj = 0; bj < 2; ++bj) cin[ai][m][bj] = *(const u32x4*)(C + (size_t)(row0 + ai * HALF + m * 16) * ldc + col0 + bj * HALF);
; template <class Epi, class Sched>
; __device__ __forceinline__ void gemm_phase(LAS unsigned char* lds, const Gemm g, const Sched& S, const Epi& E) {
;     ...
;             PG8_BAR; PG8_WAIT_L(0); PG8_MMA(1, 0, At, B0); PG8_BAR; PG8_SCHED;
;             PG8_STAGE(PG8_SB(1, 1), b3 + hstepB, voffB);
;             PG8_WAIT_V(6); PG8_BAR; PG8_MMA(1, 1, At, B1); PG8_BAR;
;         }
	s_setprio 0
	ds_read_b128 v[148:151], v224 offset:49152
	ds_read_b128 v[152:155], v224 offset:50176
	ds_read_b128 v[156:159], v224 offset:51200
	ds_read_b128 v[160:163], v224 offset:52224
	ds_read_b128 v[164:167], v224 offset:53248
	ds_read_b128 v[168:171], v224 offset:54272
	ds_read_b128 v[172:175], v224 offset:55296
	ds_read_b128 v[176:179], v224 offset:56320
	s_add_i32 s6, s45, s28
	v_lshl_add_u64 v[206:207], v[206:207], 0, s[8:9]
	s_mov_b32 m0, s6
	s_nop 0
	global_load_lds_dwordx4 v[206:207], off
	v_lshl_add_u64 v[206:207], v[208:209], 0, s[8:9]
	s_add_i32 m0, s6, 0x2000
	s_nop 0
	global_load_lds_dwordx4 v[206:207], off
	s_mov_b32 m0, s38
	v_lshl_add_u64 v[206:207], v[210:211], 0, s[8:9]
	global_load_lds_dwordx4 v[206:207], off
	v_lshl_add_u64 v[206:207], v[212:213], 0, s[8:9]
	s_mov_b32 m0, s39
	s_nop 0
	global_load_lds_dwordx4 v[206:207], off
	s_add_u32 s6, s18, 0x160080
	s_addc_u32 s7, s19, 0
	s_add_i32 s18, s20, s28
	s_mov_b32 m0, s18
	s_nop 0
	global_load_lds_dwordx4 v2, s[6:7]
	s_add_i32 m0, s18, 0x2000
	s_nop 0
	global_load_lds_dwordx4 v192, s[6:7]
	s_add_i32 s44, s44, 2
	s_add_u32 s42, s42, 0x100
	s_addc_u32 s43, s43, 0
	s_cmpk_gt_u32 s44, 0x55
	s_mov_b64 s[6:7], s[14:15]
	s_waitcnt lgkmcnt(0)
	s_waitcnt vmcnt(6)
	s_setprio 1
	s_barrier
	v_mfma_f32_16x16x32_bf16 v[64:67], v[132:135], v[148:151], v[64:67]
	v_mfma_f32_16x16x32_bf16 v[60:63], v[140:143], v[148:151], v[60:63]
	v_mfma_f32_16x16x32_bf16 v[52:55], v[132:135], v[156:159], v[52:55]
	v_mfma_f32_16x16x32_bf16 v[44:47], v[140:143], v[156:159], v[44:47]
	v_mfma_f32_16x16x32_bf16 v[36:39], v[132:135], v[164:167], v[36:39]
	v_mfma_f32_16x16x32_bf16 v[28:31], v[140:143], v[164:167], v[28:31]
	v_mfma_f32_16x16x32_bf16 v[20:23], v[132:135], v[172:175], v[20:23]
	v_mfma_f32_16x16x32_bf16 v[12:15], v[140:143], v[172:175], v[12:15]
	v_mfma_f32_16x16x32_bf16 v[64:67], v[136:139], v[152:155], v[64:67]
	v_mfma_f32_16x16x32_bf16 v[60:63], v[144:147], v[152:155], v[60:63]
	v_mfma_f32_16x16x32_bf16 v[52:55], v[136:139], v[160:163], v[52:55]
	v_mfma_f32_16x16x32_bf16 v[44:47], v[144:147], v[160:163], v[44:47]
	v_mfma_f32_16x16x32_bf16 v[36:39], v[136:139], v[168:171], v[36:39]
	v_mfma_f32_16x16x32_bf16 v[28:31], v[144:147], v[168:171], v[28:31]
	v_mfma_f32_16x16x32_bf16 v[20:23], v[136:139], v[176:179], v[20:23]
	v_mfma_f32_16x16x32_bf16 v[12:15], v[144:147], v[176:179], v[12:15]
	v_mfma_f32_16x16x32_bf16 v[56:59], v[180:183], v[148:151], v[56:59]
	v_mfma_f32_16x16x32_bf16 v[48:51], v[188:191], v[148:151], v[48:51]
	v_mfma_f32_16x16x32_bf16 v[40:43], v[180:183], v[156:159], v[40:43]
	v_mfma_f32_16x16x32_bf16 v[32:35], v[188:191], v[156:159], v[32:35]
	v_mfma_f32_16x16x32_bf16 v[24:27], v[180:183], v[164:167], v[24:27]
	v_mfma_f32_16x16x32_bf16 v[16:19], v[188:191], v[164:167], v[16:19]
	v_mfma_f32_16x16x32_bf16 v[8:11], v[180:183], v[172:175], v[8:11]
	v_mfma_f32_16x16x32_bf16 v[4:7], v[188:191], v[172:175], v[4:7]
	v_mfma_f32_16x16x32_bf16 v[56:59], v[184:187], v[152:155], v[56:59]
	v_mfma_f32_16x16x32_bf16 v[48:51], v[202:205], v[152:155], v[48:51]
	v_mfma_f32_16x16x32_bf16 v[40:43], v[184:187], v[160:163], v[40:43]
	v_mfma_f32_16x16x32_bf16 v[32:35], v[202:205], v[160:163], v[32:35]
	v_mfma_f32_16x16x32_bf16 v[24:27], v[184:187], v[168:171], v[24:27]
	v_mfma_f32_16x16x32_bf16 v[16:19], v[202:205], v[168:171], v[16:19]
	v_mfma_f32_16x16x32_bf16 v[8:11], v[184:187], v[176:179], v[8:11]
	v_mfma_f32_16x16x32_bf16 v[4:7], v[202:205], v[176:179], v[4:7]
	s_barrier
	s_cbranch_scc0 .LBB0_1666
	s_setprio 0
	v_mov_b32_e32 v133, v0
	s_lshl_b32 s6, s50, 8
	s_add_i32 s6, s6, s36
	v_and_or_b32 v132, v133, 15, s6
	s_lshl_b32 s6, s49, 8
	v_lshrrev_b32_e32 v133, 1, v133
	v_and_or_b32 v133, v133, 24, s6
	v_or_b32_e32 v134, s37, v133
	v_ashrrev_i32_e32 v135, 31, v134
	v_lshlrev_b64 v[202:203], 1, v[134:135]
	v_ashrrev_i32_e32 v133, 31, v132
	v_lshl_add_u64 v[134:135], s[88:89], 0, v[202:203]
	v_lshlrev_b64 v[226:227], 12, v[132:133]
	v_lshl_add_u64 v[136:137], v[134:135], 0, v[226:227]
	global_load_dwordx4 v[216:219], v[136:137], off
	global_load_dwordx4 v[188:191], v[136:137], off offset:256
	v_or_b32_e32 v136, 16, v132
	v_ashrrev_i32_e32 v137, 31, v136
	v_lshlrev_b64 v[222:223], 12, v[136:137]
	v_lshl_add_u64 v[136:137], v[134:135], 0, v[222:223]
	global_load_dwordx4 v[184:187], v[136:137], off
	global_load_dwordx4 v[180:183], v[136:137], off offset:256
	v_or_b32_e32 v136, 32, v132
	v_ashrrev_i32_e32 v137, 31, v136
	v_lshlrev_b64 v[220:221], 12, v[136:137]
	v_lshl_add_u64 v[136:137], v[134:135], 0, v[220:221]
	global_load_dwordx4 v[176:179], v[136:137], off
	global_load_dwordx4 v[168:171], v[136:137], off offset:256
	v_or_b32_e32 v132, 48, v132
	v_ashrrev_i32_e32 v133, 31, v132
	v_lshlrev_b64 v[212:213], 12, v[132:133]
	v_lshl_add_u64 v[132:133], v[134:135], 0, v[212:213]
	global_load_dwordx4 v[172:175], v[132:133], off
	global_load_dwordx4 v[164:167], v[132:133], off offset:256
	s_mov_b64 s[6:7], 0x80000
	v_lshl_add_u64 v[210:211], v[226:227], 0, s[6:7]
	v_lshl_add_u64 v[132:133], v[134:135], 0, v[210:211]
	global_load_dwordx4 v[160:163], v[132:133], off
	global_load_dwordx4 v[156:159], v[132:133], off offset:256
	s_mov_b64 s[6:7], 0x90000
	v_lshl_add_u64 v[208:209], v[226:227], 0, s[6:7]
	v_lshl_add_u64 v[132:133], v[134:135], 0, v[208:209]
	global_load_dwordx4 v[152:155], v[132:133], off
	global_load_dwordx4 v[148:151], v[132:133], off offset:256
	s_mov_b64 s[6:7], 0xa0000
	v_lshl_add_u64 v[206:207], v[226:227], 0, s[6:7]
	v_lshl_add_u64 v[132:133], v[134:135], 0, v[206:207]
	global_load_dwordx4 v[144:147], v[132:133], off
	global_load_dwordx4 v[140:143], v[132:133], off offset:256
	s_mov_b64 s[6:7], 0xb0000
	v_lshl_add_u64 v[204:205], v[226:227], 0, s[6:7]
	v_lshl_add_u64 v[132:133], v[134:135], 0, v[204:205]
	global_load_dwordx4 v[136:139], v[132:133], off
	s_nop 0
	global_load_dwordx4 v[132:135], v[132:133], off offset:256
	s_and_b64 vcc, exec, s[40:41]
	s_mov_b32 s49, s47
	s_mov_b32 s50, s48
	s_mov_b64 s[14:15], s[4:5]
	s_mov_b64 s[6:7], s[0:1]
	s_waitcnt vmcnt(0)
; __device__ __forceinline__ unsigned cvt_pk_bf16(float lo, float hi) { const f32x2 v = {lo, hi}; const bf16v2_ r = __builtin_convertvector(v, bf16v2_); return __builtin_bit_cast(unsigned, r); }
; __device__ __forceinline__ float bflo(unsigned w) { return __uint_as_float(w << 16); }
; __device__ __forceinline__ float bfhi(unsigned w) { return __uint_as_float(w & 0xffff0000u); }
;     __device__ __forceinline__ void operator()(const f32x4 (&acc)[2][2][4][2], const Unit& u, int wr, int wc, int, int) const {
;     ...
; #pragma unroll
;         for (int ai = 0; ai < 2; ++ai)
; #pragma unroll
;             for (int m = 0; m < 4; ++m)
; #pragma unroll
;                 for (int bj = 0; bj < 2; ++bj) { const u32x4 c = cin[ai][m][bj]; const f32x4 v0 = acc[ai][bj][m][0], v1 = acc[ai][bj][m][1];
;                     u32x4 w; w.x = cvt_pk_bf16(bflo(c.x) + v0[0], bfhi(c.x) + v0[1]); w.y = cvt_pk_bf16(bflo(c.y) + v0[2], bfhi(c.y) + v0[3]);
;                     w.z = cvt_pk_bf16(bflo(c.z) + v1[0], bfhi(c.z) + v1[1]); w.w = cvt_pk_bf16(bflo(c.w) + v1[2], bfhi(c.w) + v1[3]);
;                     *(u32x4*)(C + (size_t)(row0 + ai * HALF + m * 16) * ldc + col0 + bj * HALF) = w; }
	v_lshlrev_b32_e32 v228, 16, v216
	v_and_b32_e32 v229, 0xffff0000, v216
	v_lshlrev_b32_e32 v216, 16, v217
	v_and_b32_e32 v217, 0xffff0000, v217
	v_pk_add_f32 v[128:129], v[128:129], v[228:229]
	v_pk_add_f32 v[130:131], v[130:131], v[216:217]
	v_cvt_pk_bf16_f32 v128, v128, v129
	v_cvt_pk_bf16_f32 v129, v130, v131
	v_lshlrev_b32_e32 v130, 16, v218
	v_and_b32_e32 v131, 0xffff0000, v218
	v_pk_add_f32 v[124:125], v[124:125], v[130:131]
	s_nop 0
	v_cvt_pk_bf16_f32 v130, v124, v125
	v_lshlrev_b32_e32 v124, 16, v219
	v_and_b32_e32 v125, 0xffff0000, v219
	v_pk_add_f32 v[124:125], v[126:127], v[124:125]
	v_lshlrev_b32_e32 v126, 16, v188
	v_and_b32_e32 v127, 0xffff0000, v188
	v_pk_add_f32 v[120:121], v[120:121], v[126:127]
	v_lshlrev_b32_e32 v126, 16, v189
	v_and_b32_e32 v127, 0xffff0000, v189
	v_pk_add_f32 v[122:123], v[122:123], v[126:127]
	v_cvt_pk_bf16_f32 v120, v120, v121
	v_cvt_pk_bf16_f32 v121, v122, v123
	v_lshlrev_b32_e32 v122, 16, v190
	v_and_b32_e32 v123, 0xffff0000, v190
	v_pk_add_f32 v[116:117], v[116:117], v[122:123]
	v_cvt_pk_bf16_f32 v131, v124, v125
	v_cvt_pk_bf16_f32 v122, v116, v117
	v_lshlrev_b32_e32 v116, 16, v191
	v_and_b32_e32 v117, 0xffff0000, v191
	v_pk_add_f32 v[116:117], v[118:119], v[116:117]
	v_lshl_add_u64 v[124:125], s[88:89], 0, v[226:227]
	v_cvt_pk_bf16_f32 v123, v116, v117
	v_lshlrev_b32_e32 v116, 16, v184
	v_and_b32_e32 v117, 0xffff0000, v184
	v_pk_add_f32 v[112:113], v[112:113], v[116:117]
	v_lshlrev_b32_e32 v116, 16, v185
	v_and_b32_e32 v117, 0xffff0000, v185
	v_pk_add_f32 v[114:115], v[114:115], v[116:117]
	v_cvt_pk_bf16_f32 v112, v112, v113
	v_cvt_pk_bf16_f32 v113, v114, v115
	v_lshlrev_b32_e32 v114, 16, v186
	v_and_b32_e32 v115, 0xffff0000, v186
	v_pk_add_f32 v[108:109], v[108:109], v[114:115]
	v_lshl_add_u64 v[124:125], v[124:125], 0, v[202:203]
	v_cvt_pk_bf16_f32 v114, v108, v109
	v_lshlrev_b32_e32 v108, 16, v187
	v_and_b32_e32 v109, 0xffff0000, v187
	v_pk_add_f32 v[108:109], v[110:111], v[108:109]
	v_lshlrev_b32_e32 v110, 16, v180
	v_and_b32_e32 v111, 0xffff0000, v180
	v_pk_add_f32 v[104:105], v[104:105], v[110:111]
	v_lshlrev_b32_e32 v110, 16, v181
	v_and_b32_e32 v111, 0xffff0000, v181
	v_pk_add_f32 v[106:107], v[106:107], v[110:111]
	v_cvt_pk_bf16_f32 v104, v104, v105
	v_cvt_pk_bf16_f32 v105, v106, v107
	v_lshlrev_b32_e32 v106, 16, v182
	v_and_b32_e32 v107, 0xffff0000, v182
	v_pk_add_f32 v[96:97], v[96:97], v[106:107]
	v_cvt_pk_bf16_f32 v115, v108, v109
	v_cvt_pk_bf16_f32 v106, v96, v97
	v_lshlrev_b32_e32 v96, 16, v183
	v_and_b32_e32 v97, 0xffff0000, v183
	v_pk_add_f32 v[96:97], v[98:99], v[96:97]
	v_lshlrev_b32_e32 v98, 16, v177
	v_cvt_pk_bf16_f32 v107, v96, v97
	v_lshlrev_b32_e32 v96, 16, v176
	v_and_b32_e32 v97, 0xffff0000, v176
	v_and_b32_e32 v99, 0xffff0000, v177
	v_pk_add_f32 v[96:97], v[100:101], v[96:97]
	v_pk_add_f32 v[98:99], v[102:103], v[98:99]
	v_cvt_pk_bf16_f32 v96, v96, v97
	v_cvt_pk_bf16_f32 v97, v98, v99
	v_lshlrev_b32_e32 v98, 16, v178
	v_and_b32_e32 v99, 0xffff0000, v178
	v_pk_add_f32 v[92:93], v[92:93], v[98:99]
	v_lshl_add_u64 v[108:109], s[88:89], 0, v[222:223]
	v_cvt_pk_bf16_f32 v98, v92, v93
	v_lshlrev_b32_e32 v92, 16, v179
	v_and_b32_e32 v93, 0xffff0000, v179
	v_pk_add_f32 v[92:93], v[94:95], v[92:93]
	v_lshlrev_b32_e32 v94, 16, v168
	v_and_b32_e32 v95, 0xffff0000, v168
	v_pk_add_f32 v[88:89], v[88:89], v[94:95]
	v_lshlrev_b32_e32 v94, 16, v169
	v_and_b32_e32 v95, 0xffff0000, v169
	v_pk_add_f32 v[90:91], v[90:91], v[94:95]
	v_cvt_pk_bf16_f32 v88, v88, v89
	v_cvt_pk_bf16_f32 v89, v90, v91
	v_lshlrev_b32_e32 v90, 16, v170
	v_and_b32_e32 v91, 0xffff0000, v170
	v_pk_add_f32 v[80:81], v[80:81], v[90:91]
	v_cvt_pk_bf16_f32 v99, v92, v93
	v_cvt_pk_bf16_f32 v90, v80, v81
	v_lshlrev_b32_e32 v80, 16, v171
	v_and_b32_e32 v81, 0xffff0000, v171
	v_pk_add_f32 v[80:81], v[82:83], v[80:81]
	v_lshlrev_b32_e32 v82, 16, v173
	v_cvt_pk_bf16_f32 v91, v80, v81
	v_lshlrev_b32_e32 v80, 16, v172
	v_and_b32_e32 v81, 0xffff0000, v172
	v_and_b32_e32 v83, 0xffff0000, v173
	v_pk_add_f32 v[80:81], v[84:85], v[80:81]
	v_pk_add_f32 v[82:83], v[86:87], v[82:83]
	v_cvt_pk_bf16_f32 v80, v80, v81
	v_cvt_pk_bf16_f32 v81, v82, v83
	v_lshlrev_b32_e32 v82, 16, v174
	v_and_b32_e32 v83, 0xffff0000, v174
	v_pk_add_f32 v[76:77], v[76:77], v[82:83]
	v_lshl_add_u64 v[92:93], s[88:89], 0, v[220:221]
	v_cvt_pk_bf16_f32 v82, v76, v77
	v_lshlrev_b32_e32 v76, 16, v175
	v_and_b32_e32 v77, 0xffff0000, v175
	v_pk_add_f32 v[76:77], v[78:79], v[76:77]
	v_lshlrev_b32_e32 v78, 16, v164
	v_and_b32_e32 v79, 0xffff0000, v164
	v_pk_add_f32 v[72:73], v[72:73], v[78:79]
	v_lshlrev_b32_e32 v78, 16, v165
	v_and_b32_e32 v79, 0xffff0000, v165
	v_pk_add_f32 v[74:75], v[74:75], v[78:79]
	v_cvt_pk_bf16_f32 v72, v72, v73
	v_cvt_pk_bf16_f32 v73, v74, v75
	v_lshlrev_b32_e32 v74, 16, v166
	v_and_b32_e32 v75, 0xffff0000, v166
	v_pk_add_f32 v[68:69], v[68:69], v[74:75]
	v_cvt_pk_bf16_f32 v83, v76, v77
	v_cvt_pk_bf16_f32 v74, v68, v69
	v_lshlrev_b32_e32 v68, 16, v167
	v_and_b32_e32 v69, 0xffff0000, v167
	v_pk_add_f32 v[68:69], v[70:71], v[68:69]
	v_lshl_add_u64 v[76:77], s[88:89], 0, v[212:213]
	v_cvt_pk_bf16_f32 v75, v68, v69
	v_lshlrev_b32_e32 v68, 16, v160
	v_and_b32_e32 v69, 0xffff0000, v160
	v_pk_add_f32 v[64:65], v[64:65], v[68:69]
	v_lshlrev_b32_e32 v68, 16, v161
	v_and_b32_e32 v69, 0xffff0000, v161
	v_pk_add_f32 v[66:67], v[66:67], v[68:69]
	v_cvt_pk_bf16_f32 v64, v64, v65
	v_cvt_pk_bf16_f32 v65, v66, v67
	v_lshlrev_b32_e32 v66, 16, v162
	v_and_b32_e32 v67, 0xffff0000, v162
	v_pk_add_f32 v[60:61], v[60:61], v[66:67]
	v_lshl_add_u64 v[108:109], v[108:109], 0, v[202:203]
	v_cvt_pk_bf16_f32 v66, v60, v61
	v_lshlrev_b32_e32 v60, 16, v163
; __device__ __forceinline__ unsigned cvt_pk_bf16(float lo, float hi) { const f32x2 v = {lo, hi}; const bf16v2_ r = __builtin_convertvector(v, bf16v2_); return __builtin_bit_cast(unsigned, r); }
; __device__ __forceinline__ float bflo(unsigned w) { return __uint_as_float(w << 16); }
; __device__ __forceinline__ float bfhi(unsigned w) { return __uint_as_float(w & 0xffff0000u); }
; #define PG8_WAIT_V(n) asm volatile("s_waitcnt vmcnt(" #n ")" ::: "memory")
; #define PG8_BAR __builtin_amdgcn_s_barrier()
;     __device__ __forceinline__ void operator()(const f32x4 (&acc)[2][2][4][2], const Unit& u, int wr, int wc, int, int) const {
;     ...
; #pragma unroll
;         for (int ai = 0; ai < 2; ++ai)
; #pragma unroll
;             for (int m = 0; m < 4; ++m)
; #pragma unroll
;                 for (int bj = 0; bj < 2; ++bj) { const u32x4 c = cin[ai][m][bj]; const f32x4 v0 = acc[ai][bj][m][0], v1 = acc[ai][bj][m][1];
;                     u32x4 w; w.x = cvt_pk_bf16(bflo(c.x) + v0[0], bfhi(c.x) + v0[1]); w.y = cvt_pk_bf16(bflo(c.y) + v0[2], bfhi(c.y) + v0[3]);
;                     w.z = cvt_pk_bf16(bflo(c.z) + v1[0], bfhi(c.z) + v1[1]); w.w = cvt_pk_bf16(bflo(c.w) + v1[2], bfhi(c.w) + v1[3]);
;                     *(u32x4*)(C + (size_t)(row0 + ai * HALF + m * 16) * ldc + col0 + bj * HALF) = w; }
; template <class Epi, class Sched>
; __device__ __forceinline__ void gemm_phase(LAS unsigned char* lds, const Gemm g, const Sched& S, const Epi& E) {
;     ...
;         if (!has_next) break;
; #pragma unroll
;         for (int a = 0; a < 2; ++a)
; #pragma unroll
;             for (int b = 0; b < 2; ++b)
; #pragma unroll
;                 for (int m = 0; m < 4; ++m)
; #pragma unroll
;                     for (int n = 0; n < 2; ++n) acc[a][b][m][n] = (f32x4){0.f, 0.f, 0.f, 0.f};
;         cur = nxt; cA = nA; cB = nB; ++ui;
;     }
;     PG8_WAIT_V(0);
;     if (wr == 0) PG8_BAR;
;     PG8_BAR;
	v_and_b32_e32 v61, 0xffff0000, v163
	v_pk_add_f32 v[60:61], v[62:63], v[60:61]
	v_lshlrev_b32_e32 v62, 16, v156
	v_and_b32_e32 v63, 0xffff0000, v156
	v_pk_add_f32 v[56:57], v[56:57], v[62:63]
	v_lshlrev_b32_e32 v62, 16, v157
	v_and_b32_e32 v63, 0xffff0000, v157
	v_pk_add_f32 v[58:59], v[58:59], v[62:63]
	v_cvt_pk_bf16_f32 v56, v56, v57
	v_cvt_pk_bf16_f32 v57, v58, v59
	v_lshlrev_b32_e32 v58, 16, v158
	v_and_b32_e32 v59, 0xffff0000, v158
	v_pk_add_f32 v[48:49], v[48:49], v[58:59]
	v_cvt_pk_bf16_f32 v67, v60, v61
	v_cvt_pk_bf16_f32 v58, v48, v49
	v_lshlrev_b32_e32 v48, 16, v159
	v_and_b32_e32 v49, 0xffff0000, v159
	v_pk_add_f32 v[48:49], v[50:51], v[48:49]
	v_lshlrev_b32_e32 v50, 16, v153
	v_cvt_pk_bf16_f32 v59, v48, v49
	v_lshlrev_b32_e32 v48, 16, v152
	v_and_b32_e32 v49, 0xffff0000, v152
	v_and_b32_e32 v51, 0xffff0000, v153
	v_pk_add_f32 v[48:49], v[52:53], v[48:49]
	v_pk_add_f32 v[50:51], v[54:55], v[50:51]
	v_cvt_pk_bf16_f32 v48, v48, v49
	v_cvt_pk_bf16_f32 v49, v50, v51
	v_lshlrev_b32_e32 v50, 16, v154
	v_and_b32_e32 v51, 0xffff0000, v154
	v_pk_add_f32 v[44:45], v[44:45], v[50:51]
	v_lshl_add_u64 v[60:61], s[88:89], 0, v[210:211]
	v_cvt_pk_bf16_f32 v50, v44, v45
	v_lshlrev_b32_e32 v44, 16, v155
	v_and_b32_e32 v45, 0xffff0000, v155
	v_pk_add_f32 v[44:45], v[46:47], v[44:45]
	v_lshlrev_b32_e32 v46, 16, v148
	v_and_b32_e32 v47, 0xffff0000, v148
	v_pk_add_f32 v[40:41], v[40:41], v[46:47]
	v_lshlrev_b32_e32 v46, 16, v149
	v_and_b32_e32 v47, 0xffff0000, v149
	v_pk_add_f32 v[42:43], v[42:43], v[46:47]
	v_cvt_pk_bf16_f32 v40, v40, v41
	v_cvt_pk_bf16_f32 v41, v42, v43
	v_lshlrev_b32_e32 v42, 16, v150
	v_and_b32_e32 v43, 0xffff0000, v150
	v_pk_add_f32 v[32:33], v[32:33], v[42:43]
	v_cvt_pk_bf16_f32 v51, v44, v45
	v_cvt_pk_bf16_f32 v42, v32, v33
	v_lshlrev_b32_e32 v32, 16, v151
	v_and_b32_e32 v33, 0xffff0000, v151
	v_pk_add_f32 v[32:33], v[34:35], v[32:33]
	v_lshlrev_b32_e32 v34, 16, v145
	v_cvt_pk_bf16_f32 v43, v32, v33
	v_lshlrev_b32_e32 v32, 16, v144
	v_and_b32_e32 v33, 0xffff0000, v144
	v_and_b32_e32 v35, 0xffff0000, v145
	v_pk_add_f32 v[32:33], v[36:37], v[32:33]
	v_pk_add_f32 v[34:35], v[38:39], v[34:35]
	v_cvt_pk_bf16_f32 v32, v32, v33
	v_cvt_pk_bf16_f32 v33, v34, v35
	v_lshlrev_b32_e32 v34, 16, v146
	v_and_b32_e32 v35, 0xffff0000, v146
	v_pk_add_f32 v[28:29], v[28:29], v[34:35]
	v_lshl_add_u64 v[44:45], s[88:89], 0, v[208:209]
	v_cvt_pk_bf16_f32 v34, v28, v29
	v_lshlrev_b32_e32 v28, 16, v147
	v_and_b32_e32 v29, 0xffff0000, v147
	v_pk_add_f32 v[28:29], v[30:31], v[28:29]
	v_lshlrev_b32_e32 v30, 16, v140
	v_and_b32_e32 v31, 0xffff0000, v140
	v_pk_add_f32 v[24:25], v[24:25], v[30:31]
	v_lshlrev_b32_e32 v30, 16, v141
	v_and_b32_e32 v31, 0xffff0000, v141
	v_pk_add_f32 v[26:27], v[26:27], v[30:31]
	v_cvt_pk_bf16_f32 v24, v24, v25
	v_cvt_pk_bf16_f32 v25, v26, v27
	v_lshlrev_b32_e32 v26, 16, v142
	v_and_b32_e32 v27, 0xffff0000, v142
	v_pk_add_f32 v[16:17], v[16:17], v[26:27]
	v_cvt_pk_bf16_f32 v35, v28, v29
	v_cvt_pk_bf16_f32 v26, v16, v17
	v_lshlrev_b32_e32 v16, 16, v143
	v_and_b32_e32 v17, 0xffff0000, v143
	v_pk_add_f32 v[16:17], v[18:19], v[16:17]
	v_lshlrev_b32_e32 v18, 16, v137
	v_cvt_pk_bf16_f32 v27, v16, v17
	v_lshlrev_b32_e32 v16, 16, v136
	v_and_b32_e32 v17, 0xffff0000, v136
	v_and_b32_e32 v19, 0xffff0000, v137
	v_pk_add_f32 v[16:17], v[20:21], v[16:17]
	v_pk_add_f32 v[18:19], v[22:23], v[18:19]
	v_cvt_pk_bf16_f32 v16, v16, v17
	v_cvt_pk_bf16_f32 v17, v18, v19
	v_lshlrev_b32_e32 v18, 16, v138
	v_and_b32_e32 v19, 0xffff0000, v138
	v_pk_add_f32 v[12:13], v[12:13], v[18:19]
	v_lshl_add_u64 v[28:29], s[88:89], 0, v[206:207]
	v_cvt_pk_bf16_f32 v18, v12, v13
	v_lshlrev_b32_e32 v12, 16, v139
	v_and_b32_e32 v13, 0xffff0000, v139
	v_pk_add_f32 v[12:13], v[14:15], v[12:13]
	v_lshlrev_b32_e32 v14, 16, v132
	v_and_b32_e32 v15, 0xffff0000, v132
	v_pk_add_f32 v[8:9], v[8:9], v[14:15]
	v_lshlrev_b32_e32 v14, 16, v133
	v_and_b32_e32 v15, 0xffff0000, v133
	v_pk_add_f32 v[10:11], v[10:11], v[14:15]
	v_cvt_pk_bf16_f32 v8, v8, v9
	v_cvt_pk_bf16_f32 v9, v10, v11
	v_lshlrev_b32_e32 v10, 16, v134
	v_and_b32_e32 v11, 0xffff0000, v134
	v_pk_add_f32 v[4:5], v[4:5], v[10:11]
	v_cvt_pk_bf16_f32 v19, v12, v13
	v_cvt_pk_bf16_f32 v10, v4, v5
	v_lshlrev_b32_e32 v4, 16, v135
	v_and_b32_e32 v5, 0xffff0000, v135
	v_lshl_add_u64 v[12:13], s[88:89], 0, v[204:205]
	v_pk_add_f32 v[4:5], v[6:7], v[4:5]
	v_lshl_add_u64 v[92:93], v[92:93], 0, v[202:203]
	v_lshl_add_u64 v[76:77], v[76:77], 0, v[202:203]
	v_lshl_add_u64 v[60:61], v[60:61], 0, v[202:203]
	v_lshl_add_u64 v[44:45], v[44:45], 0, v[202:203]
	v_lshl_add_u64 v[28:29], v[28:29], 0, v[202:203]
	v_lshl_add_u64 v[12:13], v[12:13], 0, v[202:203]
	v_cvt_pk_bf16_f32 v11, v4, v5
	global_store_dwordx4 v[124:125], v[128:131], off
	global_store_dwordx4 v[124:125], v[120:123], off offset:256
	global_store_dwordx4 v[108:109], v[112:115], off
	global_store_dwordx4 v[108:109], v[104:107], off offset:256
	global_store_dwordx4 v[92:93], v[96:99], off
	global_store_dwordx4 v[92:93], v[88:91], off offset:256
	global_store_dwordx4 v[76:77], v[80:83], off
	global_store_dwordx4 v[76:77], v[72:75], off offset:256
	global_store_dwordx4 v[60:61], v[64:67], off
	global_store_dwordx4 v[60:61], v[56:59], off offset:256
	global_store_dwordx4 v[44:45], v[48:51], off
	global_store_dwordx4 v[44:45], v[40:43], off offset:256
	global_store_dwordx4 v[28:29], v[32:35], off
	global_store_dwordx4 v[28:29], v[24:27], off offset:256
	global_store_dwordx4 v[12:13], v[16:19], off
	global_store_dwordx4 v[12:13], v[8:11], off offset:256
	s_cbranch_vccz .LBB0_1655
	s_waitcnt vmcnt(0)
	s_cmpk_gt_u32 s2, 0xff
	s_cbranch_scc1 .LBB0_1670
	s_barrier
